# merge4_balanced
# baseline (speedup 1.0000x reference)
; #define STAGE(P, BASE, br, kt) do { const char* _gb = (const char*)(BASE) + ((size_t)(br) * K + (size_t)(kt) * BK) * 2; \
;     __builtin_amdgcn_global_load_lds((const unsigned*)(_gb + loff0), (unsigned*)((char*)(P) + tid * 16), 16, 0, 0); \
;     __builtin_amdgcn_global_load_lds((const unsigned*)(_gb + (size_t)K * 128 + loff0), (unsigned*)((char*)(P) + tid * 16 + 8192), 16, 0, 0); } while (0)
; #define LDA(dst, b, h) for (int m = 0; m < 4; ++m) { \
;     dst[m][0] = *reinterpret_cast<const bf16x8*>((char*)SA(b, h) + aoff0 + m * 2048); \
;     dst[m][1] = *reinterpret_cast<const bf16x8*>((char*)SA(b, h) + aoff1 + m * 2048); }
; #define LDB(dst, b, h) for (int n = 0; n < 2; ++n) { \
;     dst[n][0] = *reinterpret_cast<const bf16x8*>((char*)SB(b, h) + boff0 + n * 256); \
;     dst[n][1] = *reinterpret_cast<const bf16x8*>((char*)SB(b, h) + boff1 + n * 256); }
; #define MMA(ai, bj, At, Btf) do { __builtin_amdgcn_s_setprio(1); \
;     for (int m = 0; m < 4; ++m) for (int n = 0; n < 2; ++n) for (int k = 0; k < 2; ++k) \
;       acc[ai][bj][m][n] = __builtin_amdgcn_mfma_f32_16x16x32_bf16(Btf[n][k], At[m][k], acc[ai][bj][m][n], 0, 0, 0); \
;     __builtin_amdgcn_s_setprio(0); } while (0)
; #define WAIT_V(n) asm volatile("s_waitcnt vmcnt(" #n ")" ::: "memory")
; #define WAIT_L(n) asm volatile("s_waitcnt lgkmcnt(" #n ")" ::: "memory")
; #define BAR __builtin_amdgcn_s_barrier()
; #define SCHED __builtin_amdgcn_sched_barrier(0)
; template <int EPI> ...
;     ...
;   STAGE(SB(1, 0), Bt, bcol, 1); STAGE(SA(1, 0), A, brow, 1); STAGE(SB(1, 1), Bt, bcol + HALF, 1);
;   WAIT_V(6); BAR;
;   for (int t = 0; t < nt - 2; t += 2) {
;     LDB(B0, 0, 0); SCHED; LDA(At, 0, 0); STAGE(SA(1, 1), A, brow + HALF, t + 1);
;     WAIT_L(8); BAR; WAIT_L(0); MMA(0, 0, At, B0); BAR; SCHED;
;     LDB(B1, 0, 1); STAGE(SB(0, 0), Bt, bcol, t + 2);
;     BAR; WAIT_L(0); MMA(0, 1, At, B1); BAR;
;     LDA(At, 0, 1); STAGE(SA(0, 0), A, brow, t + 2);
;     BAR; WAIT_L(0); MMA(1, 0, At, B0); BAR; SCHED;
;     STAGE(SB(0, 1), Bt, bcol + HALF, t + 2);
;     WAIT_V(6); BAR; MMA(1, 1, At, B1); BAR;
.LBB0_276:
	s_or_b64 exec, exec, s[72:73]
	v_readfirstlane_b32 s67, v144
	v_lshl_add_u64 v[6:7], v[0:1], 0, s[12:13]
	s_mov_b32 m0, s67
	v_readfirstlane_b32 s67, v145
	s_waitcnt vmcnt(2)
	s_barrier
	global_load_lds_dwordx4 v[6:7], off
	v_lshl_add_u64 v[0:1], v[0:1], 0, s[16:17]
	s_mov_b32 m0, s67
	v_readfirstlane_b32 s67, v146
	global_load_lds_dwordx4 v[0:1], off
	v_lshl_add_u64 v[0:1], v[2:3], 0, s[12:13]
	s_mov_b32 m0, s67
	v_readfirstlane_b32 s67, v147
	global_load_lds_dwordx4 v[0:1], off
	v_lshl_add_u64 v[0:1], v[2:3], 0, s[16:17]
	s_mov_b32 m0, s67
	v_readfirstlane_b32 s67, v148
	global_load_lds_dwordx4 v[0:1], off
	v_lshl_add_u64 v[0:1], v[4:5], 0, s[12:13]
	s_mov_b32 m0, s67
	v_readfirstlane_b32 s67, v149
	global_load_lds_dwordx4 v[0:1], off
	v_lshl_add_u64 v[0:1], v[4:5], 0, s[16:17]
	s_mov_b32 m0, s67
	s_add_u32 s70, s6, s70
	global_load_lds_dwordx4 v[0:1], off
	v_mov_b32_e32 v0, 0
	s_addc_u32 s71, s7, s71
	s_mov_b32 s67, -2
	v_mov_b32_e32 v1, v0
	v_mov_b32_e32 v2, v0
	v_mov_b32_e32 v3, v0
	v_mov_b32_e32 v4, v0
	v_mov_b32_e32 v5, v0
	v_mov_b32_e32 v6, v0
	v_mov_b32_e32 v7, v0
	s_waitcnt vmcnt(6)
	s_sub_u32 s98, s68, 0x100
	s_subb_u32 s99, s69, 0
	v_lshl_add_u64 v[228:229], s[98:99], 0, v[130:131]
	s_barrier
.LBB0_277:
	ds_read_b128 v[162:165], v153
	ds_read_b128 v[166:169], v153 offset:256
	ds_read_b128 v[170:173], v154
	ds_read_b128 v[174:177], v154 offset:256
	v_lshl_add_u64 v[226:227], s[70:71], 0, v[130:131]
	v_readfirstlane_b32 s72, v151
	v_lshl_add_u64 v[210:211], v[226:227], 0, s[18:19]
	s_mov_b32 m0, s72
	v_readfirstlane_b32 s72, v152
	ds_read_b128 v[178:181], v150
	ds_read_b128 v[182:185], v150 offset:1024
	ds_read_b128 v[186:189], v150 offset:2048
	ds_read_b128 v[190:193], v150 offset:3072
	ds_read_b128 v[194:197], v150 offset:4096
	ds_read_b128 v[198:201], v150 offset:5120
	ds_read_b128 v[202:205], v150 offset:6144
	ds_read_b128 v[206:209], v150 offset:7168
	global_load_lds_dwordx4 v[210:211], off
	v_lshl_add_u64 v[210:211], v[226:227], 0, s[20:21]
	s_mov_b32 m0, s72
	s_nop 0
	global_load_lds_dwordx4 v[210:211], off
	s_waitcnt lgkmcnt(8)
	v_readfirstlane_b32 s72, v148
	v_lshl_add_u64 v[246:247], v[228:229], 0, s[58:59]
	s_mov_b32 m0, s72
	v_readfirstlane_b32 s72, v149
	global_load_lds_dwordx4 v[246:247], off
	v_lshl_add_u64 v[246:247], v[228:229], 0, s[60:61]
	s_mov_b32 m0, s72
	s_nop 0
	global_load_lds_dwordx4 v[246:247], off
	ds_read_b128 v[210:213], v155
	ds_read_b128 v[214:217], v155 offset:256
	ds_read_b128 v[218:221], v156
	ds_read_b128 v[222:225], v156 offset:256
	s_barrier
	s_waitcnt lgkmcnt(0)
	s_setprio 1
	s_waitcnt lgkmcnt(0)
	v_mfma_f32_16x16x32_bf16 v[124:127], v[162:165], v[178:181], v[124:127]
	v_mfma_f32_16x16x32_bf16 v[120:123], v[166:169], v[178:181], v[120:123]
	v_mfma_f32_16x16x32_bf16 v[116:119], v[162:165], v[186:189], v[116:119]
	v_mfma_f32_16x16x32_bf16 v[112:115], v[166:169], v[186:189], v[112:115]
	v_mfma_f32_16x16x32_bf16 v[108:111], v[162:165], v[194:197], v[108:111]
	v_mfma_f32_16x16x32_bf16 v[104:107], v[166:169], v[194:197], v[104:107]
	v_mfma_f32_16x16x32_bf16 v[100:103], v[162:165], v[202:205], v[100:103]
	v_mfma_f32_16x16x32_bf16 v[96:99], v[166:169], v[202:205], v[96:99]
	v_mfma_f32_16x16x32_bf16 v[124:127], v[170:173], v[182:185], v[124:127]
	v_mfma_f32_16x16x32_bf16 v[120:123], v[174:177], v[182:185], v[120:123]
	v_mfma_f32_16x16x32_bf16 v[116:119], v[170:173], v[190:193], v[116:119]
	v_mfma_f32_16x16x32_bf16 v[112:115], v[174:177], v[190:193], v[112:115]
	v_mfma_f32_16x16x32_bf16 v[108:111], v[170:173], v[198:201], v[108:111]
	v_mfma_f32_16x16x32_bf16 v[104:107], v[174:177], v[198:201], v[104:107]
	v_mfma_f32_16x16x32_bf16 v[100:103], v[170:173], v[206:209], v[100:103]
	v_mfma_f32_16x16x32_bf16 v[96:99], v[174:177], v[206:209], v[96:99]
	s_setprio 0
	s_waitcnt lgkmcnt(0)
	s_setprio 1
	s_waitcnt lgkmcnt(0)
	v_mfma_f32_16x16x32_bf16 v[92:95], v[210:213], v[178:181], v[92:95]
	v_mfma_f32_16x16x32_bf16 v[88:91], v[214:217], v[178:181], v[88:91]
	v_mfma_f32_16x16x32_bf16 v[84:87], v[210:213], v[186:189], v[84:87]
	v_mfma_f32_16x16x32_bf16 v[80:83], v[214:217], v[186:189], v[80:83]
	v_mfma_f32_16x16x32_bf16 v[76:79], v[210:213], v[194:197], v[76:79]
	v_mfma_f32_16x16x32_bf16 v[72:75], v[214:217], v[194:197], v[72:75]
	v_mfma_f32_16x16x32_bf16 v[68:71], v[210:213], v[202:205], v[68:71]
	v_mfma_f32_16x16x32_bf16 v[64:67], v[214:217], v[202:205], v[64:67]
	v_mfma_f32_16x16x32_bf16 v[92:95], v[218:221], v[182:185], v[92:95]
	v_mfma_f32_16x16x32_bf16 v[88:91], v[222:225], v[182:185], v[88:91]
	v_mfma_f32_16x16x32_bf16 v[84:87], v[218:221], v[190:193], v[84:87]
	v_mfma_f32_16x16x32_bf16 v[80:83], v[222:225], v[190:193], v[80:83]
	v_mfma_f32_16x16x32_bf16 v[76:79], v[218:221], v[198:201], v[76:79]
	v_mfma_f32_16x16x32_bf16 v[72:75], v[222:225], v[198:201], v[72:75]
	v_mfma_f32_16x16x32_bf16 v[68:71], v[218:221], v[206:209], v[68:71]
	v_mfma_f32_16x16x32_bf16 v[64:67], v[222:225], v[206:209], v[64:67]
	s_setprio 0
	s_barrier
	v_lshl_add_u64 v[228:229], s[68:69], 0, v[130:131]
	v_readfirstlane_b32 s72, v136
	v_lshl_add_u64 v[230:231], v[228:229], 0, s[22:23]
	s_mov_b32 m0, s72
	v_readfirstlane_b32 s72, v137
	global_load_lds_dwordx4 v[230:231], off
	v_lshl_add_u64 v[230:231], v[228:229], 0, s[26:27]
	s_mov_b32 m0, s72
	s_nop 0
	global_load_lds_dwordx4 v[230:231], off
	v_readfirstlane_b32 s72, v138
	v_lshl_add_u64 v[230:231], v[226:227], 0, s[28:29]
	s_mov_b32 m0, s72
	v_readfirstlane_b32 s72, v139
	ds_read_b128 v[178:181], v150 offset:16384
	ds_read_b128 v[182:185], v150 offset:17408
	ds_read_b128 v[186:189], v150 offset:18432
	ds_read_b128 v[190:193], v150 offset:19456
	ds_read_b128 v[194:197], v150 offset:20480
	ds_read_b128 v[198:201], v150 offset:21504
	ds_read_b128 v[202:205], v150 offset:22528
	ds_read_b128 v[206:209], v150 offset:23552
	global_load_lds_dwordx4 v[230:231], off
	v_lshl_add_u64 v[230:231], v[226:227], 0, s[30:31]
	s_mov_b32 m0, s72
	s_nop 0
	global_load_lds_dwordx4 v[230:231], off
	s_waitcnt vmcnt(4)
	s_barrier
; #define STAGE(P, BASE, br, kt) do { const char* _gb = (const char*)(BASE) + ((size_t)(br) * K + (size_t)(kt) * BK) * 2; \
;     __builtin_amdgcn_global_load_lds((const unsigned*)(_gb + loff0), (unsigned*)((char*)(P) + tid * 16), 16, 0, 0); \
;     __builtin_amdgcn_global_load_lds((const unsigned*)(_gb + (size_t)K * 128 + loff0), (unsigned*)((char*)(P) + tid * 16 + 8192), 16, 0, 0); } while (0)
; #define LDA(dst, b, h) for (int m = 0; m < 4; ++m) { \
;     dst[m][0] = *reinterpret_cast<const bf16x8*>((char*)SA(b, h) + aoff0 + m * 2048); \
;     dst[m][1] = *reinterpret_cast<const bf16x8*>((char*)SA(b, h) + aoff1 + m * 2048); }
; #define LDB(dst, b, h) for (int n = 0; n < 2; ++n) { \
;     dst[n][0] = *reinterpret_cast<const bf16x8*>((char*)SB(b, h) + boff0 + n * 256); \
;     dst[n][1] = *reinterpret_cast<const bf16x8*>((char*)SB(b, h) + boff1 + n * 256); }
; #define MMA(ai, bj, At, Btf) do { __builtin_amdgcn_s_setprio(1); \
;     for (int m = 0; m < 4; ++m) for (int n = 0; n < 2; ++n) for (int k = 0; k < 2; ++k) \
;       acc[ai][bj][m][n] = __builtin_amdgcn_mfma_f32_16x16x32_bf16(Btf[n][k], At[m][k], acc[ai][bj][m][n], 0, 0, 0); \
;     __builtin_amdgcn_s_setprio(0); } while (0)
; #define WAIT_V(n) asm volatile("s_waitcnt vmcnt(" #n ")" ::: "memory")
; #define WAIT_L(n) asm volatile("s_waitcnt lgkmcnt(" #n ")" ::: "memory")
; #define BAR __builtin_amdgcn_s_barrier()
; #define SCHED __builtin_amdgcn_sched_barrier(0)
; template <int EPI> ...
;     ...
;     WAIT_V(6); BAR; MMA(1, 1, At, B1); BAR;
;     LDB(B0, 1, 0); SCHED; LDA(At, 1, 0); STAGE(SA(0, 1), A, brow + HALF, t + 2);
;     WAIT_L(8); BAR; WAIT_L(0); MMA(0, 0, At, B0); BAR; SCHED;
;     LDB(B1, 1, 1); STAGE(SB(1, 0), Bt, bcol, t + 3);
;     BAR; WAIT_L(0); MMA(0, 1, At, B1); BAR;
	s_waitcnt lgkmcnt(0)
	s_setprio 1
	s_waitcnt lgkmcnt(0)
	v_mfma_f32_16x16x32_bf16 v[60:63], v[162:165], v[178:181], v[60:63]
	v_mfma_f32_16x16x32_bf16 v[56:59], v[166:169], v[178:181], v[56:59]
	v_mfma_f32_16x16x32_bf16 v[52:55], v[162:165], v[186:189], v[52:55]
	v_mfma_f32_16x16x32_bf16 v[48:51], v[166:169], v[186:189], v[48:51]
	v_mfma_f32_16x16x32_bf16 v[44:47], v[162:165], v[194:197], v[44:47]
	v_mfma_f32_16x16x32_bf16 v[40:43], v[166:169], v[194:197], v[40:43]
	v_mfma_f32_16x16x32_bf16 v[36:39], v[162:165], v[202:205], v[36:39]
	v_mfma_f32_16x16x32_bf16 v[32:35], v[166:169], v[202:205], v[32:35]
	v_mfma_f32_16x16x32_bf16 v[60:63], v[170:173], v[182:185], v[60:63]
	v_mfma_f32_16x16x32_bf16 v[56:59], v[174:177], v[182:185], v[56:59]
	v_mfma_f32_16x16x32_bf16 v[52:55], v[170:173], v[190:193], v[52:55]
	v_mfma_f32_16x16x32_bf16 v[48:51], v[174:177], v[190:193], v[48:51]
	v_mfma_f32_16x16x32_bf16 v[44:47], v[170:173], v[198:201], v[44:47]
	v_mfma_f32_16x16x32_bf16 v[40:43], v[174:177], v[198:201], v[40:43]
	v_mfma_f32_16x16x32_bf16 v[36:39], v[170:173], v[206:209], v[36:39]
	v_mfma_f32_16x16x32_bf16 v[32:35], v[174:177], v[206:209], v[32:35]
	s_setprio 0
	s_setprio 1
	v_mfma_f32_16x16x32_bf16 v[28:31], v[210:213], v[178:181], v[28:31]
	v_mfma_f32_16x16x32_bf16 v[24:27], v[214:217], v[178:181], v[24:27]
	v_mfma_f32_16x16x32_bf16 v[20:23], v[210:213], v[186:189], v[20:23]
	v_mfma_f32_16x16x32_bf16 v[16:19], v[214:217], v[186:189], v[16:19]
	v_mfma_f32_16x16x32_bf16 v[12:15], v[210:213], v[194:197], v[12:15]
	v_mfma_f32_16x16x32_bf16 v[8:11], v[214:217], v[194:197], v[8:11]
	v_mfma_f32_16x16x32_bf16 v[4:7], v[210:213], v[202:205], v[4:7]
	v_mfma_f32_16x16x32_bf16 v[0:3], v[214:217], v[202:205], v[0:3]
	v_mfma_f32_16x16x32_bf16 v[28:31], v[218:221], v[182:185], v[28:31]
	v_mfma_f32_16x16x32_bf16 v[24:27], v[222:225], v[182:185], v[24:27]
	v_mfma_f32_16x16x32_bf16 v[20:23], v[218:221], v[190:193], v[20:23]
	v_mfma_f32_16x16x32_bf16 v[16:19], v[222:225], v[190:193], v[16:19]
	v_mfma_f32_16x16x32_bf16 v[12:15], v[218:221], v[198:201], v[12:15]
	v_mfma_f32_16x16x32_bf16 v[8:11], v[222:225], v[198:201], v[8:11]
	v_mfma_f32_16x16x32_bf16 v[4:7], v[218:221], v[206:209], v[4:7]
	v_mfma_f32_16x16x32_bf16 v[0:3], v[222:225], v[206:209], v[0:3]
	s_setprio 0
	s_barrier
	ds_read_b128 v[162:165], v157
	ds_read_b128 v[166:169], v157 offset:256
	ds_read_b128 v[170:173], v158
	ds_read_b128 v[174:177], v158 offset:256
	v_readfirstlane_b32 s72, v142
	v_lshl_add_u64 v[210:211], v[226:227], 0, s[46:47]
	s_mov_b32 m0, s72
	v_readfirstlane_b32 s72, v143
	ds_read_b128 v[178:181], v150 offset:32768
	ds_read_b128 v[182:185], v150 offset:33792
	ds_read_b128 v[186:189], v150 offset:34816
	ds_read_b128 v[190:193], v150 offset:35840
	ds_read_b128 v[194:197], v150 offset:36864
	ds_read_b128 v[198:201], v150 offset:37888
	ds_read_b128 v[202:205], v150 offset:38912
	ds_read_b128 v[206:209], v150 offset:39936
	global_load_lds_dwordx4 v[210:211], off
	v_lshl_add_u64 v[210:211], v[226:227], 0, s[48:49]
	s_mov_b32 m0, s72
	s_nop 0
	global_load_lds_dwordx4 v[210:211], off
	s_waitcnt lgkmcnt(8)
	v_readfirstlane_b32 s72, v140
	v_lshl_add_u64 v[246:247], v[228:229], 0, s[36:37]
	s_mov_b32 m0, s72
	v_readfirstlane_b32 s72, v141
	global_load_lds_dwordx4 v[246:247], off
	v_lshl_add_u64 v[246:247], v[228:229], 0, s[38:39]
	s_mov_b32 m0, s72
	s_nop 0
	global_load_lds_dwordx4 v[246:247], off
	ds_read_b128 v[210:213], v159
	ds_read_b128 v[214:217], v159 offset:256
	ds_read_b128 v[218:221], v160
	ds_read_b128 v[222:225], v160 offset:256
	s_barrier
	s_waitcnt lgkmcnt(0)
	s_setprio 1
	s_waitcnt lgkmcnt(0)
	v_mfma_f32_16x16x32_bf16 v[124:127], v[162:165], v[178:181], v[124:127]
	v_mfma_f32_16x16x32_bf16 v[120:123], v[166:169], v[178:181], v[120:123]
	v_mfma_f32_16x16x32_bf16 v[116:119], v[162:165], v[186:189], v[116:119]
	v_mfma_f32_16x16x32_bf16 v[112:115], v[166:169], v[186:189], v[112:115]
	v_mfma_f32_16x16x32_bf16 v[108:111], v[162:165], v[194:197], v[108:111]
	v_mfma_f32_16x16x32_bf16 v[104:107], v[166:169], v[194:197], v[104:107]
	v_mfma_f32_16x16x32_bf16 v[100:103], v[162:165], v[202:205], v[100:103]
	v_mfma_f32_16x16x32_bf16 v[96:99], v[166:169], v[202:205], v[96:99]
	v_mfma_f32_16x16x32_bf16 v[124:127], v[170:173], v[182:185], v[124:127]
	v_mfma_f32_16x16x32_bf16 v[120:123], v[174:177], v[182:185], v[120:123]
	v_mfma_f32_16x16x32_bf16 v[116:119], v[170:173], v[190:193], v[116:119]
	v_mfma_f32_16x16x32_bf16 v[112:115], v[174:177], v[190:193], v[112:115]
	v_mfma_f32_16x16x32_bf16 v[108:111], v[170:173], v[198:201], v[108:111]
	v_mfma_f32_16x16x32_bf16 v[104:107], v[174:177], v[198:201], v[104:107]
	v_mfma_f32_16x16x32_bf16 v[100:103], v[170:173], v[206:209], v[100:103]
	v_mfma_f32_16x16x32_bf16 v[96:99], v[174:177], v[206:209], v[96:99]
	s_setprio 0
	s_waitcnt lgkmcnt(0)
	s_setprio 1
	s_waitcnt lgkmcnt(0)
	v_mfma_f32_16x16x32_bf16 v[92:95], v[210:213], v[178:181], v[92:95]
	v_mfma_f32_16x16x32_bf16 v[88:91], v[214:217], v[178:181], v[88:91]
	v_mfma_f32_16x16x32_bf16 v[84:87], v[210:213], v[186:189], v[84:87]
	v_mfma_f32_16x16x32_bf16 v[80:83], v[214:217], v[186:189], v[80:83]
	v_mfma_f32_16x16x32_bf16 v[76:79], v[210:213], v[194:197], v[76:79]
	v_mfma_f32_16x16x32_bf16 v[72:75], v[214:217], v[194:197], v[72:75]
	v_mfma_f32_16x16x32_bf16 v[68:71], v[210:213], v[202:205], v[68:71]
	v_mfma_f32_16x16x32_bf16 v[64:67], v[214:217], v[202:205], v[64:67]
	v_mfma_f32_16x16x32_bf16 v[92:95], v[218:221], v[182:185], v[92:95]
	v_mfma_f32_16x16x32_bf16 v[88:91], v[222:225], v[182:185], v[88:91]
	v_mfma_f32_16x16x32_bf16 v[84:87], v[218:221], v[190:193], v[84:87]
	v_mfma_f32_16x16x32_bf16 v[80:83], v[222:225], v[190:193], v[80:83]
	v_mfma_f32_16x16x32_bf16 v[76:79], v[218:221], v[198:201], v[76:79]
	v_mfma_f32_16x16x32_bf16 v[72:75], v[222:225], v[198:201], v[72:75]
	v_mfma_f32_16x16x32_bf16 v[68:71], v[218:221], v[206:209], v[68:71]
	v_mfma_f32_16x16x32_bf16 v[64:67], v[222:225], v[206:209], v[64:67]
	s_setprio 0
	s_barrier
; #define STAGE(P, BASE, br, kt) do { const char* _gb = (const char*)(BASE) + ((size_t)(br) * K + (size_t)(kt) * BK) * 2; \
;     __builtin_amdgcn_global_load_lds((const unsigned*)(_gb + loff0), (unsigned*)((char*)(P) + tid * 16), 16, 0, 0); \
;     __builtin_amdgcn_global_load_lds((const unsigned*)(_gb + (size_t)K * 128 + loff0), (unsigned*)((char*)(P) + tid * 16 + 8192), 16, 0, 0); } while (0)
; #define LDA(dst, b, h) for (int m = 0; m < 4; ++m) { \
;     dst[m][0] = *reinterpret_cast<const bf16x8*>((char*)SA(b, h) + aoff0 + m * 2048); \
;     dst[m][1] = *reinterpret_cast<const bf16x8*>((char*)SA(b, h) + aoff1 + m * 2048); }
; #define LDB(dst, b, h) for (int n = 0; n < 2; ++n) { \
;     dst[n][0] = *reinterpret_cast<const bf16x8*>((char*)SB(b, h) + boff0 + n * 256); \
;     dst[n][1] = *reinterpret_cast<const bf16x8*>((char*)SB(b, h) + boff1 + n * 256); }
; #define MMA(ai, bj, At, Btf) do { __builtin_amdgcn_s_setprio(1); \
;     for (int m = 0; m < 4; ++m) for (int n = 0; n < 2; ++n) for (int k = 0; k < 2; ++k) \
;       acc[ai][bj][m][n] = __builtin_amdgcn_mfma_f32_16x16x32_bf16(Btf[n][k], At[m][k], acc[ai][bj][m][n], 0, 0, 0); \
;     __builtin_amdgcn_s_setprio(0); } while (0)
; #define WAIT_V(n) asm volatile("s_waitcnt vmcnt(" #n ")" ::: "memory")
; #define WAIT_L(n) asm volatile("s_waitcnt lgkmcnt(" #n ")" ::: "memory")
; #define BAR __builtin_amdgcn_s_barrier()
; #define SCHED __builtin_amdgcn_sched_barrier(0)
; template <int EPI> ...
;     ...
;     LDB(B1, 1, 1); STAGE(SB(1, 0), Bt, bcol, t + 3);
;     BAR; WAIT_L(0); MMA(0, 1, At, B1); BAR;
;     LDA(At, 1, 1); STAGE(SA(1, 0), A, brow, t + 3);
;     BAR; WAIT_L(0); MMA(1, 0, At, B0); BAR; SCHED;
;     STAGE(SB(1, 1), Bt, bcol + HALF, t + 3);
;     WAIT_V(6); BAR; MMA(1, 1, At, B1); BAR;
;   }
;   { LDB(B0, 0, 0); LDA(At, 0, 0); STAGE(SA(1, 1), A, brow + HALF, nt - 1);
;     BAR; WAIT_L(0); MMA(0, 0, At, B0); BAR;
	v_readfirstlane_b32 s72, v144
	v_lshl_add_u64 v[230:231], v[228:229], 0, s[50:51]
	s_mov_b32 m0, s72
	v_readfirstlane_b32 s72, v145
	global_load_lds_dwordx4 v[230:231], off
	v_lshl_add_u64 v[230:231], v[228:229], 0, s[52:53]
	s_mov_b32 m0, s72
	s_nop 0
	global_load_lds_dwordx4 v[230:231], off
	v_readfirstlane_b32 s72, v146
	v_lshl_add_u64 v[230:231], v[226:227], 0, s[54:55]
	s_mov_b32 m0, s72
	v_readfirstlane_b32 s72, v147
	ds_read_b128 v[178:181], v150 offset:49152
	ds_read_b128 v[182:185], v150 offset:50176
	ds_read_b128 v[186:189], v150 offset:51200
	ds_read_b128 v[190:193], v150 offset:52224
	ds_read_b128 v[194:197], v150 offset:53248
	ds_read_b128 v[198:201], v150 offset:54272
	ds_read_b128 v[202:205], v150 offset:55296
	ds_read_b128 v[206:209], v150 offset:56320
	global_load_lds_dwordx4 v[230:231], off
	v_lshl_add_u64 v[226:227], v[226:227], 0, s[56:57]
	s_mov_b32 m0, s72
	s_nop 0
	global_load_lds_dwordx4 v[226:227], off
	s_waitcnt vmcnt(4)
	s_barrier
	s_waitcnt lgkmcnt(0)
	s_setprio 1
	s_waitcnt lgkmcnt(0)
	v_mfma_f32_16x16x32_bf16 v[60:63], v[162:165], v[178:181], v[60:63]
	v_mfma_f32_16x16x32_bf16 v[56:59], v[166:169], v[178:181], v[56:59]
	v_mfma_f32_16x16x32_bf16 v[52:55], v[162:165], v[186:189], v[52:55]
	v_mfma_f32_16x16x32_bf16 v[48:51], v[166:169], v[186:189], v[48:51]
	v_mfma_f32_16x16x32_bf16 v[44:47], v[162:165], v[194:197], v[44:47]
	v_mfma_f32_16x16x32_bf16 v[40:43], v[166:169], v[194:197], v[40:43]
	v_mfma_f32_16x16x32_bf16 v[36:39], v[162:165], v[202:205], v[36:39]
	v_mfma_f32_16x16x32_bf16 v[32:35], v[166:169], v[202:205], v[32:35]
	v_mfma_f32_16x16x32_bf16 v[60:63], v[170:173], v[182:185], v[60:63]
	v_mfma_f32_16x16x32_bf16 v[56:59], v[174:177], v[182:185], v[56:59]
	v_mfma_f32_16x16x32_bf16 v[52:55], v[170:173], v[190:193], v[52:55]
	v_mfma_f32_16x16x32_bf16 v[48:51], v[174:177], v[190:193], v[48:51]
	v_mfma_f32_16x16x32_bf16 v[44:47], v[170:173], v[198:201], v[44:47]
	v_mfma_f32_16x16x32_bf16 v[40:43], v[174:177], v[198:201], v[40:43]
	v_mfma_f32_16x16x32_bf16 v[36:39], v[170:173], v[206:209], v[36:39]
	v_mfma_f32_16x16x32_bf16 v[32:35], v[174:177], v[206:209], v[32:35]
	s_setprio 0
	s_setprio 1
	v_mfma_f32_16x16x32_bf16 v[28:31], v[210:213], v[178:181], v[28:31]
	v_mfma_f32_16x16x32_bf16 v[24:27], v[214:217], v[178:181], v[24:27]
	v_mfma_f32_16x16x32_bf16 v[20:23], v[210:213], v[186:189], v[20:23]
	v_mfma_f32_16x16x32_bf16 v[16:19], v[214:217], v[186:189], v[16:19]
	v_mfma_f32_16x16x32_bf16 v[12:15], v[210:213], v[194:197], v[12:15]
	v_mfma_f32_16x16x32_bf16 v[8:11], v[214:217], v[194:197], v[8:11]
	v_mfma_f32_16x16x32_bf16 v[4:7], v[210:213], v[202:205], v[4:7]
	v_mfma_f32_16x16x32_bf16 v[0:3], v[214:217], v[202:205], v[0:3]
	v_mfma_f32_16x16x32_bf16 v[28:31], v[218:221], v[182:185], v[28:31]
	v_mfma_f32_16x16x32_bf16 v[24:27], v[222:225], v[182:185], v[24:27]
	v_mfma_f32_16x16x32_bf16 v[20:23], v[218:221], v[190:193], v[20:23]
	v_mfma_f32_16x16x32_bf16 v[16:19], v[222:225], v[190:193], v[16:19]
	v_mfma_f32_16x16x32_bf16 v[12:15], v[218:221], v[198:201], v[12:15]
	v_mfma_f32_16x16x32_bf16 v[8:11], v[222:225], v[198:201], v[8:11]
	v_mfma_f32_16x16x32_bf16 v[4:7], v[218:221], v[206:209], v[4:7]
	v_mfma_f32_16x16x32_bf16 v[0:3], v[222:225], v[206:209], v[0:3]
	s_setprio 0
	s_add_i32 s67, s67, 2
	s_add_u32 s70, s70, 0x100
	s_addc_u32 s71, s71, 0
	s_add_u32 s68, s68, 0x100
	s_addc_u32 s69, s69, 0
	s_cmp_lt_u32 s67, 28
	s_barrier
	s_cbranch_scc1 .LBB0_277
	v_readfirstlane_b32 s72, v148
	v_lshl_add_u64 v[246:247], v[228:229], 0, s[58:59]
	s_mov_b32 m0, s72
	v_readfirstlane_b32 s72, v149
	global_load_lds_dwordx4 v[246:247], off
	v_lshl_add_u64 v[246:247], v[228:229], 0, s[60:61]
	s_mov_b32 m0, s72
	s_nop 0
	global_load_lds_dwordx4 v[246:247], off
	v_readfirstlane_b32 s67, v151
	v_lshl_add_u64 v[210:211], v[132:133], 0, s[62:63]
	s_mov_b32 m0, s67
	v_readfirstlane_b32 s67, v152
	ds_read_b128 v[162:165], v153
	ds_read_b128 v[166:169], v153 offset:256
	ds_read_b128 v[170:173], v154
	ds_read_b128 v[174:177], v154 offset:256
	ds_read_b128 v[178:181], v150
	ds_read_b128 v[182:185], v150 offset:1024
	ds_read_b128 v[186:189], v150 offset:2048
	ds_read_b128 v[190:193], v150 offset:3072
	ds_read_b128 v[194:197], v150 offset:4096
	ds_read_b128 v[198:201], v150 offset:5120
	ds_read_b128 v[202:205], v150 offset:6144
	ds_read_b128 v[206:209], v150 offset:7168
	global_load_lds_dwordx4 v[210:211], off
	v_lshl_add_u64 v[132:133], v[132:133], 0, s[64:65]
	s_mov_b32 m0, s67
	s_nop 0
	global_load_lds_dwordx4 v[132:133], off
	s_barrier
	s_waitcnt lgkmcnt(0)
	s_setprio 1
	s_waitcnt lgkmcnt(0)
	v_mfma_f32_16x16x32_bf16 v[124:127], v[162:165], v[178:181], v[124:127]
	v_mfma_f32_16x16x32_bf16 v[116:119], v[162:165], v[186:189], v[116:119]
	v_mfma_f32_16x16x32_bf16 v[108:111], v[162:165], v[194:197], v[108:111]
	v_mfma_f32_16x16x32_bf16 v[100:103], v[162:165], v[202:205], v[100:103]
	v_mfma_f32_16x16x32_bf16 v[124:127], v[170:173], v[182:185], v[124:127]
	v_mfma_f32_16x16x32_bf16 v[120:123], v[166:169], v[178:181], v[120:123]
	v_mfma_f32_16x16x32_bf16 v[116:119], v[170:173], v[190:193], v[116:119]
	v_mfma_f32_16x16x32_bf16 v[112:115], v[166:169], v[186:189], v[112:115]
	v_mfma_f32_16x16x32_bf16 v[108:111], v[170:173], v[198:201], v[108:111]
	v_mfma_f32_16x16x32_bf16 v[104:107], v[166:169], v[194:197], v[104:107]
	v_mfma_f32_16x16x32_bf16 v[100:103], v[170:173], v[206:209], v[100:103]
	v_mfma_f32_16x16x32_bf16 v[96:99], v[166:169], v[202:205], v[96:99]
	v_mfma_f32_16x16x32_bf16 v[210:213], v[174:177], v[182:185], v[120:123]
	v_mfma_f32_16x16x32_bf16 v[214:217], v[174:177], v[190:193], v[112:115]
	v_mfma_f32_16x16x32_bf16 v[218:221], v[174:177], v[198:201], v[104:107]
	v_mfma_f32_16x16x32_bf16 v[222:225], v[174:177], v[206:209], v[96:99]
	s_setprio 0
	s_barrier
; #define LDA(dst, b, h) for (int m = 0; m < 4; ++m) { \
;     dst[m][0] = *reinterpret_cast<const bf16x8*>((char*)SA(b, h) + aoff0 + m * 2048); \
;     dst[m][1] = *reinterpret_cast<const bf16x8*>((char*)SA(b, h) + aoff1 + m * 2048); }
; #define LDB(dst, b, h) for (int n = 0; n < 2; ++n) { \
;     dst[n][0] = *reinterpret_cast<const bf16x8*>((char*)SB(b, h) + boff0 + n * 256); \
;     dst[n][1] = *reinterpret_cast<const bf16x8*>((char*)SB(b, h) + boff1 + n * 256); }
; #define MMA(ai, bj, At, Btf) do { __builtin_amdgcn_s_setprio(1); \
;     for (int m = 0; m < 4; ++m) for (int n = 0; n < 2; ++n) for (int k = 0; k < 2; ++k) \
;       acc[ai][bj][m][n] = __builtin_amdgcn_mfma_f32_16x16x32_bf16(Btf[n][k], At[m][k], acc[ai][bj][m][n], 0, 0, 0); \
;     __builtin_amdgcn_s_setprio(0); } while (0)
; #define WAIT_V(n) asm volatile("s_waitcnt vmcnt(" #n ")" ::: "memory")
; #define WAIT_L(n) asm volatile("s_waitcnt lgkmcnt(" #n ")" ::: "memory")
; #define BAR __builtin_amdgcn_s_barrier()
; template <int EPI> ...
;     ...
;     BAR; WAIT_L(0); MMA(0, 0, At, B0); BAR;
;     LDB(B1, 0, 1); BAR; WAIT_L(0); MMA(0, 1, At, B1); BAR;
;     LDA(At, 0, 1); WAIT_V(4); BAR; WAIT_L(0); MMA(1, 0, At, B0); MMA(1, 1, At, B1); BAR; }
;   { LDB(B0, 1, 0); LDA(At, 1, 0); WAIT_V(2); BAR; WAIT_L(0); MMA(0, 0, At, B0); BAR;
	s_nop 1
	ds_read_b128 v[96:99], v155
	ds_read_b128 v[104:107], v155 offset:256
	ds_read_b128 v[112:115], v156
	ds_read_b128 v[120:123], v156 offset:256
	s_barrier
	s_waitcnt lgkmcnt(0)
	s_setprio 1
	s_waitcnt lgkmcnt(0)
	v_mfma_f32_16x16x32_bf16 v[92:95], v[96:99], v[178:181], v[92:95]
	v_mfma_f32_16x16x32_bf16 v[84:87], v[96:99], v[186:189], v[84:87]
	v_mfma_f32_16x16x32_bf16 v[76:79], v[96:99], v[194:197], v[76:79]
	v_mfma_f32_16x16x32_bf16 v[68:71], v[96:99], v[202:205], v[68:71]
	v_mfma_f32_16x16x32_bf16 v[92:95], v[112:115], v[182:185], v[92:95]
	v_mfma_f32_16x16x32_bf16 v[88:91], v[104:107], v[178:181], v[88:91]
	v_mfma_f32_16x16x32_bf16 v[84:87], v[112:115], v[190:193], v[84:87]
	v_mfma_f32_16x16x32_bf16 v[80:83], v[104:107], v[186:189], v[80:83]
	v_mfma_f32_16x16x32_bf16 v[76:79], v[112:115], v[198:201], v[76:79]
	v_mfma_f32_16x16x32_bf16 v[72:75], v[104:107], v[194:197], v[72:75]
	v_mfma_f32_16x16x32_bf16 v[68:71], v[112:115], v[206:209], v[68:71]
	v_mfma_f32_16x16x32_bf16 v[64:67], v[104:107], v[202:205], v[64:67]
	v_mfma_f32_16x16x32_bf16 v[178:181], v[120:123], v[182:185], v[88:91]
	v_mfma_f32_16x16x32_bf16 v[182:185], v[120:123], v[190:193], v[80:83]
	v_mfma_f32_16x16x32_bf16 v[186:189], v[120:123], v[198:201], v[72:75]
	v_mfma_f32_16x16x32_bf16 v[190:193], v[120:123], v[206:209], v[64:67]
	s_setprio 0
	s_barrier
	s_nop 1
	ds_read_b128 v[64:67], v150 offset:16384
	ds_read_b128 v[72:75], v150 offset:17408
	ds_read_b128 v[80:83], v150 offset:18432
	ds_read_b128 v[88:91], v150 offset:19456
	ds_read_b128 v[194:197], v150 offset:20480
	ds_read_b128 v[198:201], v150 offset:21504
	ds_read_b128 v[202:205], v150 offset:22528
	ds_read_b128 v[206:209], v150 offset:23552
	s_waitcnt vmcnt(4)
	s_barrier
	s_waitcnt lgkmcnt(0)
	s_setprio 1
	s_waitcnt lgkmcnt(0)
	v_mfma_f32_16x16x32_bf16 v[60:63], v[162:165], v[64:67], v[60:63]
	v_mfma_f32_16x16x32_bf16 v[56:59], v[166:169], v[64:67], v[56:59]
	v_mfma_f32_16x16x32_bf16 v[52:55], v[162:165], v[80:83], v[52:55]
	v_mfma_f32_16x16x32_bf16 v[40:43], v[166:169], v[194:197], v[40:43]
	v_mfma_f32_16x16x32_bf16 v[36:39], v[162:165], v[202:205], v[36:39]
	v_mfma_f32_16x16x32_bf16 v[60:63], v[170:173], v[72:75], v[60:63]
	v_mfma_f32_16x16x32_bf16 v[56:59], v[174:177], v[72:75], v[56:59]
	v_mfma_f32_16x16x32_bf16 v[52:55], v[170:173], v[88:91], v[52:55]
	v_mfma_f32_16x16x32_bf16 v[48:51], v[166:169], v[80:83], v[48:51]
	v_mfma_f32_16x16x32_bf16 v[44:47], v[162:165], v[194:197], v[44:47]
	v_mfma_f32_16x16x32_bf16 v[40:43], v[174:177], v[198:201], v[40:43]
	v_mfma_f32_16x16x32_bf16 v[36:39], v[170:173], v[206:209], v[36:39]
	v_mfma_f32_16x16x32_bf16 v[32:35], v[166:169], v[202:205], v[32:35]
	v_mfma_f32_16x16x32_bf16 v[226:229], v[174:177], v[88:91], v[48:51]
	v_mfma_f32_16x16x32_bf16 v[230:233], v[170:173], v[198:201], v[44:47]
	v_mfma_f32_16x16x32_bf16 v[162:165], v[174:177], v[206:209], v[32:35]
	s_setprio 0
	s_setprio 1
	v_mfma_f32_16x16x32_bf16 v[24:27], v[104:107], v[64:67], v[24:27]
	v_mfma_f32_16x16x32_bf16 v[20:23], v[96:99], v[80:83], v[20:23]
	v_mfma_f32_16x16x32_bf16 v[8:11], v[104:107], v[194:197], v[8:11]
	v_mfma_f32_16x16x32_bf16 v[4:7], v[96:99], v[202:205], v[4:7]
	v_mfma_f32_16x16x32_bf16 v[28:31], v[96:99], v[64:67], v[28:31]
	v_mfma_f32_16x16x32_bf16 v[24:27], v[120:123], v[72:75], v[24:27]
	v_mfma_f32_16x16x32_bf16 v[20:23], v[112:115], v[88:91], v[20:23]
	v_mfma_f32_16x16x32_bf16 v[16:19], v[104:107], v[80:83], v[16:19]
	v_mfma_f32_16x16x32_bf16 v[12:15], v[96:99], v[194:197], v[12:15]
	v_mfma_f32_16x16x32_bf16 v[8:11], v[120:123], v[198:201], v[8:11]
	v_mfma_f32_16x16x32_bf16 v[4:7], v[112:115], v[206:209], v[4:7]
	v_mfma_f32_16x16x32_bf16 v[0:3], v[104:107], v[202:205], v[0:3]
	v_mfma_f32_16x16x32_bf16 v[166:169], v[112:115], v[72:75], v[28:31]
	v_mfma_f32_16x16x32_bf16 v[170:173], v[120:123], v[88:91], v[16:19]
	v_mfma_f32_16x16x32_bf16 v[174:177], v[112:115], v[198:201], v[12:15]
	v_mfma_f32_16x16x32_bf16 v[194:197], v[120:123], v[206:209], v[0:3]
	s_setprio 0
	s_barrier
	s_nop 1
	ds_read_b128 v[0:3], v157
	ds_read_b128 v[198:201], v157 offset:256
	ds_read_b128 v[12:15], v158
	ds_read_b128 v[202:205], v158 offset:256
	ds_read_b128 v[16:19], v150 offset:32768
	ds_read_b128 v[28:31], v150 offset:33792
	ds_read_b128 v[32:35], v150 offset:34816
	ds_read_b128 v[44:47], v150 offset:35840
	ds_read_b128 v[48:51], v150 offset:36864
	ds_read_b128 v[206:209], v150 offset:37888
	ds_read_b128 v[234:237], v150 offset:38912
	ds_read_b128 v[238:241], v150 offset:39936
	s_waitcnt vmcnt(2)
	s_barrier
; #define LDA(dst, b, h) for (int m = 0; m < 4; ++m) { \
;     dst[m][0] = *reinterpret_cast<const bf16x8*>((char*)SA(b, h) + aoff0 + m * 2048); \
;     dst[m][1] = *reinterpret_cast<const bf16x8*>((char*)SA(b, h) + aoff1 + m * 2048); }
; #define LDB(dst, b, h) for (int n = 0; n < 2; ++n) { \
;     dst[n][0] = *reinterpret_cast<const bf16x8*>((char*)SB(b, h) + boff0 + n * 256); \
;     dst[n][1] = *reinterpret_cast<const bf16x8*>((char*)SB(b, h) + boff1 + n * 256); }
; #define MMA(ai, bj, At, Btf) do { __builtin_amdgcn_s_setprio(1); \
;     for (int m = 0; m < 4; ++m) for (int n = 0; n < 2; ++n) for (int k = 0; k < 2; ++k) \
;       acc[ai][bj][m][n] = __builtin_amdgcn_mfma_f32_16x16x32_bf16(Btf[n][k], At[m][k], acc[ai][bj][m][n], 0, 0, 0); \
;     __builtin_amdgcn_s_setprio(0); } while (0)
; #define WAIT_V(n) asm volatile("s_waitcnt vmcnt(" #n ")" ::: "memory")
; #define WAIT_L(n) asm volatile("s_waitcnt lgkmcnt(" #n ")" ::: "memory")
; #define BAR __builtin_amdgcn_s_barrier()
; template <int EPI> ...
;     ...
;   { LDB(B0, 1, 0); LDA(At, 1, 0); WAIT_V(2); BAR; WAIT_L(0); MMA(0, 0, At, B0); BAR;
;     LDB(B1, 1, 1); WAIT_V(0); BAR; WAIT_L(0); MMA(0, 1, At, B1); BAR;
;     LDA(At, 1, 1); BAR; WAIT_L(0); MMA(1, 0, At, B0); MMA(1, 1, At, B1); BAR; }
;   if (wr == 0) BAR;
	s_waitcnt lgkmcnt(0)
	s_setprio 1
	s_waitcnt lgkmcnt(0)
	v_mfma_f32_16x16x32_bf16 v[64:67], v[0:3], v[16:19], v[124:127]
	v_mfma_f32_16x16x32_bf16 v[120:123], v[12:15], v[28:31], v[64:67]
	v_mfma_f32_16x16x32_bf16 v[64:67], v[198:201], v[16:19], v[210:213]
	v_mfma_f32_16x16x32_bf16 v[112:115], v[202:205], v[28:31], v[64:67]
	v_mfma_f32_16x16x32_bf16 v[64:67], v[0:3], v[32:35], v[116:119]
	v_mfma_f32_16x16x32_bf16 v[104:107], v[12:15], v[44:47], v[64:67]
	v_mfma_f32_16x16x32_bf16 v[64:67], v[198:201], v[32:35], v[214:217]
	v_mfma_f32_16x16x32_bf16 v[96:99], v[202:205], v[44:47], v[64:67]
	v_mfma_f32_16x16x32_bf16 v[64:67], v[0:3], v[48:51], v[108:111]
	v_mfma_f32_16x16x32_bf16 v[88:91], v[12:15], v[206:209], v[64:67]
	v_mfma_f32_16x16x32_bf16 v[64:67], v[198:201], v[48:51], v[218:221]
	v_mfma_f32_16x16x32_bf16 v[80:83], v[202:205], v[206:209], v[64:67]
	v_mfma_f32_16x16x32_bf16 v[64:67], v[0:3], v[234:237], v[100:103]
	v_mfma_f32_16x16x32_bf16 v[72:75], v[12:15], v[238:241], v[64:67]
	v_mfma_f32_16x16x32_bf16 v[64:67], v[198:201], v[234:237], v[222:225]
	v_mfma_f32_16x16x32_bf16 v[64:67], v[202:205], v[238:241], v[64:67]
	s_setprio 0
	s_barrier
	ds_read_b128 v[210:213], v159
	ds_read_b128 v[214:217], v159 offset:256
	ds_read_b128 v[218:221], v160
	ds_read_b128 v[222:225], v160 offset:256
	s_waitcnt vmcnt(0)
	s_barrier
	s_waitcnt lgkmcnt(0)
	s_setprio 1
	s_waitcnt lgkmcnt(0)
	v_mfma_f32_16x16x32_bf16 v[92:95], v[210:213], v[16:19], v[92:95]
	v_mfma_f32_16x16x32_bf16 v[16:19], v[214:217], v[16:19], v[178:181]
	v_mfma_f32_16x16x32_bf16 v[116:119], v[222:225], v[28:31], v[16:19]
	v_mfma_f32_16x16x32_bf16 v[16:19], v[210:213], v[32:35], v[84:87]
	v_mfma_f32_16x16x32_bf16 v[108:111], v[218:221], v[44:47], v[16:19]
	v_mfma_f32_16x16x32_bf16 v[16:19], v[214:217], v[32:35], v[182:185]
	v_mfma_f32_16x16x32_bf16 v[100:103], v[222:225], v[44:47], v[16:19]
	v_mfma_f32_16x16x32_bf16 v[16:19], v[210:213], v[48:51], v[76:79]
	v_mfma_f32_16x16x32_bf16 v[124:127], v[218:221], v[28:31], v[92:95]
	v_mfma_f32_16x16x32_bf16 v[92:95], v[218:221], v[206:209], v[16:19]
	v_mfma_f32_16x16x32_bf16 v[16:19], v[214:217], v[48:51], v[186:189]
	v_mfma_f32_16x16x32_bf16 v[84:87], v[222:225], v[206:209], v[16:19]
	v_mfma_f32_16x16x32_bf16 v[16:19], v[210:213], v[234:237], v[68:71]
	v_mfma_f32_16x16x32_bf16 v[76:79], v[218:221], v[238:241], v[16:19]
	v_mfma_f32_16x16x32_bf16 v[16:19], v[214:217], v[234:237], v[190:193]
	v_mfma_f32_16x16x32_bf16 v[68:71], v[222:225], v[238:241], v[16:19]
	s_setprio 0
	s_barrier
	ds_read_b128 v[178:181], v150 offset:49152
	ds_read_b128 v[182:185], v150 offset:50176
	ds_read_b128 v[186:189], v150 offset:51200
	ds_read_b128 v[190:193], v150 offset:52224
	ds_read_b128 v[206:209], v150 offset:53248
	ds_read_b128 v[234:237], v150 offset:54272
	ds_read_b128 v[238:241], v150 offset:55296
	ds_read_b128 v[242:245], v150 offset:56320
	s_barrier
	s_waitcnt lgkmcnt(0)
	s_setprio 1
	s_waitcnt lgkmcnt(0)
	v_mfma_f32_16x16x32_bf16 v[16:19], v[0:3], v[178:181], v[60:63]
	v_mfma_f32_16x16x32_bf16 v[60:63], v[12:15], v[182:185], v[16:19]
	v_mfma_f32_16x16x32_bf16 v[16:19], v[198:201], v[178:181], v[56:59]
	v_mfma_f32_16x16x32_bf16 v[48:51], v[202:205], v[182:185], v[16:19]
	v_mfma_f32_16x16x32_bf16 v[16:19], v[0:3], v[186:189], v[52:55]
	v_mfma_f32_16x16x32_bf16 v[44:47], v[12:15], v[190:193], v[16:19]
	v_mfma_f32_16x16x32_bf16 v[16:19], v[198:201], v[186:189], v[226:229]
	v_mfma_f32_16x16x32_bf16 v[32:35], v[202:205], v[190:193], v[16:19]
	v_mfma_f32_16x16x32_bf16 v[16:19], v[0:3], v[206:209], v[230:233]
	v_mfma_f32_16x16x32_bf16 v[0:3], v[0:3], v[238:241], v[36:39]
	v_mfma_f32_16x16x32_bf16 v[28:31], v[12:15], v[234:237], v[16:19]
	v_mfma_f32_16x16x32_bf16 v[16:19], v[198:201], v[206:209], v[40:43]
	v_mfma_f32_16x16x32_bf16 v[12:15], v[12:15], v[242:245], v[0:3]
	v_mfma_f32_16x16x32_bf16 v[0:3], v[198:201], v[238:241], v[162:165]
	v_mfma_f32_16x16x32_bf16 v[16:19], v[202:205], v[234:237], v[16:19]
	v_mfma_f32_16x16x32_bf16 v[0:3], v[202:205], v[242:245], v[0:3]
	s_setprio 0
	s_setprio 1
	v_mfma_f32_16x16x32_bf16 v[20:23], v[210:213], v[186:189], v[20:23]
	v_mfma_f32_16x16x32_bf16 v[36:39], v[210:213], v[178:181], v[166:169]
	v_mfma_f32_16x16x32_bf16 v[40:43], v[218:221], v[190:193], v[20:23]
	v_mfma_f32_16x16x32_bf16 v[20:23], v[214:217], v[186:189], v[170:173]
	v_mfma_f32_16x16x32_bf16 v[56:59], v[218:221], v[182:185], v[36:39]
	v_mfma_f32_16x16x32_bf16 v[24:27], v[214:217], v[178:181], v[24:27]
	v_mfma_f32_16x16x32_bf16 v[36:39], v[222:225], v[190:193], v[20:23]
	v_mfma_f32_16x16x32_bf16 v[20:23], v[210:213], v[206:209], v[174:177]
	v_mfma_f32_16x16x32_bf16 v[8:11], v[214:217], v[206:209], v[8:11]
	v_mfma_f32_16x16x32_bf16 v[4:7], v[210:213], v[238:241], v[4:7]
	v_mfma_f32_16x16x32_bf16 v[52:55], v[222:225], v[182:185], v[24:27]
	v_mfma_f32_16x16x32_bf16 v[24:27], v[218:221], v[234:237], v[20:23]
	v_mfma_f32_16x16x32_bf16 v[20:23], v[222:225], v[234:237], v[8:11]
	v_mfma_f32_16x16x32_bf16 v[8:11], v[218:221], v[242:245], v[4:7]
	v_mfma_f32_16x16x32_bf16 v[4:7], v[214:217], v[238:241], v[194:197]
	v_mfma_f32_16x16x32_bf16 v[4:7], v[222:225], v[242:245], v[4:7]
	s_setprio 0
	s_barrier
	s_and_saveexec_b64 s[68:69], s[2:3]
	s_cbranch_execz .LBB0_271
	s_barrier
	s_branch .LBB0_271

; #define STAGE(P, BASE, br, kt) do { const char* _gb = (const char*)(BASE) + ((size_t)(br) * K + (size_t)(kt) * BK) * 2; \
;     __builtin_amdgcn_global_load_lds((const unsigned*)(_gb + loff0), (unsigned*)((char*)(P) + tid * 16), 16, 0, 0); \
;     __builtin_amdgcn_global_load_lds((const unsigned*)(_gb + (size_t)K * 128 + loff0), (unsigned*)((char*)(P) + tid * 16 + 8192), 16, 0, 0); } while (0)
; #define LDA(dst, b, h) for (int m = 0; m < 4; ++m) { \
;     dst[m][0] = *reinterpret_cast<const bf16x8*>((char*)SA(b, h) + aoff0 + m * 2048); \
;     dst[m][1] = *reinterpret_cast<const bf16x8*>((char*)SA(b, h) + aoff1 + m * 2048); }
; #define LDB(dst, b, h) for (int n = 0; n < 2; ++n) { \
;     dst[n][0] = *reinterpret_cast<const bf16x8*>((char*)SB(b, h) + boff0 + n * 256); \
;     dst[n][1] = *reinterpret_cast<const bf16x8*>((char*)SB(b, h) + boff1 + n * 256); }
; #define MMA(ai, bj, At, Btf) do { __builtin_amdgcn_s_setprio(1); \
;     for (int m = 0; m < 4; ++m) for (int n = 0; n < 2; ++n) for (int k = 0; k < 2; ++k) \
;       acc[ai][bj][m][n] = __builtin_amdgcn_mfma_f32_16x16x32_bf16(Btf[n][k], At[m][k], acc[ai][bj][m][n], 0, 0, 0); \
;     __builtin_amdgcn_s_setprio(0); } while (0)
; #define WAIT_V(n) asm volatile("s_waitcnt vmcnt(" #n ")" ::: "memory")
; #define WAIT_L(n) asm volatile("s_waitcnt lgkmcnt(" #n ")" ::: "memory")
; #define BAR __builtin_amdgcn_s_barrier()
; #define SCHED __builtin_amdgcn_sched_barrier(0)
; template <int EPI> ...
;     ...
;   STAGE(SB(1, 0), Bt, bcol, 1); STAGE(SA(1, 0), A, brow, 1); STAGE(SB(1, 1), Bt, bcol + HALF, 1);
;   WAIT_V(6); BAR;
;   for (int t = 0; t < nt - 2; t += 2) {
;     LDB(B0, 0, 0); SCHED; LDA(At, 0, 0); STAGE(SA(1, 1), A, brow + HALF, t + 1);
;     WAIT_L(8); BAR; WAIT_L(0); MMA(0, 0, At, B0); BAR; SCHED;
;     LDB(B1, 0, 1); STAGE(SB(0, 0), Bt, bcol, t + 2);
;     BAR; WAIT_L(0); MMA(0, 1, At, B1); BAR;
;     LDA(At, 0, 1); STAGE(SA(0, 0), A, brow, t + 2);
;     BAR; WAIT_L(0); MMA(1, 0, At, B0); BAR; SCHED;
;     STAGE(SB(0, 1), Bt, bcol + HALF, t + 2);
;     WAIT_V(6); BAR; MMA(1, 1, At, B1); BAR;
.LBB0_323:
	s_or_b64 exec, exec, s[64:65]
	v_readfirstlane_b32 s64, v143
	v_lshl_add_u64 v[6:7], v[0:1], 0, s[10:11]
	s_mov_b32 m0, s64
	v_readfirstlane_b32 s64, v144
	s_waitcnt vmcnt(2)
	s_barrier
	global_load_lds_dwordx4 v[6:7], off
	v_lshl_add_u64 v[0:1], v[0:1], 0, s[12:13]
	s_mov_b32 m0, s64
	v_readfirstlane_b32 s64, v145
	global_load_lds_dwordx4 v[0:1], off
	v_lshl_add_u64 v[0:1], v[2:3], 0, s[10:11]
	s_mov_b32 m0, s64
	v_readfirstlane_b32 s64, v146
	global_load_lds_dwordx4 v[0:1], off
	v_lshl_add_u64 v[0:1], v[2:3], 0, s[12:13]
	s_mov_b32 m0, s64
	v_readfirstlane_b32 s64, v147
	global_load_lds_dwordx4 v[0:1], off
	v_lshl_add_u64 v[0:1], v[4:5], 0, s[10:11]
	s_mov_b32 m0, s64
	v_readfirstlane_b32 s64, v148
	global_load_lds_dwordx4 v[0:1], off
	v_lshl_add_u64 v[0:1], v[4:5], 0, s[12:13]
	s_mov_b32 m0, s64
	s_ashr_i32 s61, s60, 31
	global_load_lds_dwordx4 v[0:1], off
	s_add_u32 s62, s6, s62
	s_addc_u32 s63, s7, s63
	s_add_u32 s64, s6, s77
	s_addc_u32 s65, s7, s76
	s_add_u32 s66, s6, s66
	v_mov_b32_e32 v0, 0
	s_addc_u32 s67, s7, s67
	s_mov_b32 s76, -2
	v_mov_b32_e32 v1, v0
	v_mov_b32_e32 v2, v0
	v_mov_b32_e32 v3, v0
	v_mov_b32_e32 v4, v0
	v_mov_b32_e32 v5, v0
	v_mov_b32_e32 v6, v0
	v_mov_b32_e32 v7, v0
	s_waitcnt vmcnt(6)
	s_sub_u32 s98, s62, 0x100
	s_subb_u32 s99, s63, 0
	v_lshl_add_u64 v[228:229], s[98:99], 0, v[132:133]
	s_barrier
.LBB0_324:
	ds_read_b128 v[160:163], v152
	ds_read_b128 v[164:167], v152 offset:256
	ds_read_b128 v[168:171], v153
	ds_read_b128 v[172:175], v153 offset:256
	v_lshl_add_u64 v[224:225], s[64:65], 0, v[132:133]
	v_readfirstlane_b32 s77, v150
	v_lshl_add_u64 v[208:209], v[224:225], 0, s[16:17]
	s_mov_b32 m0, s77
	v_readfirstlane_b32 s77, v151
	ds_read_b128 v[176:179], v149
	ds_read_b128 v[180:183], v149 offset:1024
	ds_read_b128 v[184:187], v149 offset:2048
	ds_read_b128 v[188:191], v149 offset:3072
	ds_read_b128 v[192:195], v149 offset:4096
	ds_read_b128 v[196:199], v149 offset:5120
	ds_read_b128 v[200:203], v149 offset:6144
	ds_read_b128 v[204:207], v149 offset:7168
	global_load_lds_dwordx4 v[208:209], off
	v_lshl_add_u64 v[208:209], v[224:225], 0, s[18:19]
	s_mov_b32 m0, s77
	s_nop 0
	global_load_lds_dwordx4 v[208:209], off
	s_waitcnt lgkmcnt(8)
	v_readfirstlane_b32 s77, v147
	v_lshl_add_u64 v[246:247], v[228:229], 0, s[56:57]
	s_mov_b32 m0, s77
	v_readfirstlane_b32 s77, v148
	global_load_lds_dwordx4 v[246:247], off
	v_lshl_add_u64 v[246:247], v[228:229], 0, s[58:59]
	s_mov_b32 m0, s77
	s_nop 0
	global_load_lds_dwordx4 v[246:247], off
	ds_read_b128 v[208:211], v154
	ds_read_b128 v[212:215], v154 offset:256
	ds_read_b128 v[216:219], v155
	ds_read_b128 v[220:223], v155 offset:256
	s_barrier
	s_waitcnt lgkmcnt(0)
	s_setprio 1
	s_waitcnt lgkmcnt(0)
	v_mfma_f32_16x16x32_bf16 v[124:127], v[160:163], v[176:179], v[124:127]
	v_mfma_f32_16x16x32_bf16 v[120:123], v[164:167], v[176:179], v[120:123]
	v_mfma_f32_16x16x32_bf16 v[116:119], v[160:163], v[184:187], v[116:119]
	v_mfma_f32_16x16x32_bf16 v[112:115], v[164:167], v[184:187], v[112:115]
	v_mfma_f32_16x16x32_bf16 v[108:111], v[160:163], v[192:195], v[108:111]
	v_mfma_f32_16x16x32_bf16 v[104:107], v[164:167], v[192:195], v[104:107]
	v_mfma_f32_16x16x32_bf16 v[100:103], v[160:163], v[200:203], v[100:103]
	v_mfma_f32_16x16x32_bf16 v[96:99], v[164:167], v[200:203], v[96:99]
	v_mfma_f32_16x16x32_bf16 v[124:127], v[168:171], v[180:183], v[124:127]
	v_mfma_f32_16x16x32_bf16 v[120:123], v[172:175], v[180:183], v[120:123]
	v_mfma_f32_16x16x32_bf16 v[116:119], v[168:171], v[188:191], v[116:119]
	v_mfma_f32_16x16x32_bf16 v[112:115], v[172:175], v[188:191], v[112:115]
	v_mfma_f32_16x16x32_bf16 v[108:111], v[168:171], v[196:199], v[108:111]
	v_mfma_f32_16x16x32_bf16 v[104:107], v[172:175], v[196:199], v[104:107]
	v_mfma_f32_16x16x32_bf16 v[100:103], v[168:171], v[204:207], v[100:103]
	v_mfma_f32_16x16x32_bf16 v[96:99], v[172:175], v[204:207], v[96:99]
	s_setprio 0
	s_waitcnt lgkmcnt(0)
	s_setprio 1
	s_waitcnt lgkmcnt(0)
	v_mfma_f32_16x16x32_bf16 v[92:95], v[208:211], v[176:179], v[92:95]
	v_mfma_f32_16x16x32_bf16 v[88:91], v[212:215], v[176:179], v[88:91]
	v_mfma_f32_16x16x32_bf16 v[84:87], v[208:211], v[184:187], v[84:87]
	v_mfma_f32_16x16x32_bf16 v[80:83], v[212:215], v[184:187], v[80:83]
	v_mfma_f32_16x16x32_bf16 v[76:79], v[208:211], v[192:195], v[76:79]
	v_mfma_f32_16x16x32_bf16 v[72:75], v[212:215], v[192:195], v[72:75]
	v_mfma_f32_16x16x32_bf16 v[68:71], v[208:211], v[200:203], v[68:71]
	v_mfma_f32_16x16x32_bf16 v[64:67], v[212:215], v[200:203], v[64:67]
	v_mfma_f32_16x16x32_bf16 v[92:95], v[216:219], v[180:183], v[92:95]
	v_mfma_f32_16x16x32_bf16 v[88:91], v[220:223], v[180:183], v[88:91]
	v_mfma_f32_16x16x32_bf16 v[84:87], v[216:219], v[188:191], v[84:87]
	v_mfma_f32_16x16x32_bf16 v[80:83], v[220:223], v[188:191], v[80:83]
	v_mfma_f32_16x16x32_bf16 v[76:79], v[216:219], v[196:199], v[76:79]
	v_mfma_f32_16x16x32_bf16 v[72:75], v[220:223], v[196:199], v[72:75]
	v_mfma_f32_16x16x32_bf16 v[68:71], v[216:219], v[204:207], v[68:71]
	v_mfma_f32_16x16x32_bf16 v[64:67], v[220:223], v[204:207], v[64:67]
	s_setprio 0
	s_barrier
	v_lshl_add_u64 v[226:227], s[66:67], 0, v[132:133]
	v_readfirstlane_b32 s77, v135
	v_lshl_add_u64 v[228:229], v[226:227], 0, s[20:21]
	s_mov_b32 m0, s77
	v_readfirstlane_b32 s77, v136
	global_load_lds_dwordx4 v[228:229], off
	v_lshl_add_u64 v[228:229], v[226:227], 0, s[22:23]
	s_mov_b32 m0, s77
	s_nop 0
	global_load_lds_dwordx4 v[228:229], off
	v_readfirstlane_b32 s77, v137
	v_lshl_add_u64 v[228:229], v[224:225], 0, s[26:27]
	s_mov_b32 m0, s77
	v_readfirstlane_b32 s77, v138
	ds_read_b128 v[176:179], v149 offset:16384
	ds_read_b128 v[180:183], v149 offset:17408
	ds_read_b128 v[184:187], v149 offset:18432
	ds_read_b128 v[188:191], v149 offset:19456
	ds_read_b128 v[192:195], v149 offset:20480
	ds_read_b128 v[196:199], v149 offset:21504
	ds_read_b128 v[200:203], v149 offset:22528
	ds_read_b128 v[204:207], v149 offset:23552
	global_load_lds_dwordx4 v[228:229], off
	v_lshl_add_u64 v[228:229], v[224:225], 0, s[28:29]
	s_mov_b32 m0, s77
	s_nop 0
	global_load_lds_dwordx4 v[228:229], off
	s_waitcnt vmcnt(4)
	s_barrier
; #define STAGE(P, BASE, br, kt) do { const char* _gb = (const char*)(BASE) + ((size_t)(br) * K + (size_t)(kt) * BK) * 2; \
;     __builtin_amdgcn_global_load_lds((const unsigned*)(_gb + loff0), (unsigned*)((char*)(P) + tid * 16), 16, 0, 0); \
;     __builtin_amdgcn_global_load_lds((const unsigned*)(_gb + (size_t)K * 128 + loff0), (unsigned*)((char*)(P) + tid * 16 + 8192), 16, 0, 0); } while (0)
; #define LDA(dst, b, h) for (int m = 0; m < 4; ++m) { \
;     dst[m][0] = *reinterpret_cast<const bf16x8*>((char*)SA(b, h) + aoff0 + m * 2048); \
;     dst[m][1] = *reinterpret_cast<const bf16x8*>((char*)SA(b, h) + aoff1 + m * 2048); }
; #define LDB(dst, b, h) for (int n = 0; n < 2; ++n) { \
;     dst[n][0] = *reinterpret_cast<const bf16x8*>((char*)SB(b, h) + boff0 + n * 256); \
;     dst[n][1] = *reinterpret_cast<const bf16x8*>((char*)SB(b, h) + boff1 + n * 256); }
; #define MMA(ai, bj, At, Btf) do { __builtin_amdgcn_s_setprio(1); \
;     for (int m = 0; m < 4; ++m) for (int n = 0; n < 2; ++n) for (int k = 0; k < 2; ++k) \
;       acc[ai][bj][m][n] = __builtin_amdgcn_mfma_f32_16x16x32_bf16(Btf[n][k], At[m][k], acc[ai][bj][m][n], 0, 0, 0); \
;     __builtin_amdgcn_s_setprio(0); } while (0)
; #define WAIT_V(n) asm volatile("s_waitcnt vmcnt(" #n ")" ::: "memory")
; #define WAIT_L(n) asm volatile("s_waitcnt lgkmcnt(" #n ")" ::: "memory")
; #define BAR __builtin_amdgcn_s_barrier()
; #define SCHED __builtin_amdgcn_sched_barrier(0)
; template <int EPI> ...
;     ...
;     WAIT_V(6); BAR; MMA(1, 1, At, B1); BAR;
;     LDB(B0, 1, 0); SCHED; LDA(At, 1, 0); STAGE(SA(0, 1), A, brow + HALF, t + 2);
;     WAIT_L(8); BAR; WAIT_L(0); MMA(0, 0, At, B0); BAR; SCHED;
;     LDB(B1, 1, 1); STAGE(SB(1, 0), Bt, bcol, t + 3);
;     BAR; WAIT_L(0); MMA(0, 1, At, B1); BAR;
	s_waitcnt lgkmcnt(0)
	s_setprio 1
	s_waitcnt lgkmcnt(0)
	v_mfma_f32_16x16x32_bf16 v[60:63], v[160:163], v[176:179], v[60:63]
	v_mfma_f32_16x16x32_bf16 v[56:59], v[164:167], v[176:179], v[56:59]
	v_mfma_f32_16x16x32_bf16 v[52:55], v[160:163], v[184:187], v[52:55]
	v_mfma_f32_16x16x32_bf16 v[48:51], v[164:167], v[184:187], v[48:51]
	v_mfma_f32_16x16x32_bf16 v[44:47], v[160:163], v[192:195], v[44:47]
	v_mfma_f32_16x16x32_bf16 v[40:43], v[164:167], v[192:195], v[40:43]
	v_mfma_f32_16x16x32_bf16 v[36:39], v[160:163], v[200:203], v[36:39]
	v_mfma_f32_16x16x32_bf16 v[32:35], v[164:167], v[200:203], v[32:35]
	v_mfma_f32_16x16x32_bf16 v[60:63], v[168:171], v[180:183], v[60:63]
	v_mfma_f32_16x16x32_bf16 v[56:59], v[172:175], v[180:183], v[56:59]
	v_mfma_f32_16x16x32_bf16 v[52:55], v[168:171], v[188:191], v[52:55]
	v_mfma_f32_16x16x32_bf16 v[48:51], v[172:175], v[188:191], v[48:51]
	v_mfma_f32_16x16x32_bf16 v[44:47], v[168:171], v[196:199], v[44:47]
	v_mfma_f32_16x16x32_bf16 v[40:43], v[172:175], v[196:199], v[40:43]
	v_mfma_f32_16x16x32_bf16 v[36:39], v[168:171], v[204:207], v[36:39]
	v_mfma_f32_16x16x32_bf16 v[32:35], v[172:175], v[204:207], v[32:35]
	s_setprio 0
	s_setprio 1
	v_mfma_f32_16x16x32_bf16 v[28:31], v[208:211], v[176:179], v[28:31]
	v_mfma_f32_16x16x32_bf16 v[24:27], v[212:215], v[176:179], v[24:27]
	v_mfma_f32_16x16x32_bf16 v[20:23], v[208:211], v[184:187], v[20:23]
	v_mfma_f32_16x16x32_bf16 v[16:19], v[212:215], v[184:187], v[16:19]
	v_mfma_f32_16x16x32_bf16 v[12:15], v[208:211], v[192:195], v[12:15]
	v_mfma_f32_16x16x32_bf16 v[8:11], v[212:215], v[192:195], v[8:11]
	v_mfma_f32_16x16x32_bf16 v[4:7], v[208:211], v[200:203], v[4:7]
	v_mfma_f32_16x16x32_bf16 v[0:3], v[212:215], v[200:203], v[0:3]
	v_mfma_f32_16x16x32_bf16 v[28:31], v[216:219], v[180:183], v[28:31]
	v_mfma_f32_16x16x32_bf16 v[24:27], v[220:223], v[180:183], v[24:27]
	v_mfma_f32_16x16x32_bf16 v[20:23], v[216:219], v[188:191], v[20:23]
	v_mfma_f32_16x16x32_bf16 v[16:19], v[220:223], v[188:191], v[16:19]
	v_mfma_f32_16x16x32_bf16 v[12:15], v[216:219], v[196:199], v[12:15]
	v_mfma_f32_16x16x32_bf16 v[8:11], v[220:223], v[196:199], v[8:11]
	v_mfma_f32_16x16x32_bf16 v[4:7], v[216:219], v[204:207], v[4:7]
	v_mfma_f32_16x16x32_bf16 v[0:3], v[220:223], v[204:207], v[0:3]
	s_setprio 0
	s_barrier
	ds_read_b128 v[160:163], v156
	ds_read_b128 v[164:167], v156 offset:256
	ds_read_b128 v[168:171], v157
	ds_read_b128 v[172:175], v157 offset:256
	v_readfirstlane_b32 s77, v141
	v_lshl_add_u64 v[208:209], v[224:225], 0, s[38:39]
	s_mov_b32 m0, s77
	v_readfirstlane_b32 s77, v142
	ds_read_b128 v[176:179], v149 offset:32768
	ds_read_b128 v[180:183], v149 offset:33792
	ds_read_b128 v[184:187], v149 offset:34816
	ds_read_b128 v[188:191], v149 offset:35840
	ds_read_b128 v[192:195], v149 offset:36864
	ds_read_b128 v[196:199], v149 offset:37888
	ds_read_b128 v[200:203], v149 offset:38912
	ds_read_b128 v[204:207], v149 offset:39936
	global_load_lds_dwordx4 v[208:209], off
	v_lshl_add_u64 v[208:209], v[224:225], 0, s[46:47]
	s_mov_b32 m0, s77
	s_nop 0
	global_load_lds_dwordx4 v[208:209], off
	s_waitcnt lgkmcnt(8)
	v_lshl_add_u64 v[228:229], s[62:63], 0, v[132:133]
	v_readfirstlane_b32 s77, v139
	v_lshl_add_u64 v[246:247], v[228:229], 0, s[30:31]
	s_mov_b32 m0, s77
	v_readfirstlane_b32 s77, v140
	global_load_lds_dwordx4 v[246:247], off
	v_lshl_add_u64 v[246:247], v[228:229], 0, s[36:37]
	s_mov_b32 m0, s77
	s_nop 0
	global_load_lds_dwordx4 v[246:247], off
	ds_read_b128 v[208:211], v158
	ds_read_b128 v[212:215], v158 offset:256
	ds_read_b128 v[216:219], v159
	ds_read_b128 v[220:223], v159 offset:256
	s_barrier
	s_waitcnt lgkmcnt(0)
	s_setprio 1
	s_waitcnt lgkmcnt(0)
	v_mfma_f32_16x16x32_bf16 v[124:127], v[160:163], v[176:179], v[124:127]
	v_mfma_f32_16x16x32_bf16 v[120:123], v[164:167], v[176:179], v[120:123]
	v_mfma_f32_16x16x32_bf16 v[116:119], v[160:163], v[184:187], v[116:119]
	v_mfma_f32_16x16x32_bf16 v[112:115], v[164:167], v[184:187], v[112:115]
	v_mfma_f32_16x16x32_bf16 v[108:111], v[160:163], v[192:195], v[108:111]
	v_mfma_f32_16x16x32_bf16 v[104:107], v[164:167], v[192:195], v[104:107]
	v_mfma_f32_16x16x32_bf16 v[100:103], v[160:163], v[200:203], v[100:103]
	v_mfma_f32_16x16x32_bf16 v[96:99], v[164:167], v[200:203], v[96:99]
	v_mfma_f32_16x16x32_bf16 v[124:127], v[168:171], v[180:183], v[124:127]
	v_mfma_f32_16x16x32_bf16 v[120:123], v[172:175], v[180:183], v[120:123]
	v_mfma_f32_16x16x32_bf16 v[116:119], v[168:171], v[188:191], v[116:119]
	v_mfma_f32_16x16x32_bf16 v[112:115], v[172:175], v[188:191], v[112:115]
	v_mfma_f32_16x16x32_bf16 v[108:111], v[168:171], v[196:199], v[108:111]
	v_mfma_f32_16x16x32_bf16 v[104:107], v[172:175], v[196:199], v[104:107]
	v_mfma_f32_16x16x32_bf16 v[100:103], v[168:171], v[204:207], v[100:103]
	v_mfma_f32_16x16x32_bf16 v[96:99], v[172:175], v[204:207], v[96:99]
	s_setprio 0
	s_waitcnt lgkmcnt(0)
	s_setprio 1
	s_waitcnt lgkmcnt(0)
	v_mfma_f32_16x16x32_bf16 v[92:95], v[208:211], v[176:179], v[92:95]
	v_mfma_f32_16x16x32_bf16 v[88:91], v[212:215], v[176:179], v[88:91]
	v_mfma_f32_16x16x32_bf16 v[84:87], v[208:211], v[184:187], v[84:87]
	v_mfma_f32_16x16x32_bf16 v[80:83], v[212:215], v[184:187], v[80:83]
	v_mfma_f32_16x16x32_bf16 v[76:79], v[208:211], v[192:195], v[76:79]
	v_mfma_f32_16x16x32_bf16 v[72:75], v[212:215], v[192:195], v[72:75]
	v_mfma_f32_16x16x32_bf16 v[68:71], v[208:211], v[200:203], v[68:71]
	v_mfma_f32_16x16x32_bf16 v[64:67], v[212:215], v[200:203], v[64:67]
	v_mfma_f32_16x16x32_bf16 v[92:95], v[216:219], v[180:183], v[92:95]
	v_mfma_f32_16x16x32_bf16 v[88:91], v[220:223], v[180:183], v[88:91]
	v_mfma_f32_16x16x32_bf16 v[84:87], v[216:219], v[188:191], v[84:87]
	v_mfma_f32_16x16x32_bf16 v[80:83], v[220:223], v[188:191], v[80:83]
	v_mfma_f32_16x16x32_bf16 v[76:79], v[216:219], v[196:199], v[76:79]
	v_mfma_f32_16x16x32_bf16 v[72:75], v[220:223], v[196:199], v[72:75]
	v_mfma_f32_16x16x32_bf16 v[68:71], v[216:219], v[204:207], v[68:71]
	v_mfma_f32_16x16x32_bf16 v[64:67], v[220:223], v[204:207], v[64:67]
	s_setprio 0
	s_barrier
; #define STAGE(P, BASE, br, kt) do { const char* _gb = (const char*)(BASE) + ((size_t)(br) * K + (size_t)(kt) * BK) * 2; \
;     __builtin_amdgcn_global_load_lds((const unsigned*)(_gb + loff0), (unsigned*)((char*)(P) + tid * 16), 16, 0, 0); \
;     __builtin_amdgcn_global_load_lds((const unsigned*)(_gb + (size_t)K * 128 + loff0), (unsigned*)((char*)(P) + tid * 16 + 8192), 16, 0, 0); } while (0)
; #define LDA(dst, b, h) for (int m = 0; m < 4; ++m) { \
;     dst[m][0] = *reinterpret_cast<const bf16x8*>((char*)SA(b, h) + aoff0 + m * 2048); \
;     dst[m][1] = *reinterpret_cast<const bf16x8*>((char*)SA(b, h) + aoff1 + m * 2048); }
; #define LDB(dst, b, h) for (int n = 0; n < 2; ++n) { \
;     dst[n][0] = *reinterpret_cast<const bf16x8*>((char*)SB(b, h) + boff0 + n * 256); \
;     dst[n][1] = *reinterpret_cast<const bf16x8*>((char*)SB(b, h) + boff1 + n * 256); }
; #define MMA(ai, bj, At, Btf) do { __builtin_amdgcn_s_setprio(1); \
;     for (int m = 0; m < 4; ++m) for (int n = 0; n < 2; ++n) for (int k = 0; k < 2; ++k) \
;       acc[ai][bj][m][n] = __builtin_amdgcn_mfma_f32_16x16x32_bf16(Btf[n][k], At[m][k], acc[ai][bj][m][n], 0, 0, 0); \
;     __builtin_amdgcn_s_setprio(0); } while (0)
; #define WAIT_V(n) asm volatile("s_waitcnt vmcnt(" #n ")" ::: "memory")
; #define WAIT_L(n) asm volatile("s_waitcnt lgkmcnt(" #n ")" ::: "memory")
; #define BAR __builtin_amdgcn_s_barrier()
; #define SCHED __builtin_amdgcn_sched_barrier(0)
; template <int EPI> ...
;     ...
;     LDB(B1, 1, 1); STAGE(SB(1, 0), Bt, bcol, t + 3);
;     BAR; WAIT_L(0); MMA(0, 1, At, B1); BAR;
;     LDA(At, 1, 1); STAGE(SA(1, 0), A, brow, t + 3);
;     BAR; WAIT_L(0); MMA(1, 0, At, B0); BAR; SCHED;
;     STAGE(SB(1, 1), Bt, bcol + HALF, t + 3);
;     WAIT_V(6); BAR; MMA(1, 1, At, B1); BAR;
;   }
;   { LDB(B0, 0, 0); LDA(At, 0, 0); STAGE(SA(1, 1), A, brow + HALF, nt - 1);
;     BAR; WAIT_L(0); MMA(0, 0, At, B0); BAR;
	v_readfirstlane_b32 s77, v143
	v_lshl_add_u64 v[230:231], v[226:227], 0, s[48:49]
	s_mov_b32 m0, s77
	v_readfirstlane_b32 s77, v144
	global_load_lds_dwordx4 v[230:231], off
	v_lshl_add_u64 v[226:227], v[226:227], 0, s[50:51]
	s_mov_b32 m0, s77
	s_nop 0
	global_load_lds_dwordx4 v[226:227], off
	v_readfirstlane_b32 s77, v145
	v_lshl_add_u64 v[226:227], v[224:225], 0, s[52:53]
	s_mov_b32 m0, s77
	v_readfirstlane_b32 s77, v146
	ds_read_b128 v[176:179], v149 offset:49152
	ds_read_b128 v[180:183], v149 offset:50176
	ds_read_b128 v[184:187], v149 offset:51200
	ds_read_b128 v[188:191], v149 offset:52224
	ds_read_b128 v[192:195], v149 offset:53248
	ds_read_b128 v[196:199], v149 offset:54272
	ds_read_b128 v[200:203], v149 offset:55296
	ds_read_b128 v[204:207], v149 offset:56320
	global_load_lds_dwordx4 v[226:227], off
	v_lshl_add_u64 v[224:225], v[224:225], 0, s[54:55]
	s_mov_b32 m0, s77
	s_nop 0
	global_load_lds_dwordx4 v[224:225], off
	s_waitcnt vmcnt(4)
	s_barrier
	s_waitcnt lgkmcnt(0)
	s_setprio 1
	s_waitcnt lgkmcnt(0)
	v_mfma_f32_16x16x32_bf16 v[60:63], v[160:163], v[176:179], v[60:63]
	v_mfma_f32_16x16x32_bf16 v[56:59], v[164:167], v[176:179], v[56:59]
	v_mfma_f32_16x16x32_bf16 v[52:55], v[160:163], v[184:187], v[52:55]
	v_mfma_f32_16x16x32_bf16 v[48:51], v[164:167], v[184:187], v[48:51]
	v_mfma_f32_16x16x32_bf16 v[44:47], v[160:163], v[192:195], v[44:47]
	v_mfma_f32_16x16x32_bf16 v[40:43], v[164:167], v[192:195], v[40:43]
	v_mfma_f32_16x16x32_bf16 v[36:39], v[160:163], v[200:203], v[36:39]
	v_mfma_f32_16x16x32_bf16 v[32:35], v[164:167], v[200:203], v[32:35]
	v_mfma_f32_16x16x32_bf16 v[60:63], v[168:171], v[180:183], v[60:63]
	v_mfma_f32_16x16x32_bf16 v[56:59], v[172:175], v[180:183], v[56:59]
	v_mfma_f32_16x16x32_bf16 v[52:55], v[168:171], v[188:191], v[52:55]
	v_mfma_f32_16x16x32_bf16 v[48:51], v[172:175], v[188:191], v[48:51]
	v_mfma_f32_16x16x32_bf16 v[44:47], v[168:171], v[196:199], v[44:47]
	v_mfma_f32_16x16x32_bf16 v[40:43], v[172:175], v[196:199], v[40:43]
	v_mfma_f32_16x16x32_bf16 v[36:39], v[168:171], v[204:207], v[36:39]
	v_mfma_f32_16x16x32_bf16 v[32:35], v[172:175], v[204:207], v[32:35]
	s_setprio 0
	s_setprio 1
	v_mfma_f32_16x16x32_bf16 v[28:31], v[208:211], v[176:179], v[28:31]
	v_mfma_f32_16x16x32_bf16 v[24:27], v[212:215], v[176:179], v[24:27]
	v_mfma_f32_16x16x32_bf16 v[20:23], v[208:211], v[184:187], v[20:23]
	v_mfma_f32_16x16x32_bf16 v[16:19], v[212:215], v[184:187], v[16:19]
	v_mfma_f32_16x16x32_bf16 v[12:15], v[208:211], v[192:195], v[12:15]
	v_mfma_f32_16x16x32_bf16 v[8:11], v[212:215], v[192:195], v[8:11]
	v_mfma_f32_16x16x32_bf16 v[4:7], v[208:211], v[200:203], v[4:7]
	v_mfma_f32_16x16x32_bf16 v[0:3], v[212:215], v[200:203], v[0:3]
	v_mfma_f32_16x16x32_bf16 v[28:31], v[216:219], v[180:183], v[28:31]
	v_mfma_f32_16x16x32_bf16 v[24:27], v[220:223], v[180:183], v[24:27]
	v_mfma_f32_16x16x32_bf16 v[20:23], v[216:219], v[188:191], v[20:23]
	v_mfma_f32_16x16x32_bf16 v[16:19], v[220:223], v[188:191], v[16:19]
	v_mfma_f32_16x16x32_bf16 v[12:15], v[216:219], v[196:199], v[12:15]
	v_mfma_f32_16x16x32_bf16 v[8:11], v[220:223], v[196:199], v[8:11]
	v_mfma_f32_16x16x32_bf16 v[4:7], v[216:219], v[204:207], v[4:7]
	v_mfma_f32_16x16x32_bf16 v[0:3], v[220:223], v[204:207], v[0:3]
	s_setprio 0
	s_add_i32 s76, s76, 2
	s_add_u32 s62, s62, 0x100
	s_addc_u32 s63, s63, 0
	s_add_u32 s64, s64, 0x100
	s_addc_u32 s65, s65, 0
	s_add_u32 s66, s66, 0x100
	s_addc_u32 s67, s67, 0
	s_cmpk_lt_u32 s76, 0x54
	s_barrier
	s_cbranch_scc1 .LBB0_324
	v_readfirstlane_b32 s77, v147
	v_lshl_add_u64 v[246:247], v[228:229], 0, s[56:57]
	s_mov_b32 m0, s77
	v_readfirstlane_b32 s77, v148
	global_load_lds_dwordx4 v[246:247], off
	v_lshl_add_u64 v[246:247], v[228:229], 0, s[58:59]
	s_mov_b32 m0, s77
	s_nop 0
	global_load_lds_dwordx4 v[246:247], off
	s_add_u32 s62, s70, s75
	s_addc_u32 s63, s71, s74
	v_lshl_add_u64 v[208:209], s[62:63], 0, v[128:129]
	v_readfirstlane_b32 s62, v150
	s_mov_b32 m0, s62
	v_readfirstlane_b32 s62, v151
	ds_read_b128 v[160:163], v152
	ds_read_b128 v[164:167], v152 offset:256
	ds_read_b128 v[168:171], v153
	ds_read_b128 v[172:175], v153 offset:256
	ds_read_b128 v[176:179], v149
	ds_read_b128 v[180:183], v149 offset:1024
	ds_read_b128 v[184:187], v149 offset:2048
	ds_read_b128 v[188:191], v149 offset:3072
	ds_read_b128 v[192:195], v149 offset:4096
	ds_read_b128 v[196:199], v149 offset:5120
	ds_read_b128 v[200:203], v149 offset:6144
	ds_read_b128 v[204:207], v149 offset:7168
	global_load_lds_dwordx4 v[208:209], off
	v_lshl_add_u64 v[208:209], v[208:209], 0, s[8:9]
	s_mov_b32 m0, s62
	s_nop 0
	global_load_lds_dwordx4 v[208:209], off
	s_barrier
	s_waitcnt lgkmcnt(0)
	s_setprio 1
	s_waitcnt lgkmcnt(0)
	v_mfma_f32_16x16x32_bf16 v[124:127], v[160:163], v[176:179], v[124:127]
	v_mfma_f32_16x16x32_bf16 v[116:119], v[160:163], v[184:187], v[116:119]
	v_mfma_f32_16x16x32_bf16 v[108:111], v[160:163], v[192:195], v[108:111]
	v_mfma_f32_16x16x32_bf16 v[100:103], v[160:163], v[200:203], v[100:103]
	v_mfma_f32_16x16x32_bf16 v[96:99], v[164:167], v[200:203], v[96:99]
	v_mfma_f32_16x16x32_bf16 v[124:127], v[168:171], v[180:183], v[124:127]
	v_mfma_f32_16x16x32_bf16 v[120:123], v[164:167], v[176:179], v[120:123]
	v_mfma_f32_16x16x32_bf16 v[116:119], v[168:171], v[188:191], v[116:119]
	v_mfma_f32_16x16x32_bf16 v[112:115], v[164:167], v[184:187], v[112:115]
	v_mfma_f32_16x16x32_bf16 v[108:111], v[168:171], v[196:199], v[108:111]
	v_mfma_f32_16x16x32_bf16 v[104:107], v[164:167], v[192:195], v[104:107]
	v_mfma_f32_16x16x32_bf16 v[100:103], v[168:171], v[204:207], v[100:103]
	v_mfma_f32_16x16x32_bf16 v[96:99], v[172:175], v[204:207], v[96:99]
	v_mfma_f32_16x16x32_bf16 v[208:211], v[172:175], v[180:183], v[120:123]
	v_mfma_f32_16x16x32_bf16 v[212:215], v[172:175], v[188:191], v[112:115]
	v_mfma_f32_16x16x32_bf16 v[216:219], v[172:175], v[196:199], v[104:107]
	s_setprio 0
	s_barrier
; #define LDA(dst, b, h) for (int m = 0; m < 4; ++m) { \
;     dst[m][0] = *reinterpret_cast<const bf16x8*>((char*)SA(b, h) + aoff0 + m * 2048); \
;     dst[m][1] = *reinterpret_cast<const bf16x8*>((char*)SA(b, h) + aoff1 + m * 2048); }
; #define LDB(dst, b, h) for (int n = 0; n < 2; ++n) { \
;     dst[n][0] = *reinterpret_cast<const bf16x8*>((char*)SB(b, h) + boff0 + n * 256); \
;     dst[n][1] = *reinterpret_cast<const bf16x8*>((char*)SB(b, h) + boff1 + n * 256); }
; #define MMA(ai, bj, At, Btf) do { __builtin_amdgcn_s_setprio(1); \
;     for (int m = 0; m < 4; ++m) for (int n = 0; n < 2; ++n) for (int k = 0; k < 2; ++k) \
;       acc[ai][bj][m][n] = __builtin_amdgcn_mfma_f32_16x16x32_bf16(Btf[n][k], At[m][k], acc[ai][bj][m][n], 0, 0, 0); \
;     __builtin_amdgcn_s_setprio(0); } while (0)
; #define WAIT_V(n) asm volatile("s_waitcnt vmcnt(" #n ")" ::: "memory")
; #define WAIT_L(n) asm volatile("s_waitcnt lgkmcnt(" #n ")" ::: "memory")
; #define BAR __builtin_amdgcn_s_barrier()
; template <int EPI> ...
;     ...
;     BAR; WAIT_L(0); MMA(0, 0, At, B0); BAR;
;     LDB(B1, 0, 1); BAR; WAIT_L(0); MMA(0, 1, At, B1); BAR;
;     LDA(At, 0, 1); WAIT_V(4); BAR; WAIT_L(0); MMA(1, 0, At, B0); MMA(1, 1, At, B1); BAR; }
;   { LDB(B0, 1, 0); LDA(At, 1, 0); WAIT_V(2); BAR; WAIT_L(0); MMA(0, 0, At, B0); BAR;
	s_nop 0
	ds_read_b128 v[104:107], v154
	ds_read_b128 v[112:115], v154 offset:256
	ds_read_b128 v[120:123], v155
	ds_read_b128 v[220:223], v155 offset:256
	s_barrier
	s_waitcnt lgkmcnt(0)
	s_setprio 1
	s_waitcnt lgkmcnt(0)
	v_mfma_f32_16x16x32_bf16 v[84:87], v[104:107], v[184:187], v[84:87]
	v_mfma_f32_16x16x32_bf16 v[76:79], v[104:107], v[192:195], v[76:79]
	v_mfma_f32_16x16x32_bf16 v[72:75], v[112:115], v[192:195], v[72:75]
	v_mfma_f32_16x16x32_bf16 v[92:95], v[104:107], v[176:179], v[92:95]
	v_mfma_f32_16x16x32_bf16 v[88:91], v[112:115], v[176:179], v[88:91]
	v_mfma_f32_16x16x32_bf16 v[84:87], v[120:123], v[188:191], v[84:87]
	v_mfma_f32_16x16x32_bf16 v[80:83], v[112:115], v[184:187], v[80:83]
	v_mfma_f32_16x16x32_bf16 v[76:79], v[120:123], v[196:199], v[76:79]
	v_mfma_f32_16x16x32_bf16 v[72:75], v[220:223], v[196:199], v[72:75]
	v_mfma_f32_16x16x32_bf16 v[68:71], v[104:107], v[200:203], v[68:71]
	v_mfma_f32_16x16x32_bf16 v[64:67], v[112:115], v[200:203], v[64:67]
	v_mfma_f32_16x16x32_bf16 v[224:227], v[120:123], v[180:183], v[92:95]
	v_mfma_f32_16x16x32_bf16 v[176:179], v[220:223], v[180:183], v[88:91]
	v_mfma_f32_16x16x32_bf16 v[180:183], v[220:223], v[188:191], v[80:83]
	v_mfma_f32_16x16x32_bf16 v[184:187], v[120:123], v[204:207], v[68:71]
	v_mfma_f32_16x16x32_bf16 v[188:191], v[220:223], v[204:207], v[64:67]
	s_setprio 0
	s_barrier
	s_nop 0
	ds_read_b128 v[64:67], v149 offset:16384
	ds_read_b128 v[68:71], v149 offset:17408
	ds_read_b128 v[80:83], v149 offset:18432
	ds_read_b128 v[88:91], v149 offset:19456
	ds_read_b128 v[92:95], v149 offset:20480
	ds_read_b128 v[192:195], v149 offset:21504
	ds_read_b128 v[196:199], v149 offset:22528
	ds_read_b128 v[200:203], v149 offset:23552
	s_waitcnt vmcnt(4)
	s_barrier
	s_waitcnt lgkmcnt(0)
	s_setprio 1
	s_waitcnt lgkmcnt(0)
	v_mfma_f32_16x16x32_bf16 v[52:55], v[160:163], v[80:83], v[52:55]
	v_mfma_f32_16x16x32_bf16 v[44:47], v[160:163], v[92:95], v[44:47]
	v_mfma_f32_16x16x32_bf16 v[36:39], v[160:163], v[196:199], v[36:39]
	v_mfma_f32_16x16x32_bf16 v[60:63], v[160:163], v[64:67], v[60:63]
	v_mfma_f32_16x16x32_bf16 v[56:59], v[164:167], v[64:67], v[56:59]
	v_mfma_f32_16x16x32_bf16 v[52:55], v[168:171], v[88:91], v[52:55]
	v_mfma_f32_16x16x32_bf16 v[48:51], v[164:167], v[80:83], v[48:51]
	v_mfma_f32_16x16x32_bf16 v[44:47], v[168:171], v[192:195], v[44:47]
	v_mfma_f32_16x16x32_bf16 v[40:43], v[164:167], v[92:95], v[40:43]
	v_mfma_f32_16x16x32_bf16 v[36:39], v[168:171], v[200:203], v[36:39]
	v_mfma_f32_16x16x32_bf16 v[32:35], v[164:167], v[196:199], v[32:35]
	v_mfma_f32_16x16x32_bf16 v[204:207], v[168:171], v[68:71], v[60:63]
	v_mfma_f32_16x16x32_bf16 v[228:231], v[172:175], v[68:71], v[56:59]
	v_mfma_f32_16x16x32_bf16 v[232:235], v[172:175], v[88:91], v[48:51]
	v_mfma_f32_16x16x32_bf16 v[236:239], v[172:175], v[192:195], v[40:43]
	v_mfma_f32_16x16x32_bf16 v[160:163], v[172:175], v[200:203], v[32:35]
	s_setprio 0
	s_setprio 1
	v_mfma_f32_16x16x32_bf16 v[28:31], v[104:107], v[64:67], v[28:31]
	v_mfma_f32_16x16x32_bf16 v[20:23], v[104:107], v[80:83], v[20:23]
	v_mfma_f32_16x16x32_bf16 v[12:15], v[104:107], v[92:95], v[12:15]
	v_mfma_f32_16x16x32_bf16 v[4:7], v[104:107], v[196:199], v[4:7]
	v_mfma_f32_16x16x32_bf16 v[28:31], v[120:123], v[68:71], v[28:31]
	v_mfma_f32_16x16x32_bf16 v[24:27], v[112:115], v[64:67], v[24:27]
	v_mfma_f32_16x16x32_bf16 v[20:23], v[120:123], v[88:91], v[20:23]
	v_mfma_f32_16x16x32_bf16 v[16:19], v[112:115], v[80:83], v[16:19]
	v_mfma_f32_16x16x32_bf16 v[12:15], v[120:123], v[192:195], v[12:15]
	v_mfma_f32_16x16x32_bf16 v[8:11], v[112:115], v[92:95], v[8:11]
	v_mfma_f32_16x16x32_bf16 v[4:7], v[120:123], v[200:203], v[4:7]
	v_mfma_f32_16x16x32_bf16 v[0:3], v[112:115], v[196:199], v[0:3]
	v_mfma_f32_16x16x32_bf16 v[164:167], v[220:223], v[68:71], v[24:27]
	v_mfma_f32_16x16x32_bf16 v[168:171], v[220:223], v[88:91], v[16:19]
	v_mfma_f32_16x16x32_bf16 v[172:175], v[220:223], v[192:195], v[8:11]
	v_mfma_f32_16x16x32_bf16 v[192:195], v[220:223], v[200:203], v[0:3]
	s_setprio 0
	s_barrier
	s_nop 1
	ds_read_b128 v[0:3], v156
	ds_read_b128 v[8:11], v156 offset:256
	ds_read_b128 v[16:19], v157
	ds_read_b128 v[24:27], v157 offset:256
	ds_read_b128 v[32:35], v149 offset:32768
	ds_read_b128 v[40:43], v149 offset:33792
	ds_read_b128 v[48:51], v149 offset:34816
	ds_read_b128 v[56:59], v149 offset:35840
	ds_read_b128 v[60:63], v149 offset:36864
	ds_read_b128 v[68:71], v149 offset:37888
	ds_read_b128 v[196:199], v149 offset:38912
	ds_read_b128 v[200:203], v149 offset:39936
	s_waitcnt vmcnt(2)
	s_barrier
; #define LDA(dst, b, h) for (int m = 0; m < 4; ++m) { \
;     dst[m][0] = *reinterpret_cast<const bf16x8*>((char*)SA(b, h) + aoff0 + m * 2048); \
;     dst[m][1] = *reinterpret_cast<const bf16x8*>((char*)SA(b, h) + aoff1 + m * 2048); }
; #define LDB(dst, b, h) for (int n = 0; n < 2; ++n) { \
;     dst[n][0] = *reinterpret_cast<const bf16x8*>((char*)SB(b, h) + boff0 + n * 256); \
;     dst[n][1] = *reinterpret_cast<const bf16x8*>((char*)SB(b, h) + boff1 + n * 256); }
; #define MMA(ai, bj, At, Btf) do { __builtin_amdgcn_s_setprio(1); \
;     for (int m = 0; m < 4; ++m) for (int n = 0; n < 2; ++n) for (int k = 0; k < 2; ++k) \
;       acc[ai][bj][m][n] = __builtin_amdgcn_mfma_f32_16x16x32_bf16(Btf[n][k], At[m][k], acc[ai][bj][m][n], 0, 0, 0); \
;     __builtin_amdgcn_s_setprio(0); } while (0)
; #define WAIT_V(n) asm volatile("s_waitcnt vmcnt(" #n ")" ::: "memory")
; #define WAIT_L(n) asm volatile("s_waitcnt lgkmcnt(" #n ")" ::: "memory")
; #define BAR __builtin_amdgcn_s_barrier()
; template <int EPI> ...
;     ...
;   { LDB(B0, 1, 0); LDA(At, 1, 0); WAIT_V(2); BAR; WAIT_L(0); MMA(0, 0, At, B0); BAR;
;     LDB(B1, 1, 1); WAIT_V(0); BAR; WAIT_L(0); MMA(0, 1, At, B1); BAR;
;     LDA(At, 1, 1); BAR; WAIT_L(0); MMA(1, 0, At, B0); MMA(1, 1, At, B1); BAR; }
;   if (wr == 0) BAR;
	s_waitcnt lgkmcnt(0)
	s_setprio 1
	s_waitcnt lgkmcnt(0)
	v_mfma_f32_16x16x32_bf16 v[64:67], v[0:3], v[32:35], v[124:127]
	v_mfma_f32_16x16x32_bf16 v[120:123], v[16:19], v[40:43], v[64:67]
	v_mfma_f32_16x16x32_bf16 v[64:67], v[8:11], v[32:35], v[208:211]
	v_mfma_f32_16x16x32_bf16 v[124:127], v[24:27], v[40:43], v[64:67]
	v_mfma_f32_16x16x32_bf16 v[64:67], v[0:3], v[48:51], v[116:119]
	v_mfma_f32_16x16x32_bf16 v[112:115], v[16:19], v[56:59], v[64:67]
	v_mfma_f32_16x16x32_bf16 v[64:67], v[8:11], v[48:51], v[212:215]
	v_mfma_f32_16x16x32_bf16 v[116:119], v[24:27], v[56:59], v[64:67]
	v_mfma_f32_16x16x32_bf16 v[64:67], v[0:3], v[60:63], v[108:111]
	v_mfma_f32_16x16x32_bf16 v[104:107], v[16:19], v[68:71], v[64:67]
	v_mfma_f32_16x16x32_bf16 v[64:67], v[8:11], v[60:63], v[216:219]
	v_mfma_f32_16x16x32_bf16 v[108:111], v[24:27], v[68:71], v[64:67]
	v_mfma_f32_16x16x32_bf16 v[64:67], v[0:3], v[196:199], v[100:103]
	v_mfma_f32_16x16x32_bf16 v[88:91], v[16:19], v[200:203], v[64:67]
	v_mfma_f32_16x16x32_bf16 v[64:67], v[8:11], v[196:199], v[96:99]
	v_mfma_f32_16x16x32_bf16 v[92:95], v[24:27], v[200:203], v[64:67]
	s_setprio 0
	s_barrier
	ds_read_b128 v[208:211], v158
	ds_read_b128 v[212:215], v158 offset:256
	ds_read_b128 v[216:219], v159
	ds_read_b128 v[220:223], v159 offset:256
	s_waitcnt vmcnt(0)
	s_barrier
	s_waitcnt lgkmcnt(0)
	s_setprio 1
	s_waitcnt lgkmcnt(0)
	v_mfma_f32_16x16x32_bf16 v[64:67], v[208:211], v[32:35], v[224:227]
	v_mfma_f32_16x16x32_bf16 v[32:35], v[212:215], v[32:35], v[176:179]
	v_mfma_f32_16x16x32_bf16 v[100:103], v[220:223], v[40:43], v[32:35]
	v_mfma_f32_16x16x32_bf16 v[32:35], v[208:211], v[48:51], v[84:87]
	v_mfma_f32_16x16x32_bf16 v[80:83], v[216:219], v[56:59], v[32:35]
	v_mfma_f32_16x16x32_bf16 v[32:35], v[212:215], v[48:51], v[180:183]
	v_mfma_f32_16x16x32_bf16 v[84:87], v[220:223], v[56:59], v[32:35]
	v_mfma_f32_16x16x32_bf16 v[32:35], v[208:211], v[60:63], v[76:79]
	v_mfma_f32_16x16x32_bf16 v[96:99], v[216:219], v[40:43], v[64:67]
	v_mfma_f32_16x16x32_bf16 v[64:67], v[216:219], v[68:71], v[32:35]
	v_mfma_f32_16x16x32_bf16 v[32:35], v[212:215], v[60:63], v[72:75]
	v_mfma_f32_16x16x32_bf16 v[68:71], v[220:223], v[68:71], v[32:35]
	v_mfma_f32_16x16x32_bf16 v[32:35], v[208:211], v[196:199], v[184:187]
	v_mfma_f32_16x16x32_bf16 v[56:59], v[216:219], v[200:203], v[32:35]
	v_mfma_f32_16x16x32_bf16 v[32:35], v[212:215], v[196:199], v[188:191]
	v_mfma_f32_16x16x32_bf16 v[60:63], v[220:223], v[200:203], v[32:35]
	s_setprio 0
	s_barrier
	ds_read_b128 v[176:179], v149 offset:49152
	ds_read_b128 v[180:183], v149 offset:50176
	ds_read_b128 v[184:187], v149 offset:51200
	ds_read_b128 v[188:191], v149 offset:52224
	ds_read_b128 v[196:199], v149 offset:53248
	ds_read_b128 v[200:203], v149 offset:54272
	ds_read_b128 v[224:227], v149 offset:55296
	ds_read_b128 v[240:243], v149 offset:56320
	s_barrier
	s_waitcnt lgkmcnt(0)
	s_setprio 1
	s_waitcnt lgkmcnt(0)
	v_mfma_f32_16x16x32_bf16 v[32:35], v[0:3], v[176:179], v[204:207]
	v_mfma_f32_16x16x32_bf16 v[72:75], v[16:19], v[180:183], v[32:35]
	v_mfma_f32_16x16x32_bf16 v[32:35], v[8:11], v[176:179], v[228:231]
	v_mfma_f32_16x16x32_bf16 v[76:79], v[24:27], v[180:183], v[32:35]
	v_mfma_f32_16x16x32_bf16 v[32:35], v[0:3], v[184:187], v[52:55]
	v_mfma_f32_16x16x32_bf16 v[48:51], v[16:19], v[188:191], v[32:35]
	v_mfma_f32_16x16x32_bf16 v[32:35], v[8:11], v[184:187], v[232:235]
	v_mfma_f32_16x16x32_bf16 v[52:55], v[24:27], v[188:191], v[32:35]
	v_mfma_f32_16x16x32_bf16 v[32:35], v[0:3], v[196:199], v[44:47]
	v_mfma_f32_16x16x32_bf16 v[40:43], v[16:19], v[200:203], v[32:35]
	v_mfma_f32_16x16x32_bf16 v[32:35], v[8:11], v[196:199], v[236:239]
	v_mfma_f32_16x16x32_bf16 v[0:3], v[0:3], v[224:227], v[36:39]
	v_mfma_f32_16x16x32_bf16 v[44:47], v[24:27], v[200:203], v[32:35]
	v_mfma_f32_16x16x32_bf16 v[32:35], v[16:19], v[240:243], v[0:3]
	v_mfma_f32_16x16x32_bf16 v[0:3], v[8:11], v[224:227], v[160:163]
	v_mfma_f32_16x16x32_bf16 v[36:39], v[24:27], v[240:243], v[0:3]
	s_setprio 0
	s_setprio 1
	v_mfma_f32_16x16x32_bf16 v[0:3], v[208:211], v[176:179], v[28:31]
	v_mfma_f32_16x16x32_bf16 v[24:27], v[216:219], v[180:183], v[0:3]
	v_mfma_f32_16x16x32_bf16 v[0:3], v[212:215], v[176:179], v[164:167]
	v_mfma_f32_16x16x32_bf16 v[28:31], v[220:223], v[180:183], v[0:3]
	v_mfma_f32_16x16x32_bf16 v[0:3], v[208:211], v[184:187], v[20:23]
	v_mfma_f32_16x16x32_bf16 v[16:19], v[216:219], v[188:191], v[0:3]
	v_mfma_f32_16x16x32_bf16 v[0:3], v[212:215], v[184:187], v[168:171]
	v_mfma_f32_16x16x32_bf16 v[20:23], v[220:223], v[188:191], v[0:3]
	v_mfma_f32_16x16x32_bf16 v[0:3], v[208:211], v[196:199], v[12:15]
	v_mfma_f32_16x16x32_bf16 v[8:11], v[216:219], v[200:203], v[0:3]
	v_mfma_f32_16x16x32_bf16 v[0:3], v[212:215], v[196:199], v[172:175]
	v_mfma_f32_16x16x32_bf16 v[12:15], v[220:223], v[200:203], v[0:3]
	v_mfma_f32_16x16x32_bf16 v[0:3], v[208:211], v[224:227], v[4:7]
	v_mfma_f32_16x16x32_bf16 v[4:7], v[212:215], v[224:227], v[192:195]
	v_mfma_f32_16x16x32_bf16 v[0:3], v[216:219], v[240:243], v[0:3]
	v_mfma_f32_16x16x32_bf16 v[4:7], v[220:223], v[240:243], v[4:7]
	s_setprio 0
	s_barrier
	s_and_saveexec_b64 s[62:63], s[2:3]
	s_cbranch_execz .LBB0_318
	s_barrier
	s_branch .LBB0_318

; #define STAGE(P, BASE, br, kt) do { const char* _gb = (const char*)(BASE) + ((size_t)(br) * K + (size_t)(kt) * BK) * 2; \
;     __builtin_amdgcn_global_load_lds((const unsigned*)(_gb + loff0), (unsigned*)((char*)(P) + tid * 16), 16, 0, 0); \
;     __builtin_amdgcn_global_load_lds((const unsigned*)(_gb + (size_t)K * 128 + loff0), (unsigned*)((char*)(P) + tid * 16 + 8192), 16, 0, 0); } while (0)
; #define LDA(dst, b, h) for (int m = 0; m < 4; ++m) { \
;     dst[m][0] = *reinterpret_cast<const bf16x8*>((char*)SA(b, h) + aoff0 + m * 2048); \
;     dst[m][1] = *reinterpret_cast<const bf16x8*>((char*)SA(b, h) + aoff1 + m * 2048); }
; #define LDB(dst, b, h) for (int n = 0; n < 2; ++n) { \
;     dst[n][0] = *reinterpret_cast<const bf16x8*>((char*)SB(b, h) + boff0 + n * 256); \
;     dst[n][1] = *reinterpret_cast<const bf16x8*>((char*)SB(b, h) + boff1 + n * 256); }
; #define MMA(ai, bj, At, Btf) do { __builtin_amdgcn_s_setprio(1); \
;     for (int m = 0; m < 4; ++m) for (int n = 0; n < 2; ++n) for (int k = 0; k < 2; ++k) \
;       acc[ai][bj][m][n] = __builtin_amdgcn_mfma_f32_16x16x32_bf16(Btf[n][k], At[m][k], acc[ai][bj][m][n], 0, 0, 0); \
;     __builtin_amdgcn_s_setprio(0); } while (0)
; #define WAIT_V(n) asm volatile("s_waitcnt vmcnt(" #n ")" ::: "memory")
; #define WAIT_L(n) asm volatile("s_waitcnt lgkmcnt(" #n ")" ::: "memory")
; #define BAR __builtin_amdgcn_s_barrier()
; #define SCHED __builtin_amdgcn_sched_barrier(0)
; template <int EPI> ...
;     ...
;   STAGE(SB(1, 0), Bt, bcol, 1); STAGE(SA(1, 0), A, brow, 1); STAGE(SB(1, 1), Bt, bcol + HALF, 1);
;   WAIT_V(6); BAR;
;   for (int t = 0; t < nt - 2; t += 2) {
;     LDB(B0, 0, 0); SCHED; LDA(At, 0, 0); STAGE(SA(1, 1), A, brow + HALF, t + 1);
;     WAIT_L(8); BAR; WAIT_L(0); MMA(0, 0, At, B0); BAR; SCHED;
;     LDB(B1, 0, 1); STAGE(SB(0, 0), Bt, bcol, t + 2);
;     BAR; WAIT_L(0); MMA(0, 1, At, B1); BAR;
;     LDA(At, 0, 1); STAGE(SA(0, 0), A, brow, t + 2);
;     BAR; WAIT_L(0); MMA(1, 0, At, B0); BAR; SCHED;
;     STAGE(SB(0, 1), Bt, bcol + HALF, t + 2);
;     WAIT_V(6); BAR; MMA(1, 1, At, B1); BAR;
.LBB0_410:
	s_or_b64 exec, exec, s[70:71]
	v_readfirstlane_b32 s61, v143
	v_lshl_add_u64 v[6:7], v[0:1], 0, s[10:11]
	s_mov_b32 m0, s61
	v_readfirstlane_b32 s61, v144
	s_waitcnt vmcnt(2)
	s_barrier
	global_load_lds_dwordx4 v[6:7], off
	v_lshl_add_u64 v[0:1], v[0:1], 0, s[12:13]
	s_mov_b32 m0, s61
	v_readfirstlane_b32 s61, v145
	global_load_lds_dwordx4 v[0:1], off
	v_lshl_add_u64 v[0:1], v[2:3], 0, s[10:11]
	s_mov_b32 m0, s61
	v_readfirstlane_b32 s61, v146
	global_load_lds_dwordx4 v[0:1], off
	v_lshl_add_u64 v[0:1], v[2:3], 0, s[12:13]
	s_mov_b32 m0, s61
	v_readfirstlane_b32 s61, v147
	global_load_lds_dwordx4 v[0:1], off
	v_lshl_add_u64 v[0:1], v[4:5], 0, s[10:11]
	s_mov_b32 m0, s61
	v_readfirstlane_b32 s61, v148
	global_load_lds_dwordx4 v[0:1], off
	v_lshl_add_u64 v[0:1], v[4:5], 0, s[12:13]
	s_mov_b32 m0, s61
	s_add_u32 s66, s6, s66
	global_load_lds_dwordx4 v[0:1], off
	s_addc_u32 s67, s7, s67
	s_add_u32 s68, s6, s68
	v_mov_b32_e32 v0, 0
	s_addc_u32 s69, s7, s69
	s_mov_b32 s61, -2
	v_mov_b32_e32 v1, v0
	v_mov_b32_e32 v2, v0
	v_mov_b32_e32 v3, v0
	v_mov_b32_e32 v4, v0
	v_mov_b32_e32 v5, v0
	v_mov_b32_e32 v6, v0
	v_mov_b32_e32 v7, v0
	s_waitcnt vmcnt(6)
	s_sub_u32 s98, s66, 0x100
	s_subb_u32 s99, s67, 0
	v_lshl_add_u64 v[226:227], s[98:99], 0, v[132:133]
	s_barrier
.LBB0_411:
	ds_read_b128 v[160:163], v152
	ds_read_b128 v[164:167], v152 offset:256
	ds_read_b128 v[168:171], v153
	ds_read_b128 v[172:175], v153 offset:256
	v_lshl_add_u64 v[224:225], s[68:69], 0, v[132:133]
	v_readfirstlane_b32 s70, v150
	v_lshl_add_u64 v[208:209], v[224:225], 0, s[16:17]
	s_mov_b32 m0, s70
	v_readfirstlane_b32 s70, v151
	ds_read_b128 v[176:179], v149
	ds_read_b128 v[180:183], v149 offset:1024
	ds_read_b128 v[184:187], v149 offset:2048
	ds_read_b128 v[188:191], v149 offset:3072
	ds_read_b128 v[192:195], v149 offset:4096
	ds_read_b128 v[196:199], v149 offset:5120
	ds_read_b128 v[200:203], v149 offset:6144
	ds_read_b128 v[204:207], v149 offset:7168
	global_load_lds_dwordx4 v[208:209], off
	v_lshl_add_u64 v[208:209], v[224:225], 0, s[18:19]
	s_mov_b32 m0, s70
	s_nop 0
	global_load_lds_dwordx4 v[208:209], off
	s_waitcnt lgkmcnt(8)
	v_readfirstlane_b32 s70, v147
	v_lshl_add_u64 v[246:247], v[226:227], 0, s[56:57]
	s_mov_b32 m0, s70
	v_readfirstlane_b32 s70, v148
	global_load_lds_dwordx4 v[246:247], off
	v_lshl_add_u64 v[246:247], v[226:227], 0, s[58:59]
	s_mov_b32 m0, s70
	s_nop 0
	global_load_lds_dwordx4 v[246:247], off
	ds_read_b128 v[208:211], v154
	ds_read_b128 v[212:215], v154 offset:256
	ds_read_b128 v[216:219], v155
	ds_read_b128 v[220:223], v155 offset:256
	s_barrier
	s_waitcnt lgkmcnt(0)
	s_setprio 1
	s_waitcnt lgkmcnt(0)
	v_mfma_f32_16x16x32_bf16 v[124:127], v[160:163], v[176:179], v[124:127]
	v_mfma_f32_16x16x32_bf16 v[120:123], v[164:167], v[176:179], v[120:123]
	v_mfma_f32_16x16x32_bf16 v[116:119], v[160:163], v[184:187], v[116:119]
	v_mfma_f32_16x16x32_bf16 v[112:115], v[164:167], v[184:187], v[112:115]
	v_mfma_f32_16x16x32_bf16 v[108:111], v[160:163], v[192:195], v[108:111]
	v_mfma_f32_16x16x32_bf16 v[104:107], v[164:167], v[192:195], v[104:107]
	v_mfma_f32_16x16x32_bf16 v[100:103], v[160:163], v[200:203], v[100:103]
	v_mfma_f32_16x16x32_bf16 v[96:99], v[164:167], v[200:203], v[96:99]
	v_mfma_f32_16x16x32_bf16 v[124:127], v[168:171], v[180:183], v[124:127]
	v_mfma_f32_16x16x32_bf16 v[120:123], v[172:175], v[180:183], v[120:123]
	v_mfma_f32_16x16x32_bf16 v[116:119], v[168:171], v[188:191], v[116:119]
	v_mfma_f32_16x16x32_bf16 v[112:115], v[172:175], v[188:191], v[112:115]
	v_mfma_f32_16x16x32_bf16 v[108:111], v[168:171], v[196:199], v[108:111]
	v_mfma_f32_16x16x32_bf16 v[104:107], v[172:175], v[196:199], v[104:107]
	v_mfma_f32_16x16x32_bf16 v[100:103], v[168:171], v[204:207], v[100:103]
	v_mfma_f32_16x16x32_bf16 v[96:99], v[172:175], v[204:207], v[96:99]
	s_setprio 0
	s_waitcnt lgkmcnt(0)
	s_setprio 1
	s_waitcnt lgkmcnt(0)
	v_mfma_f32_16x16x32_bf16 v[92:95], v[208:211], v[176:179], v[92:95]
	v_mfma_f32_16x16x32_bf16 v[88:91], v[212:215], v[176:179], v[88:91]
	v_mfma_f32_16x16x32_bf16 v[84:87], v[208:211], v[184:187], v[84:87]
	v_mfma_f32_16x16x32_bf16 v[80:83], v[212:215], v[184:187], v[80:83]
	v_mfma_f32_16x16x32_bf16 v[76:79], v[208:211], v[192:195], v[76:79]
	v_mfma_f32_16x16x32_bf16 v[72:75], v[212:215], v[192:195], v[72:75]
	v_mfma_f32_16x16x32_bf16 v[68:71], v[208:211], v[200:203], v[68:71]
	v_mfma_f32_16x16x32_bf16 v[64:67], v[212:215], v[200:203], v[64:67]
	v_mfma_f32_16x16x32_bf16 v[92:95], v[216:219], v[180:183], v[92:95]
	v_mfma_f32_16x16x32_bf16 v[88:91], v[220:223], v[180:183], v[88:91]
	v_mfma_f32_16x16x32_bf16 v[84:87], v[216:219], v[188:191], v[84:87]
	v_mfma_f32_16x16x32_bf16 v[80:83], v[220:223], v[188:191], v[80:83]
	v_mfma_f32_16x16x32_bf16 v[76:79], v[216:219], v[196:199], v[76:79]
	v_mfma_f32_16x16x32_bf16 v[72:75], v[220:223], v[196:199], v[72:75]
	v_mfma_f32_16x16x32_bf16 v[68:71], v[216:219], v[204:207], v[68:71]
	v_mfma_f32_16x16x32_bf16 v[64:67], v[220:223], v[204:207], v[64:67]
	s_setprio 0
	s_barrier
	v_lshl_add_u64 v[226:227], s[66:67], 0, v[132:133]
	v_readfirstlane_b32 s70, v135
	v_lshl_add_u64 v[228:229], v[226:227], 0, s[20:21]
	s_mov_b32 m0, s70
	v_readfirstlane_b32 s70, v136
	global_load_lds_dwordx4 v[228:229], off
	v_lshl_add_u64 v[228:229], v[226:227], 0, s[22:23]
	s_mov_b32 m0, s70
	s_nop 0
	global_load_lds_dwordx4 v[228:229], off
	v_readfirstlane_b32 s70, v137
	v_lshl_add_u64 v[228:229], v[224:225], 0, s[26:27]
	s_mov_b32 m0, s70
	v_readfirstlane_b32 s70, v138
	ds_read_b128 v[176:179], v149 offset:16384
	ds_read_b128 v[180:183], v149 offset:17408
	ds_read_b128 v[184:187], v149 offset:18432
	ds_read_b128 v[188:191], v149 offset:19456
	ds_read_b128 v[192:195], v149 offset:20480
	ds_read_b128 v[196:199], v149 offset:21504
	ds_read_b128 v[200:203], v149 offset:22528
	ds_read_b128 v[204:207], v149 offset:23552
	global_load_lds_dwordx4 v[228:229], off
	v_lshl_add_u64 v[228:229], v[224:225], 0, s[28:29]
	s_mov_b32 m0, s70
	s_nop 0
	global_load_lds_dwordx4 v[228:229], off
	s_waitcnt vmcnt(4)
	s_barrier
; #define STAGE(P, BASE, br, kt) do { const char* _gb = (const char*)(BASE) + ((size_t)(br) * K + (size_t)(kt) * BK) * 2; \
;     __builtin_amdgcn_global_load_lds((const unsigned*)(_gb + loff0), (unsigned*)((char*)(P) + tid * 16), 16, 0, 0); \
;     __builtin_amdgcn_global_load_lds((const unsigned*)(_gb + (size_t)K * 128 + loff0), (unsigned*)((char*)(P) + tid * 16 + 8192), 16, 0, 0); } while (0)
; #define LDA(dst, b, h) for (int m = 0; m < 4; ++m) { \
;     dst[m][0] = *reinterpret_cast<const bf16x8*>((char*)SA(b, h) + aoff0 + m * 2048); \
;     dst[m][1] = *reinterpret_cast<const bf16x8*>((char*)SA(b, h) + aoff1 + m * 2048); }
; #define LDB(dst, b, h) for (int n = 0; n < 2; ++n) { \
;     dst[n][0] = *reinterpret_cast<const bf16x8*>((char*)SB(b, h) + boff0 + n * 256); \
;     dst[n][1] = *reinterpret_cast<const bf16x8*>((char*)SB(b, h) + boff1 + n * 256); }
; #define MMA(ai, bj, At, Btf) do { __builtin_amdgcn_s_setprio(1); \
;     for (int m = 0; m < 4; ++m) for (int n = 0; n < 2; ++n) for (int k = 0; k < 2; ++k) \
;       acc[ai][bj][m][n] = __builtin_amdgcn_mfma_f32_16x16x32_bf16(Btf[n][k], At[m][k], acc[ai][bj][m][n], 0, 0, 0); \
;     __builtin_amdgcn_s_setprio(0); } while (0)
; #define WAIT_V(n) asm volatile("s_waitcnt vmcnt(" #n ")" ::: "memory")
; #define WAIT_L(n) asm volatile("s_waitcnt lgkmcnt(" #n ")" ::: "memory")
; #define BAR __builtin_amdgcn_s_barrier()
; #define SCHED __builtin_amdgcn_sched_barrier(0)
; template <int EPI> ...
;     ...
;     WAIT_V(6); BAR; MMA(1, 1, At, B1); BAR;
;     LDB(B0, 1, 0); SCHED; LDA(At, 1, 0); STAGE(SA(0, 1), A, brow + HALF, t + 2);
;     WAIT_L(8); BAR; WAIT_L(0); MMA(0, 0, At, B0); BAR; SCHED;
;     LDB(B1, 1, 1); STAGE(SB(1, 0), Bt, bcol, t + 3);
;     BAR; WAIT_L(0); MMA(0, 1, At, B1); BAR;
	s_waitcnt lgkmcnt(0)
	s_setprio 1
	s_waitcnt lgkmcnt(0)
	v_mfma_f32_16x16x32_bf16 v[60:63], v[160:163], v[176:179], v[60:63]
	v_mfma_f32_16x16x32_bf16 v[56:59], v[164:167], v[176:179], v[56:59]
	v_mfma_f32_16x16x32_bf16 v[52:55], v[160:163], v[184:187], v[52:55]
	v_mfma_f32_16x16x32_bf16 v[48:51], v[164:167], v[184:187], v[48:51]
	v_mfma_f32_16x16x32_bf16 v[44:47], v[160:163], v[192:195], v[44:47]
	v_mfma_f32_16x16x32_bf16 v[40:43], v[164:167], v[192:195], v[40:43]
	v_mfma_f32_16x16x32_bf16 v[36:39], v[160:163], v[200:203], v[36:39]
	v_mfma_f32_16x16x32_bf16 v[32:35], v[164:167], v[200:203], v[32:35]
	v_mfma_f32_16x16x32_bf16 v[60:63], v[168:171], v[180:183], v[60:63]
	v_mfma_f32_16x16x32_bf16 v[56:59], v[172:175], v[180:183], v[56:59]
	v_mfma_f32_16x16x32_bf16 v[52:55], v[168:171], v[188:191], v[52:55]
	v_mfma_f32_16x16x32_bf16 v[48:51], v[172:175], v[188:191], v[48:51]
	v_mfma_f32_16x16x32_bf16 v[44:47], v[168:171], v[196:199], v[44:47]
	v_mfma_f32_16x16x32_bf16 v[40:43], v[172:175], v[196:199], v[40:43]
	v_mfma_f32_16x16x32_bf16 v[36:39], v[168:171], v[204:207], v[36:39]
	v_mfma_f32_16x16x32_bf16 v[32:35], v[172:175], v[204:207], v[32:35]
	s_setprio 0
	s_setprio 1
	v_mfma_f32_16x16x32_bf16 v[28:31], v[208:211], v[176:179], v[28:31]
	v_mfma_f32_16x16x32_bf16 v[24:27], v[212:215], v[176:179], v[24:27]
	v_mfma_f32_16x16x32_bf16 v[20:23], v[208:211], v[184:187], v[20:23]
	v_mfma_f32_16x16x32_bf16 v[16:19], v[212:215], v[184:187], v[16:19]
	v_mfma_f32_16x16x32_bf16 v[12:15], v[208:211], v[192:195], v[12:15]
	v_mfma_f32_16x16x32_bf16 v[8:11], v[212:215], v[192:195], v[8:11]
	v_mfma_f32_16x16x32_bf16 v[4:7], v[208:211], v[200:203], v[4:7]
	v_mfma_f32_16x16x32_bf16 v[0:3], v[212:215], v[200:203], v[0:3]
	v_mfma_f32_16x16x32_bf16 v[28:31], v[216:219], v[180:183], v[28:31]
	v_mfma_f32_16x16x32_bf16 v[24:27], v[220:223], v[180:183], v[24:27]
	v_mfma_f32_16x16x32_bf16 v[20:23], v[216:219], v[188:191], v[20:23]
	v_mfma_f32_16x16x32_bf16 v[16:19], v[220:223], v[188:191], v[16:19]
	v_mfma_f32_16x16x32_bf16 v[12:15], v[216:219], v[196:199], v[12:15]
	v_mfma_f32_16x16x32_bf16 v[8:11], v[220:223], v[196:199], v[8:11]
	v_mfma_f32_16x16x32_bf16 v[4:7], v[216:219], v[204:207], v[4:7]
	v_mfma_f32_16x16x32_bf16 v[0:3], v[220:223], v[204:207], v[0:3]
	s_setprio 0
	s_barrier
	ds_read_b128 v[160:163], v156
	ds_read_b128 v[164:167], v156 offset:256
	ds_read_b128 v[168:171], v157
	ds_read_b128 v[172:175], v157 offset:256
	v_readfirstlane_b32 s70, v141
	v_lshl_add_u64 v[208:209], v[224:225], 0, s[38:39]
	s_mov_b32 m0, s70
	v_readfirstlane_b32 s70, v142
	ds_read_b128 v[176:179], v149 offset:32768
	ds_read_b128 v[180:183], v149 offset:33792
	ds_read_b128 v[184:187], v149 offset:34816
	ds_read_b128 v[188:191], v149 offset:35840
	ds_read_b128 v[192:195], v149 offset:36864
	ds_read_b128 v[196:199], v149 offset:37888
	ds_read_b128 v[200:203], v149 offset:38912
	ds_read_b128 v[204:207], v149 offset:39936
	global_load_lds_dwordx4 v[208:209], off
	v_lshl_add_u64 v[208:209], v[224:225], 0, s[46:47]
	s_mov_b32 m0, s70
	s_nop 0
	global_load_lds_dwordx4 v[208:209], off
	s_waitcnt lgkmcnt(8)
	v_readfirstlane_b32 s70, v139
	v_lshl_add_u64 v[246:247], v[226:227], 0, s[30:31]
	s_mov_b32 m0, s70
	v_readfirstlane_b32 s70, v140
	global_load_lds_dwordx4 v[246:247], off
	v_lshl_add_u64 v[246:247], v[226:227], 0, s[36:37]
	s_mov_b32 m0, s70
	s_nop 0
	global_load_lds_dwordx4 v[246:247], off
	ds_read_b128 v[208:211], v158
	ds_read_b128 v[212:215], v158 offset:256
	ds_read_b128 v[216:219], v159
	ds_read_b128 v[220:223], v159 offset:256
	s_barrier
	s_waitcnt lgkmcnt(0)
	s_setprio 1
	s_waitcnt lgkmcnt(0)
	v_mfma_f32_16x16x32_bf16 v[124:127], v[160:163], v[176:179], v[124:127]
	v_mfma_f32_16x16x32_bf16 v[120:123], v[164:167], v[176:179], v[120:123]
	v_mfma_f32_16x16x32_bf16 v[116:119], v[160:163], v[184:187], v[116:119]
	v_mfma_f32_16x16x32_bf16 v[112:115], v[164:167], v[184:187], v[112:115]
	v_mfma_f32_16x16x32_bf16 v[108:111], v[160:163], v[192:195], v[108:111]
	v_mfma_f32_16x16x32_bf16 v[104:107], v[164:167], v[192:195], v[104:107]
	v_mfma_f32_16x16x32_bf16 v[100:103], v[160:163], v[200:203], v[100:103]
	v_mfma_f32_16x16x32_bf16 v[96:99], v[164:167], v[200:203], v[96:99]
	v_mfma_f32_16x16x32_bf16 v[124:127], v[168:171], v[180:183], v[124:127]
	v_mfma_f32_16x16x32_bf16 v[120:123], v[172:175], v[180:183], v[120:123]
	v_mfma_f32_16x16x32_bf16 v[116:119], v[168:171], v[188:191], v[116:119]
	v_mfma_f32_16x16x32_bf16 v[112:115], v[172:175], v[188:191], v[112:115]
	v_mfma_f32_16x16x32_bf16 v[108:111], v[168:171], v[196:199], v[108:111]
	v_mfma_f32_16x16x32_bf16 v[104:107], v[172:175], v[196:199], v[104:107]
	v_mfma_f32_16x16x32_bf16 v[100:103], v[168:171], v[204:207], v[100:103]
	v_mfma_f32_16x16x32_bf16 v[96:99], v[172:175], v[204:207], v[96:99]
	s_setprio 0
	s_waitcnt lgkmcnt(0)
	s_setprio 1
	s_waitcnt lgkmcnt(0)
	v_mfma_f32_16x16x32_bf16 v[92:95], v[208:211], v[176:179], v[92:95]
	v_mfma_f32_16x16x32_bf16 v[88:91], v[212:215], v[176:179], v[88:91]
	v_mfma_f32_16x16x32_bf16 v[84:87], v[208:211], v[184:187], v[84:87]
	v_mfma_f32_16x16x32_bf16 v[80:83], v[212:215], v[184:187], v[80:83]
	v_mfma_f32_16x16x32_bf16 v[76:79], v[208:211], v[192:195], v[76:79]
	v_mfma_f32_16x16x32_bf16 v[72:75], v[212:215], v[192:195], v[72:75]
	v_mfma_f32_16x16x32_bf16 v[68:71], v[208:211], v[200:203], v[68:71]
	v_mfma_f32_16x16x32_bf16 v[64:67], v[212:215], v[200:203], v[64:67]
	v_mfma_f32_16x16x32_bf16 v[92:95], v[216:219], v[180:183], v[92:95]
	v_mfma_f32_16x16x32_bf16 v[88:91], v[220:223], v[180:183], v[88:91]
	v_mfma_f32_16x16x32_bf16 v[84:87], v[216:219], v[188:191], v[84:87]
	v_mfma_f32_16x16x32_bf16 v[80:83], v[220:223], v[188:191], v[80:83]
	v_mfma_f32_16x16x32_bf16 v[76:79], v[216:219], v[196:199], v[76:79]
	v_mfma_f32_16x16x32_bf16 v[72:75], v[220:223], v[196:199], v[72:75]
	v_mfma_f32_16x16x32_bf16 v[68:71], v[216:219], v[204:207], v[68:71]
	v_mfma_f32_16x16x32_bf16 v[64:67], v[220:223], v[204:207], v[64:67]
	s_setprio 0
	s_barrier
; #define STAGE(P, BASE, br, kt) do { const char* _gb = (const char*)(BASE) + ((size_t)(br) * K + (size_t)(kt) * BK) * 2; \
;     __builtin_amdgcn_global_load_lds((const unsigned*)(_gb + loff0), (unsigned*)((char*)(P) + tid * 16), 16, 0, 0); \
;     __builtin_amdgcn_global_load_lds((const unsigned*)(_gb + (size_t)K * 128 + loff0), (unsigned*)((char*)(P) + tid * 16 + 8192), 16, 0, 0); } while (0)
; #define LDA(dst, b, h) for (int m = 0; m < 4; ++m) { \
;     dst[m][0] = *reinterpret_cast<const bf16x8*>((char*)SA(b, h) + aoff0 + m * 2048); \
;     dst[m][1] = *reinterpret_cast<const bf16x8*>((char*)SA(b, h) + aoff1 + m * 2048); }
; #define LDB(dst, b, h) for (int n = 0; n < 2; ++n) { \
;     dst[n][0] = *reinterpret_cast<const bf16x8*>((char*)SB(b, h) + boff0 + n * 256); \
;     dst[n][1] = *reinterpret_cast<const bf16x8*>((char*)SB(b, h) + boff1 + n * 256); }
; #define MMA(ai, bj, At, Btf) do { __builtin_amdgcn_s_setprio(1); \
;     for (int m = 0; m < 4; ++m) for (int n = 0; n < 2; ++n) for (int k = 0; k < 2; ++k) \
;       acc[ai][bj][m][n] = __builtin_amdgcn_mfma_f32_16x16x32_bf16(Btf[n][k], At[m][k], acc[ai][bj][m][n], 0, 0, 0); \
;     __builtin_amdgcn_s_setprio(0); } while (0)
; #define WAIT_V(n) asm volatile("s_waitcnt vmcnt(" #n ")" ::: "memory")
; #define WAIT_L(n) asm volatile("s_waitcnt lgkmcnt(" #n ")" ::: "memory")
; #define BAR __builtin_amdgcn_s_barrier()
; #define SCHED __builtin_amdgcn_sched_barrier(0)
; template <int EPI> ...
;     ...
;     LDB(B1, 1, 1); STAGE(SB(1, 0), Bt, bcol, t + 3);
;     BAR; WAIT_L(0); MMA(0, 1, At, B1); BAR;
;     LDA(At, 1, 1); STAGE(SA(1, 0), A, brow, t + 3);
;     BAR; WAIT_L(0); MMA(1, 0, At, B0); BAR; SCHED;
;     STAGE(SB(1, 1), Bt, bcol + HALF, t + 3);
;     WAIT_V(6); BAR; MMA(1, 1, At, B1); BAR;
;   }
;   { LDB(B0, 0, 0); LDA(At, 0, 0); STAGE(SA(1, 1), A, brow + HALF, nt - 1);
;     BAR; WAIT_L(0); MMA(0, 0, At, B0); BAR;
	v_readfirstlane_b32 s70, v143
	v_lshl_add_u64 v[228:229], v[226:227], 0, s[48:49]
	s_mov_b32 m0, s70
	v_readfirstlane_b32 s70, v144
	global_load_lds_dwordx4 v[228:229], off
	v_lshl_add_u64 v[228:229], v[226:227], 0, s[50:51]
	s_mov_b32 m0, s70
	s_nop 0
	global_load_lds_dwordx4 v[228:229], off
	v_readfirstlane_b32 s70, v145
	v_lshl_add_u64 v[228:229], v[224:225], 0, s[52:53]
	s_mov_b32 m0, s70
	v_readfirstlane_b32 s70, v146
	ds_read_b128 v[176:179], v149 offset:49152
	ds_read_b128 v[180:183], v149 offset:50176
	ds_read_b128 v[184:187], v149 offset:51200
	ds_read_b128 v[188:191], v149 offset:52224
	ds_read_b128 v[192:195], v149 offset:53248
	ds_read_b128 v[196:199], v149 offset:54272
	ds_read_b128 v[200:203], v149 offset:55296
	ds_read_b128 v[204:207], v149 offset:56320
	global_load_lds_dwordx4 v[228:229], off
	v_lshl_add_u64 v[224:225], v[224:225], 0, s[54:55]
	s_mov_b32 m0, s70
	s_nop 0
	global_load_lds_dwordx4 v[224:225], off
	s_waitcnt vmcnt(4)
	s_barrier
	s_waitcnt lgkmcnt(0)
	s_setprio 1
	s_waitcnt lgkmcnt(0)
	v_mfma_f32_16x16x32_bf16 v[60:63], v[160:163], v[176:179], v[60:63]
	v_mfma_f32_16x16x32_bf16 v[56:59], v[164:167], v[176:179], v[56:59]
	v_mfma_f32_16x16x32_bf16 v[52:55], v[160:163], v[184:187], v[52:55]
	v_mfma_f32_16x16x32_bf16 v[48:51], v[164:167], v[184:187], v[48:51]
	v_mfma_f32_16x16x32_bf16 v[44:47], v[160:163], v[192:195], v[44:47]
	v_mfma_f32_16x16x32_bf16 v[40:43], v[164:167], v[192:195], v[40:43]
	v_mfma_f32_16x16x32_bf16 v[36:39], v[160:163], v[200:203], v[36:39]
	v_mfma_f32_16x16x32_bf16 v[32:35], v[164:167], v[200:203], v[32:35]
	v_mfma_f32_16x16x32_bf16 v[60:63], v[168:171], v[180:183], v[60:63]
	v_mfma_f32_16x16x32_bf16 v[56:59], v[172:175], v[180:183], v[56:59]
	v_mfma_f32_16x16x32_bf16 v[52:55], v[168:171], v[188:191], v[52:55]
	v_mfma_f32_16x16x32_bf16 v[48:51], v[172:175], v[188:191], v[48:51]
	v_mfma_f32_16x16x32_bf16 v[44:47], v[168:171], v[196:199], v[44:47]
	v_mfma_f32_16x16x32_bf16 v[40:43], v[172:175], v[196:199], v[40:43]
	v_mfma_f32_16x16x32_bf16 v[36:39], v[168:171], v[204:207], v[36:39]
	v_mfma_f32_16x16x32_bf16 v[32:35], v[172:175], v[204:207], v[32:35]
	s_setprio 0
	s_setprio 1
	v_mfma_f32_16x16x32_bf16 v[28:31], v[208:211], v[176:179], v[28:31]
	v_mfma_f32_16x16x32_bf16 v[24:27], v[212:215], v[176:179], v[24:27]
	v_mfma_f32_16x16x32_bf16 v[20:23], v[208:211], v[184:187], v[20:23]
	v_mfma_f32_16x16x32_bf16 v[16:19], v[212:215], v[184:187], v[16:19]
	v_mfma_f32_16x16x32_bf16 v[12:15], v[208:211], v[192:195], v[12:15]
	v_mfma_f32_16x16x32_bf16 v[8:11], v[212:215], v[192:195], v[8:11]
	v_mfma_f32_16x16x32_bf16 v[4:7], v[208:211], v[200:203], v[4:7]
	v_mfma_f32_16x16x32_bf16 v[0:3], v[212:215], v[200:203], v[0:3]
	v_mfma_f32_16x16x32_bf16 v[28:31], v[216:219], v[180:183], v[28:31]
	v_mfma_f32_16x16x32_bf16 v[24:27], v[220:223], v[180:183], v[24:27]
	v_mfma_f32_16x16x32_bf16 v[20:23], v[216:219], v[188:191], v[20:23]
	v_mfma_f32_16x16x32_bf16 v[16:19], v[220:223], v[188:191], v[16:19]
	v_mfma_f32_16x16x32_bf16 v[12:15], v[216:219], v[196:199], v[12:15]
	v_mfma_f32_16x16x32_bf16 v[8:11], v[220:223], v[196:199], v[8:11]
	v_mfma_f32_16x16x32_bf16 v[4:7], v[216:219], v[204:207], v[4:7]
	v_mfma_f32_16x16x32_bf16 v[0:3], v[220:223], v[204:207], v[0:3]
	s_setprio 0
	s_add_i32 s61, s61, 2
	s_add_u32 s66, s66, 0x100
	s_addc_u32 s67, s67, 0
	s_add_u32 s68, s68, 0x100
	s_addc_u32 s69, s69, 0
	s_cmp_lt_u32 s61, 28
	s_barrier
	s_cbranch_scc1 .LBB0_411
	v_readfirstlane_b32 s70, v147
	v_lshl_add_u64 v[246:247], v[226:227], 0, s[56:57]
	s_mov_b32 m0, s70
	v_readfirstlane_b32 s70, v148
	global_load_lds_dwordx4 v[246:247], off
	v_lshl_add_u64 v[246:247], v[226:227], 0, s[58:59]
	s_mov_b32 m0, s70
	s_nop 0
	global_load_lds_dwordx4 v[246:247], off
	s_add_u32 s64, s74, s64
	s_addc_u32 s65, s75, s65
	v_readfirstlane_b32 s61, v150
	v_lshl_add_u64 v[208:209], s[64:65], 0, v[128:129]
	s_mov_b32 m0, s61
	v_readfirstlane_b32 s61, v151
	ds_read_b128 v[160:163], v152
	ds_read_b128 v[164:167], v152 offset:256
	ds_read_b128 v[168:171], v153
	ds_read_b128 v[172:175], v153 offset:256
	ds_read_b128 v[176:179], v149
	ds_read_b128 v[180:183], v149 offset:1024
	ds_read_b128 v[184:187], v149 offset:2048
	ds_read_b128 v[188:191], v149 offset:3072
	ds_read_b128 v[192:195], v149 offset:4096
	ds_read_b128 v[196:199], v149 offset:5120
	ds_read_b128 v[200:203], v149 offset:6144
	ds_read_b128 v[204:207], v149 offset:7168
	global_load_lds_dwordx4 v[208:209], off
	v_lshl_add_u64 v[208:209], v[208:209], 0, s[8:9]
	s_mov_b32 m0, s61
	s_nop 0
	global_load_lds_dwordx4 v[208:209], off
	s_barrier
	s_waitcnt lgkmcnt(0)
	s_setprio 1
	s_waitcnt lgkmcnt(0)
	v_mfma_f32_16x16x32_bf16 v[124:127], v[160:163], v[176:179], v[124:127]
	v_mfma_f32_16x16x32_bf16 v[116:119], v[160:163], v[184:187], v[116:119]
	v_mfma_f32_16x16x32_bf16 v[108:111], v[160:163], v[192:195], v[108:111]
	v_mfma_f32_16x16x32_bf16 v[100:103], v[160:163], v[200:203], v[100:103]
	v_mfma_f32_16x16x32_bf16 v[96:99], v[164:167], v[200:203], v[96:99]
	v_mfma_f32_16x16x32_bf16 v[124:127], v[168:171], v[180:183], v[124:127]
	v_mfma_f32_16x16x32_bf16 v[120:123], v[164:167], v[176:179], v[120:123]
	v_mfma_f32_16x16x32_bf16 v[116:119], v[168:171], v[188:191], v[116:119]
	v_mfma_f32_16x16x32_bf16 v[112:115], v[164:167], v[184:187], v[112:115]
	v_mfma_f32_16x16x32_bf16 v[108:111], v[168:171], v[196:199], v[108:111]
	v_mfma_f32_16x16x32_bf16 v[104:107], v[164:167], v[192:195], v[104:107]
	v_mfma_f32_16x16x32_bf16 v[100:103], v[168:171], v[204:207], v[100:103]
	v_mfma_f32_16x16x32_bf16 v[96:99], v[172:175], v[204:207], v[96:99]
	v_mfma_f32_16x16x32_bf16 v[208:211], v[172:175], v[180:183], v[120:123]
	v_mfma_f32_16x16x32_bf16 v[212:215], v[172:175], v[188:191], v[112:115]
	v_mfma_f32_16x16x32_bf16 v[216:219], v[172:175], v[196:199], v[104:107]
	s_setprio 0
	s_barrier
; #define LDA(dst, b, h) for (int m = 0; m < 4; ++m) { \
;     dst[m][0] = *reinterpret_cast<const bf16x8*>((char*)SA(b, h) + aoff0 + m * 2048); \
;     dst[m][1] = *reinterpret_cast<const bf16x8*>((char*)SA(b, h) + aoff1 + m * 2048); }
; #define LDB(dst, b, h) for (int n = 0; n < 2; ++n) { \
;     dst[n][0] = *reinterpret_cast<const bf16x8*>((char*)SB(b, h) + boff0 + n * 256); \
;     dst[n][1] = *reinterpret_cast<const bf16x8*>((char*)SB(b, h) + boff1 + n * 256); }
; #define MMA(ai, bj, At, Btf) do { __builtin_amdgcn_s_setprio(1); \
;     for (int m = 0; m < 4; ++m) for (int n = 0; n < 2; ++n) for (int k = 0; k < 2; ++k) \
;       acc[ai][bj][m][n] = __builtin_amdgcn_mfma_f32_16x16x32_bf16(Btf[n][k], At[m][k], acc[ai][bj][m][n], 0, 0, 0); \
;     __builtin_amdgcn_s_setprio(0); } while (0)
; #define WAIT_V(n) asm volatile("s_waitcnt vmcnt(" #n ")" ::: "memory")
; #define WAIT_L(n) asm volatile("s_waitcnt lgkmcnt(" #n ")" ::: "memory")
; #define BAR __builtin_amdgcn_s_barrier()
; template <int EPI> ...
;     ...
;     BAR; WAIT_L(0); MMA(0, 0, At, B0); BAR;
;     LDB(B1, 0, 1); BAR; WAIT_L(0); MMA(0, 1, At, B1); BAR;
;     LDA(At, 0, 1); WAIT_V(4); BAR; WAIT_L(0); MMA(1, 0, At, B0); MMA(1, 1, At, B1); BAR; }
;   { LDB(B0, 1, 0); LDA(At, 1, 0); WAIT_V(2); BAR; WAIT_L(0); MMA(0, 0, At, B0); BAR;
	s_nop 0
	ds_read_b128 v[104:107], v154
	ds_read_b128 v[112:115], v154 offset:256
	ds_read_b128 v[120:123], v155
	ds_read_b128 v[220:223], v155 offset:256
	s_barrier
	s_waitcnt lgkmcnt(0)
	s_setprio 1
	s_waitcnt lgkmcnt(0)
	v_mfma_f32_16x16x32_bf16 v[92:95], v[104:107], v[176:179], v[92:95]
	v_mfma_f32_16x16x32_bf16 v[88:91], v[112:115], v[176:179], v[88:91]
	v_mfma_f32_16x16x32_bf16 v[76:79], v[104:107], v[192:195], v[76:79]
	v_mfma_f32_16x16x32_bf16 v[72:75], v[112:115], v[192:195], v[72:75]
	v_mfma_f32_16x16x32_bf16 v[92:95], v[120:123], v[180:183], v[92:95]
	v_mfma_f32_16x16x32_bf16 v[88:91], v[220:223], v[180:183], v[88:91]
	v_mfma_f32_16x16x32_bf16 v[84:87], v[104:107], v[184:187], v[84:87]
	v_mfma_f32_16x16x32_bf16 v[80:83], v[112:115], v[184:187], v[80:83]
	v_mfma_f32_16x16x32_bf16 v[76:79], v[120:123], v[196:199], v[76:79]
	v_mfma_f32_16x16x32_bf16 v[72:75], v[220:223], v[196:199], v[72:75]
	v_mfma_f32_16x16x32_bf16 v[68:71], v[104:107], v[200:203], v[68:71]
	v_mfma_f32_16x16x32_bf16 v[64:67], v[112:115], v[200:203], v[64:67]
	v_mfma_f32_16x16x32_bf16 v[176:179], v[120:123], v[188:191], v[84:87]
	v_mfma_f32_16x16x32_bf16 v[180:183], v[220:223], v[188:191], v[80:83]
	v_mfma_f32_16x16x32_bf16 v[184:187], v[120:123], v[204:207], v[68:71]
	v_mfma_f32_16x16x32_bf16 v[188:191], v[220:223], v[204:207], v[64:67]
	s_setprio 0
	s_barrier
	s_nop 1
	ds_read_b128 v[64:67], v149 offset:16384
	ds_read_b128 v[68:71], v149 offset:17408
	ds_read_b128 v[80:83], v149 offset:18432
	ds_read_b128 v[84:87], v149 offset:19456
	ds_read_b128 v[192:195], v149 offset:20480
	ds_read_b128 v[196:199], v149 offset:21504
	ds_read_b128 v[200:203], v149 offset:22528
	ds_read_b128 v[204:207], v149 offset:23552
	s_waitcnt vmcnt(4)
	s_barrier
	s_waitcnt lgkmcnt(0)
	s_setprio 1
	s_waitcnt lgkmcnt(0)
	v_mfma_f32_16x16x32_bf16 v[60:63], v[160:163], v[64:67], v[60:63]
	v_mfma_f32_16x16x32_bf16 v[56:59], v[164:167], v[64:67], v[56:59]
	v_mfma_f32_16x16x32_bf16 v[44:47], v[160:163], v[192:195], v[44:47]
	v_mfma_f32_16x16x32_bf16 v[36:39], v[160:163], v[200:203], v[36:39]
	v_mfma_f32_16x16x32_bf16 v[60:63], v[168:171], v[68:71], v[60:63]
	v_mfma_f32_16x16x32_bf16 v[56:59], v[172:175], v[68:71], v[56:59]
	v_mfma_f32_16x16x32_bf16 v[52:55], v[160:163], v[80:83], v[52:55]
	v_mfma_f32_16x16x32_bf16 v[48:51], v[164:167], v[80:83], v[48:51]
	v_mfma_f32_16x16x32_bf16 v[44:47], v[168:171], v[196:199], v[44:47]
	v_mfma_f32_16x16x32_bf16 v[40:43], v[164:167], v[192:195], v[40:43]
	v_mfma_f32_16x16x32_bf16 v[36:39], v[168:171], v[204:207], v[36:39]
	v_mfma_f32_16x16x32_bf16 v[32:35], v[164:167], v[200:203], v[32:35]
	v_mfma_f32_16x16x32_bf16 v[224:227], v[168:171], v[84:87], v[52:55]
	v_mfma_f32_16x16x32_bf16 v[228:231], v[172:175], v[84:87], v[48:51]
	v_mfma_f32_16x16x32_bf16 v[232:235], v[172:175], v[196:199], v[40:43]
	v_mfma_f32_16x16x32_bf16 v[160:163], v[172:175], v[204:207], v[32:35]
	s_setprio 0
	s_setprio 1
	v_mfma_f32_16x16x32_bf16 v[28:31], v[104:107], v[64:67], v[28:31]
	v_mfma_f32_16x16x32_bf16 v[20:23], v[104:107], v[80:83], v[20:23]
	v_mfma_f32_16x16x32_bf16 v[12:15], v[104:107], v[192:195], v[12:15]
	v_mfma_f32_16x16x32_bf16 v[4:7], v[104:107], v[200:203], v[4:7]
	v_mfma_f32_16x16x32_bf16 v[28:31], v[120:123], v[68:71], v[28:31]
	v_mfma_f32_16x16x32_bf16 v[24:27], v[112:115], v[64:67], v[24:27]
	v_mfma_f32_16x16x32_bf16 v[20:23], v[120:123], v[84:87], v[20:23]
	v_mfma_f32_16x16x32_bf16 v[16:19], v[112:115], v[80:83], v[16:19]
	v_mfma_f32_16x16x32_bf16 v[12:15], v[120:123], v[196:199], v[12:15]
	v_mfma_f32_16x16x32_bf16 v[8:11], v[112:115], v[192:195], v[8:11]
	v_mfma_f32_16x16x32_bf16 v[4:7], v[120:123], v[204:207], v[4:7]
	v_mfma_f32_16x16x32_bf16 v[0:3], v[112:115], v[200:203], v[0:3]
	v_mfma_f32_16x16x32_bf16 v[164:167], v[220:223], v[68:71], v[24:27]
	v_mfma_f32_16x16x32_bf16 v[168:171], v[220:223], v[84:87], v[16:19]
	v_mfma_f32_16x16x32_bf16 v[172:175], v[220:223], v[196:199], v[8:11]
	v_mfma_f32_16x16x32_bf16 v[192:195], v[220:223], v[204:207], v[0:3]
	s_setprio 0
	s_barrier
	s_nop 1
	ds_read_b128 v[0:3], v156
	ds_read_b128 v[8:11], v156 offset:256
	ds_read_b128 v[16:19], v157
	ds_read_b128 v[24:27], v157 offset:256
	ds_read_b128 v[32:35], v149 offset:32768
	ds_read_b128 v[40:43], v149 offset:33792
	ds_read_b128 v[48:51], v149 offset:34816
	ds_read_b128 v[52:55], v149 offset:35840
	ds_read_b128 v[68:71], v149 offset:36864
	ds_read_b128 v[196:199], v149 offset:37888
	ds_read_b128 v[200:203], v149 offset:38912
	ds_read_b128 v[204:207], v149 offset:39936
	s_waitcnt vmcnt(2)
	s_barrier
; #define LDA(dst, b, h) for (int m = 0; m < 4; ++m) { \
;     dst[m][0] = *reinterpret_cast<const bf16x8*>((char*)SA(b, h) + aoff0 + m * 2048); \
;     dst[m][1] = *reinterpret_cast<const bf16x8*>((char*)SA(b, h) + aoff1 + m * 2048); }
; #define LDB(dst, b, h) for (int n = 0; n < 2; ++n) { \
;     dst[n][0] = *reinterpret_cast<const bf16x8*>((char*)SB(b, h) + boff0 + n * 256); \
;     dst[n][1] = *reinterpret_cast<const bf16x8*>((char*)SB(b, h) + boff1 + n * 256); }
; #define MMA(ai, bj, At, Btf) do { __builtin_amdgcn_s_setprio(1); \
;     for (int m = 0; m < 4; ++m) for (int n = 0; n < 2; ++n) for (int k = 0; k < 2; ++k) \
;       acc[ai][bj][m][n] = __builtin_amdgcn_mfma_f32_16x16x32_bf16(Btf[n][k], At[m][k], acc[ai][bj][m][n], 0, 0, 0); \
;     __builtin_amdgcn_s_setprio(0); } while (0)
; #define WAIT_V(n) asm volatile("s_waitcnt vmcnt(" #n ")" ::: "memory")
; #define WAIT_L(n) asm volatile("s_waitcnt lgkmcnt(" #n ")" ::: "memory")
; #define BAR __builtin_amdgcn_s_barrier()
; template <int EPI> ...
;     ...
;   { LDB(B0, 1, 0); LDA(At, 1, 0); WAIT_V(2); BAR; WAIT_L(0); MMA(0, 0, At, B0); BAR;
;     LDB(B1, 1, 1); WAIT_V(0); BAR; WAIT_L(0); MMA(0, 1, At, B1); BAR;
;     LDA(At, 1, 1); BAR; WAIT_L(0); MMA(1, 0, At, B0); MMA(1, 1, At, B1); BAR; }
;   if (wr == 0) BAR;
	s_waitcnt lgkmcnt(0)
	s_setprio 1
	s_waitcnt lgkmcnt(0)
	v_mfma_f32_16x16x32_bf16 v[64:67], v[0:3], v[32:35], v[124:127]
	v_mfma_f32_16x16x32_bf16 v[120:123], v[16:19], v[40:43], v[64:67]
	v_mfma_f32_16x16x32_bf16 v[64:67], v[8:11], v[32:35], v[208:211]
	v_mfma_f32_16x16x32_bf16 v[124:127], v[24:27], v[40:43], v[64:67]
	v_mfma_f32_16x16x32_bf16 v[64:67], v[0:3], v[48:51], v[116:119]
	v_mfma_f32_16x16x32_bf16 v[112:115], v[16:19], v[52:55], v[64:67]
	v_mfma_f32_16x16x32_bf16 v[64:67], v[8:11], v[48:51], v[212:215]
	v_mfma_f32_16x16x32_bf16 v[116:119], v[24:27], v[52:55], v[64:67]
	v_mfma_f32_16x16x32_bf16 v[64:67], v[0:3], v[68:71], v[108:111]
	v_mfma_f32_16x16x32_bf16 v[104:107], v[16:19], v[196:199], v[64:67]
	v_mfma_f32_16x16x32_bf16 v[64:67], v[8:11], v[68:71], v[216:219]
	v_mfma_f32_16x16x32_bf16 v[108:111], v[24:27], v[196:199], v[64:67]
	v_mfma_f32_16x16x32_bf16 v[64:67], v[0:3], v[200:203], v[100:103]
	v_mfma_f32_16x16x32_bf16 v[80:83], v[16:19], v[204:207], v[64:67]
	v_mfma_f32_16x16x32_bf16 v[64:67], v[8:11], v[200:203], v[96:99]
	v_mfma_f32_16x16x32_bf16 v[84:87], v[24:27], v[204:207], v[64:67]
	s_setprio 0
	s_barrier
	ds_read_b128 v[208:211], v158
	ds_read_b128 v[212:215], v158 offset:256
	ds_read_b128 v[216:219], v159
	ds_read_b128 v[220:223], v159 offset:256
	s_waitcnt vmcnt(0)
	s_barrier
	s_waitcnt lgkmcnt(0)
	s_setprio 1
	s_waitcnt lgkmcnt(0)
	v_mfma_f32_16x16x32_bf16 v[64:67], v[208:211], v[32:35], v[92:95]
	v_mfma_f32_16x16x32_bf16 v[32:35], v[212:215], v[32:35], v[88:91]
	v_mfma_f32_16x16x32_bf16 v[100:103], v[220:223], v[40:43], v[32:35]
	v_mfma_f32_16x16x32_bf16 v[32:35], v[208:211], v[48:51], v[176:179]
	v_mfma_f32_16x16x32_bf16 v[88:91], v[216:219], v[52:55], v[32:35]
	v_mfma_f32_16x16x32_bf16 v[32:35], v[212:215], v[48:51], v[180:183]
	v_mfma_f32_16x16x32_bf16 v[92:95], v[220:223], v[52:55], v[32:35]
	v_mfma_f32_16x16x32_bf16 v[32:35], v[208:211], v[68:71], v[76:79]
	v_mfma_f32_16x16x32_bf16 v[96:99], v[216:219], v[40:43], v[64:67]
	v_mfma_f32_16x16x32_bf16 v[64:67], v[216:219], v[196:199], v[32:35]
	v_mfma_f32_16x16x32_bf16 v[32:35], v[212:215], v[68:71], v[72:75]
	v_mfma_f32_16x16x32_bf16 v[68:71], v[220:223], v[196:199], v[32:35]
	v_mfma_f32_16x16x32_bf16 v[32:35], v[208:211], v[200:203], v[184:187]
	v_mfma_f32_16x16x32_bf16 v[48:51], v[216:219], v[204:207], v[32:35]
	v_mfma_f32_16x16x32_bf16 v[32:35], v[212:215], v[200:203], v[188:191]
	v_mfma_f32_16x16x32_bf16 v[52:55], v[220:223], v[204:207], v[32:35]
	s_setprio 0
	s_barrier
	ds_read_b128 v[176:179], v149 offset:49152
	ds_read_b128 v[180:183], v149 offset:50176
	ds_read_b128 v[184:187], v149 offset:51200
	ds_read_b128 v[188:191], v149 offset:52224
	ds_read_b128 v[196:199], v149 offset:53248
	ds_read_b128 v[200:203], v149 offset:54272
	ds_read_b128 v[204:207], v149 offset:55296
	ds_read_b128 v[236:239], v149 offset:56320
	s_barrier
	s_waitcnt lgkmcnt(0)
	s_setprio 1
	s_waitcnt lgkmcnt(0)
	v_mfma_f32_16x16x32_bf16 v[32:35], v[0:3], v[176:179], v[60:63]
	v_mfma_f32_16x16x32_bf16 v[72:75], v[16:19], v[180:183], v[32:35]
	v_mfma_f32_16x16x32_bf16 v[32:35], v[8:11], v[176:179], v[56:59]
	v_mfma_f32_16x16x32_bf16 v[76:79], v[24:27], v[180:183], v[32:35]
	v_mfma_f32_16x16x32_bf16 v[32:35], v[0:3], v[184:187], v[224:227]
	v_mfma_f32_16x16x32_bf16 v[56:59], v[16:19], v[188:191], v[32:35]
	v_mfma_f32_16x16x32_bf16 v[32:35], v[8:11], v[184:187], v[228:231]
	v_mfma_f32_16x16x32_bf16 v[60:63], v[24:27], v[188:191], v[32:35]
	v_mfma_f32_16x16x32_bf16 v[32:35], v[0:3], v[196:199], v[44:47]
	v_mfma_f32_16x16x32_bf16 v[40:43], v[16:19], v[200:203], v[32:35]
	v_mfma_f32_16x16x32_bf16 v[32:35], v[8:11], v[196:199], v[232:235]
	v_mfma_f32_16x16x32_bf16 v[0:3], v[0:3], v[204:207], v[36:39]
	v_mfma_f32_16x16x32_bf16 v[44:47], v[24:27], v[200:203], v[32:35]
	v_mfma_f32_16x16x32_bf16 v[32:35], v[16:19], v[236:239], v[0:3]
	v_mfma_f32_16x16x32_bf16 v[0:3], v[8:11], v[204:207], v[160:163]
	v_mfma_f32_16x16x32_bf16 v[36:39], v[24:27], v[236:239], v[0:3]
	s_setprio 0
	s_setprio 1
	v_mfma_f32_16x16x32_bf16 v[0:3], v[208:211], v[176:179], v[28:31]
	v_mfma_f32_16x16x32_bf16 v[24:27], v[216:219], v[180:183], v[0:3]
	v_mfma_f32_16x16x32_bf16 v[0:3], v[212:215], v[176:179], v[164:167]
	v_mfma_f32_16x16x32_bf16 v[28:31], v[220:223], v[180:183], v[0:3]
	v_mfma_f32_16x16x32_bf16 v[0:3], v[208:211], v[184:187], v[20:23]
	v_mfma_f32_16x16x32_bf16 v[16:19], v[216:219], v[188:191], v[0:3]
	v_mfma_f32_16x16x32_bf16 v[0:3], v[212:215], v[184:187], v[168:171]
	v_mfma_f32_16x16x32_bf16 v[20:23], v[220:223], v[188:191], v[0:3]
	v_mfma_f32_16x16x32_bf16 v[0:3], v[208:211], v[196:199], v[12:15]
	v_mfma_f32_16x16x32_bf16 v[8:11], v[216:219], v[200:203], v[0:3]
	v_mfma_f32_16x16x32_bf16 v[0:3], v[212:215], v[196:199], v[172:175]
	v_mfma_f32_16x16x32_bf16 v[12:15], v[220:223], v[200:203], v[0:3]
	v_mfma_f32_16x16x32_bf16 v[0:3], v[208:211], v[204:207], v[4:7]
	v_mfma_f32_16x16x32_bf16 v[4:7], v[212:215], v[204:207], v[192:195]
	v_mfma_f32_16x16x32_bf16 v[0:3], v[216:219], v[236:239], v[0:3]
	v_mfma_f32_16x16x32_bf16 v[4:7], v[220:223], v[236:239], v[4:7]
	s_setprio 0
	s_barrier
	s_and_saveexec_b64 s[64:65], s[2:3]
	s_cbranch_execz .LBB0_405
	s_barrier
	s_branch .LBB0_405

; #define STAGE(P, BASE, br, kt) do { const char* _gb = (const char*)(BASE) + ((size_t)(br) * K + (size_t)(kt) * BK) * 2; \
;     __builtin_amdgcn_global_load_lds((const unsigned*)(_gb + loff0), (unsigned*)((char*)(P) + tid * 16), 16, 0, 0); \
;     __builtin_amdgcn_global_load_lds((const unsigned*)(_gb + (size_t)K * 128 + loff0), (unsigned*)((char*)(P) + tid * 16 + 8192), 16, 0, 0); } while (0)
; #define LDA(dst, b, h) for (int m = 0; m < 4; ++m) { \
;     dst[m][0] = *reinterpret_cast<const bf16x8*>((char*)SA(b, h) + aoff0 + m * 2048); \
;     dst[m][1] = *reinterpret_cast<const bf16x8*>((char*)SA(b, h) + aoff1 + m * 2048); }
; #define LDB(dst, b, h) for (int n = 0; n < 2; ++n) { \
;     dst[n][0] = *reinterpret_cast<const bf16x8*>((char*)SB(b, h) + boff0 + n * 256); \
;     dst[n][1] = *reinterpret_cast<const bf16x8*>((char*)SB(b, h) + boff1 + n * 256); }
; #define MMA(ai, bj, At, Btf) do { __builtin_amdgcn_s_setprio(1); \
;     for (int m = 0; m < 4; ++m) for (int n = 0; n < 2; ++n) for (int k = 0; k < 2; ++k) \
;       acc[ai][bj][m][n] = __builtin_amdgcn_mfma_f32_16x16x32_bf16(Btf[n][k], At[m][k], acc[ai][bj][m][n], 0, 0, 0); \
;     __builtin_amdgcn_s_setprio(0); } while (0)
; #define WAIT_V(n) asm volatile("s_waitcnt vmcnt(" #n ")" ::: "memory")
; #define WAIT_L(n) asm volatile("s_waitcnt lgkmcnt(" #n ")" ::: "memory")
; #define BAR __builtin_amdgcn_s_barrier()
; #define SCHED __builtin_amdgcn_sched_barrier(0)
; template <int EPI> ...
;     ...
;   STAGE(SB(1, 0), Bt, bcol, 1); STAGE(SA(1, 0), A, brow, 1); STAGE(SB(1, 1), Bt, bcol + HALF, 1);
;   WAIT_V(6); BAR;
;   for (int t = 0; t < nt - 2; t += 2) {
;     LDB(B0, 0, 0); SCHED; LDA(At, 0, 0); STAGE(SA(1, 1), A, brow + HALF, t + 1);
;     WAIT_L(8); BAR; WAIT_L(0); MMA(0, 0, At, B0); BAR; SCHED;
;     LDB(B1, 0, 1); STAGE(SB(0, 0), Bt, bcol, t + 2);
;     BAR; WAIT_L(0); MMA(0, 1, At, B1); BAR;
;     LDA(At, 0, 1); STAGE(SA(0, 0), A, brow, t + 2);
;     BAR; WAIT_L(0); MMA(1, 0, At, B0); BAR; SCHED;
;     STAGE(SB(0, 1), Bt, bcol + HALF, t + 2);
;     WAIT_V(6); BAR; MMA(1, 1, At, B1); BAR;
.LBB0_1017:
	s_or_b64 exec, exec, s[68:69]
	v_readfirstlane_b32 s59, v143
	v_lshl_add_u64 v[6:7], v[0:1], 0, s[10:11]
	s_mov_b32 m0, s59
	v_readfirstlane_b32 s59, v144
	s_waitcnt vmcnt(2)
	s_barrier
	global_load_lds_dwordx4 v[6:7], off
	v_lshl_add_u64 v[0:1], v[0:1], 0, s[12:13]
	s_mov_b32 m0, s59
	v_readfirstlane_b32 s59, v145
	global_load_lds_dwordx4 v[0:1], off
	v_lshl_add_u64 v[0:1], v[2:3], 0, s[10:11]
	s_mov_b32 m0, s59
	v_readfirstlane_b32 s59, v146
	global_load_lds_dwordx4 v[0:1], off
	v_lshl_add_u64 v[0:1], v[2:3], 0, s[12:13]
	s_mov_b32 m0, s59
	v_readfirstlane_b32 s59, v147
	global_load_lds_dwordx4 v[0:1], off
	v_lshl_add_u64 v[0:1], v[4:5], 0, s[10:11]
	s_mov_b32 m0, s59
	v_readfirstlane_b32 s59, v148
	global_load_lds_dwordx4 v[0:1], off
	v_lshl_add_u64 v[0:1], v[4:5], 0, s[12:13]
	s_mov_b32 m0, s59
	s_add_u32 s64, s6, s64
	global_load_lds_dwordx4 v[0:1], off
	s_addc_u32 s65, s7, s65
	s_add_u32 s66, s6, s66
	v_mov_b32_e32 v0, 0
	s_addc_u32 s67, s7, s67
	s_mov_b32 s59, -2
	v_mov_b32_e32 v1, v0
	v_mov_b32_e32 v2, v0
	v_mov_b32_e32 v3, v0
	v_mov_b32_e32 v4, v0
	v_mov_b32_e32 v5, v0
	v_mov_b32_e32 v6, v0
	v_mov_b32_e32 v7, v0
	s_waitcnt vmcnt(6)
	s_sub_u32 s98, s64, 0x100
	s_subb_u32 s99, s65, 0
	v_lshl_add_u64 v[226:227], s[98:99], 0, v[132:133]
	s_barrier
.LBB0_1018:
	ds_read_b128 v[160:163], v152
	ds_read_b128 v[164:167], v152 offset:256
	ds_read_b128 v[168:171], v153
	ds_read_b128 v[172:175], v153 offset:256
	v_lshl_add_u64 v[224:225], s[66:67], 0, v[132:133]
	v_readfirstlane_b32 s68, v150
	v_lshl_add_u64 v[208:209], v[224:225], 0, s[16:17]
	s_mov_b32 m0, s68
	v_readfirstlane_b32 s68, v151
	ds_read_b128 v[176:179], v149
	ds_read_b128 v[180:183], v149 offset:1024
	ds_read_b128 v[184:187], v149 offset:2048
	ds_read_b128 v[188:191], v149 offset:3072
	ds_read_b128 v[192:195], v149 offset:4096
	ds_read_b128 v[196:199], v149 offset:5120
	ds_read_b128 v[200:203], v149 offset:6144
	ds_read_b128 v[204:207], v149 offset:7168
	global_load_lds_dwordx4 v[208:209], off
	v_lshl_add_u64 v[208:209], v[224:225], 0, s[18:19]
	s_mov_b32 m0, s68
	s_nop 0
	global_load_lds_dwordx4 v[208:209], off
	s_waitcnt lgkmcnt(8)
	v_readfirstlane_b32 s68, v147
	v_lshl_add_u64 v[246:247], v[226:227], 0, s[54:55]
	s_mov_b32 m0, s68
	v_readfirstlane_b32 s68, v148
	global_load_lds_dwordx4 v[246:247], off
	v_lshl_add_u64 v[246:247], v[226:227], 0, s[56:57]
	s_mov_b32 m0, s68
	s_nop 0
	global_load_lds_dwordx4 v[246:247], off
	ds_read_b128 v[208:211], v154
	ds_read_b128 v[212:215], v154 offset:256
	ds_read_b128 v[216:219], v155
	ds_read_b128 v[220:223], v155 offset:256
	s_barrier
	s_waitcnt lgkmcnt(0)
	s_setprio 1
	s_waitcnt lgkmcnt(0)
	v_mfma_f32_16x16x32_bf16 v[124:127], v[160:163], v[176:179], v[124:127]
	v_mfma_f32_16x16x32_bf16 v[120:123], v[164:167], v[176:179], v[120:123]
	v_mfma_f32_16x16x32_bf16 v[116:119], v[160:163], v[184:187], v[116:119]
	v_mfma_f32_16x16x32_bf16 v[112:115], v[164:167], v[184:187], v[112:115]
	v_mfma_f32_16x16x32_bf16 v[108:111], v[160:163], v[192:195], v[108:111]
	v_mfma_f32_16x16x32_bf16 v[104:107], v[164:167], v[192:195], v[104:107]
	v_mfma_f32_16x16x32_bf16 v[100:103], v[160:163], v[200:203], v[100:103]
	v_mfma_f32_16x16x32_bf16 v[96:99], v[164:167], v[200:203], v[96:99]
	v_mfma_f32_16x16x32_bf16 v[124:127], v[168:171], v[180:183], v[124:127]
	v_mfma_f32_16x16x32_bf16 v[120:123], v[172:175], v[180:183], v[120:123]
	v_mfma_f32_16x16x32_bf16 v[116:119], v[168:171], v[188:191], v[116:119]
	v_mfma_f32_16x16x32_bf16 v[112:115], v[172:175], v[188:191], v[112:115]
	v_mfma_f32_16x16x32_bf16 v[108:111], v[168:171], v[196:199], v[108:111]
	v_mfma_f32_16x16x32_bf16 v[104:107], v[172:175], v[196:199], v[104:107]
	v_mfma_f32_16x16x32_bf16 v[100:103], v[168:171], v[204:207], v[100:103]
	v_mfma_f32_16x16x32_bf16 v[96:99], v[172:175], v[204:207], v[96:99]
	s_setprio 0
	s_waitcnt lgkmcnt(0)
	s_setprio 1
	s_waitcnt lgkmcnt(0)
	v_mfma_f32_16x16x32_bf16 v[92:95], v[208:211], v[176:179], v[92:95]
	v_mfma_f32_16x16x32_bf16 v[88:91], v[212:215], v[176:179], v[88:91]
	v_mfma_f32_16x16x32_bf16 v[84:87], v[208:211], v[184:187], v[84:87]
	v_mfma_f32_16x16x32_bf16 v[80:83], v[212:215], v[184:187], v[80:83]
	v_mfma_f32_16x16x32_bf16 v[76:79], v[208:211], v[192:195], v[76:79]
	v_mfma_f32_16x16x32_bf16 v[72:75], v[212:215], v[192:195], v[72:75]
	v_mfma_f32_16x16x32_bf16 v[68:71], v[208:211], v[200:203], v[68:71]
	v_mfma_f32_16x16x32_bf16 v[64:67], v[212:215], v[200:203], v[64:67]
	v_mfma_f32_16x16x32_bf16 v[92:95], v[216:219], v[180:183], v[92:95]
	v_mfma_f32_16x16x32_bf16 v[88:91], v[220:223], v[180:183], v[88:91]
	v_mfma_f32_16x16x32_bf16 v[84:87], v[216:219], v[188:191], v[84:87]
	v_mfma_f32_16x16x32_bf16 v[80:83], v[220:223], v[188:191], v[80:83]
	v_mfma_f32_16x16x32_bf16 v[76:79], v[216:219], v[196:199], v[76:79]
	v_mfma_f32_16x16x32_bf16 v[72:75], v[220:223], v[196:199], v[72:75]
	v_mfma_f32_16x16x32_bf16 v[68:71], v[216:219], v[204:207], v[68:71]
	v_mfma_f32_16x16x32_bf16 v[64:67], v[220:223], v[204:207], v[64:67]
	s_setprio 0
	s_barrier
	v_lshl_add_u64 v[226:227], s[64:65], 0, v[132:133]
	v_readfirstlane_b32 s68, v135
	v_lshl_add_u64 v[228:229], v[226:227], 0, s[20:21]
	s_mov_b32 m0, s68
	v_readfirstlane_b32 s68, v136
	global_load_lds_dwordx4 v[228:229], off
	v_lshl_add_u64 v[228:229], v[226:227], 0, s[22:23]
	s_mov_b32 m0, s68
	s_nop 0
	global_load_lds_dwordx4 v[228:229], off
	v_readfirstlane_b32 s68, v137
	v_lshl_add_u64 v[228:229], v[224:225], 0, s[24:25]
	s_mov_b32 m0, s68
	v_readfirstlane_b32 s68, v138
	ds_read_b128 v[176:179], v149 offset:16384
	ds_read_b128 v[180:183], v149 offset:17408
	ds_read_b128 v[184:187], v149 offset:18432
	ds_read_b128 v[188:191], v149 offset:19456
	ds_read_b128 v[192:195], v149 offset:20480
	ds_read_b128 v[196:199], v149 offset:21504
	ds_read_b128 v[200:203], v149 offset:22528
	ds_read_b128 v[204:207], v149 offset:23552
	global_load_lds_dwordx4 v[228:229], off
	v_lshl_add_u64 v[228:229], v[224:225], 0, s[26:27]
	s_mov_b32 m0, s68
	s_nop 0
	global_load_lds_dwordx4 v[228:229], off
	s_waitcnt vmcnt(4)
	s_barrier
; #define STAGE(P, BASE, br, kt) do { const char* _gb = (const char*)(BASE) + ((size_t)(br) * K + (size_t)(kt) * BK) * 2; \
;     __builtin_amdgcn_global_load_lds((const unsigned*)(_gb + loff0), (unsigned*)((char*)(P) + tid * 16), 16, 0, 0); \
;     __builtin_amdgcn_global_load_lds((const unsigned*)(_gb + (size_t)K * 128 + loff0), (unsigned*)((char*)(P) + tid * 16 + 8192), 16, 0, 0); } while (0)
; #define LDA(dst, b, h) for (int m = 0; m < 4; ++m) { \
;     dst[m][0] = *reinterpret_cast<const bf16x8*>((char*)SA(b, h) + aoff0 + m * 2048); \
;     dst[m][1] = *reinterpret_cast<const bf16x8*>((char*)SA(b, h) + aoff1 + m * 2048); }
; #define LDB(dst, b, h) for (int n = 0; n < 2; ++n) { \
;     dst[n][0] = *reinterpret_cast<const bf16x8*>((char*)SB(b, h) + boff0 + n * 256); \
;     dst[n][1] = *reinterpret_cast<const bf16x8*>((char*)SB(b, h) + boff1 + n * 256); }
; #define MMA(ai, bj, At, Btf) do { __builtin_amdgcn_s_setprio(1); \
;     for (int m = 0; m < 4; ++m) for (int n = 0; n < 2; ++n) for (int k = 0; k < 2; ++k) \
;       acc[ai][bj][m][n] = __builtin_amdgcn_mfma_f32_16x16x32_bf16(Btf[n][k], At[m][k], acc[ai][bj][m][n], 0, 0, 0); \
;     __builtin_amdgcn_s_setprio(0); } while (0)
; #define WAIT_V(n) asm volatile("s_waitcnt vmcnt(" #n ")" ::: "memory")
; #define WAIT_L(n) asm volatile("s_waitcnt lgkmcnt(" #n ")" ::: "memory")
; #define BAR __builtin_amdgcn_s_barrier()
; #define SCHED __builtin_amdgcn_sched_barrier(0)
; template <int EPI> ...
;     ...
;     WAIT_V(6); BAR; MMA(1, 1, At, B1); BAR;
;     LDB(B0, 1, 0); SCHED; LDA(At, 1, 0); STAGE(SA(0, 1), A, brow + HALF, t + 2);
;     WAIT_L(8); BAR; WAIT_L(0); MMA(0, 0, At, B0); BAR; SCHED;
;     LDB(B1, 1, 1); STAGE(SB(1, 0), Bt, bcol, t + 3);
;     BAR; WAIT_L(0); MMA(0, 1, At, B1); BAR;
	s_waitcnt lgkmcnt(0)
	s_setprio 1
	s_waitcnt lgkmcnt(0)
	v_mfma_f32_16x16x32_bf16 v[60:63], v[160:163], v[176:179], v[60:63]
	v_mfma_f32_16x16x32_bf16 v[56:59], v[164:167], v[176:179], v[56:59]
	v_mfma_f32_16x16x32_bf16 v[52:55], v[160:163], v[184:187], v[52:55]
	v_mfma_f32_16x16x32_bf16 v[48:51], v[164:167], v[184:187], v[48:51]
	v_mfma_f32_16x16x32_bf16 v[44:47], v[160:163], v[192:195], v[44:47]
	v_mfma_f32_16x16x32_bf16 v[40:43], v[164:167], v[192:195], v[40:43]
	v_mfma_f32_16x16x32_bf16 v[36:39], v[160:163], v[200:203], v[36:39]
	v_mfma_f32_16x16x32_bf16 v[32:35], v[164:167], v[200:203], v[32:35]
	v_mfma_f32_16x16x32_bf16 v[60:63], v[168:171], v[180:183], v[60:63]
	v_mfma_f32_16x16x32_bf16 v[56:59], v[172:175], v[180:183], v[56:59]
	v_mfma_f32_16x16x32_bf16 v[52:55], v[168:171], v[188:191], v[52:55]
	v_mfma_f32_16x16x32_bf16 v[48:51], v[172:175], v[188:191], v[48:51]
	v_mfma_f32_16x16x32_bf16 v[44:47], v[168:171], v[196:199], v[44:47]
	v_mfma_f32_16x16x32_bf16 v[40:43], v[172:175], v[196:199], v[40:43]
	v_mfma_f32_16x16x32_bf16 v[36:39], v[168:171], v[204:207], v[36:39]
	v_mfma_f32_16x16x32_bf16 v[32:35], v[172:175], v[204:207], v[32:35]
	s_setprio 0
	s_setprio 1
	v_mfma_f32_16x16x32_bf16 v[28:31], v[208:211], v[176:179], v[28:31]
	v_mfma_f32_16x16x32_bf16 v[24:27], v[212:215], v[176:179], v[24:27]
	v_mfma_f32_16x16x32_bf16 v[20:23], v[208:211], v[184:187], v[20:23]
	v_mfma_f32_16x16x32_bf16 v[16:19], v[212:215], v[184:187], v[16:19]
	v_mfma_f32_16x16x32_bf16 v[12:15], v[208:211], v[192:195], v[12:15]
	v_mfma_f32_16x16x32_bf16 v[8:11], v[212:215], v[192:195], v[8:11]
	v_mfma_f32_16x16x32_bf16 v[4:7], v[208:211], v[200:203], v[4:7]
	v_mfma_f32_16x16x32_bf16 v[0:3], v[212:215], v[200:203], v[0:3]
	v_mfma_f32_16x16x32_bf16 v[28:31], v[216:219], v[180:183], v[28:31]
	v_mfma_f32_16x16x32_bf16 v[24:27], v[220:223], v[180:183], v[24:27]
	v_mfma_f32_16x16x32_bf16 v[20:23], v[216:219], v[188:191], v[20:23]
	v_mfma_f32_16x16x32_bf16 v[16:19], v[220:223], v[188:191], v[16:19]
	v_mfma_f32_16x16x32_bf16 v[12:15], v[216:219], v[196:199], v[12:15]
	v_mfma_f32_16x16x32_bf16 v[8:11], v[220:223], v[196:199], v[8:11]
	v_mfma_f32_16x16x32_bf16 v[4:7], v[216:219], v[204:207], v[4:7]
	v_mfma_f32_16x16x32_bf16 v[0:3], v[220:223], v[204:207], v[0:3]
	s_setprio 0
	s_barrier
	ds_read_b128 v[160:163], v156
	ds_read_b128 v[164:167], v156 offset:256
	ds_read_b128 v[168:171], v157
	ds_read_b128 v[172:175], v157 offset:256
	v_readfirstlane_b32 s68, v141
	v_lshl_add_u64 v[208:209], v[224:225], 0, s[36:37]
	s_mov_b32 m0, s68
	v_readfirstlane_b32 s68, v142
	ds_read_b128 v[176:179], v149 offset:32768
	ds_read_b128 v[180:183], v149 offset:33792
	ds_read_b128 v[184:187], v149 offset:34816
	ds_read_b128 v[188:191], v149 offset:35840
	ds_read_b128 v[192:195], v149 offset:36864
	ds_read_b128 v[196:199], v149 offset:37888
	ds_read_b128 v[200:203], v149 offset:38912
	ds_read_b128 v[204:207], v149 offset:39936
	global_load_lds_dwordx4 v[208:209], off
	v_lshl_add_u64 v[208:209], v[224:225], 0, s[38:39]
	s_mov_b32 m0, s68
	s_nop 0
	global_load_lds_dwordx4 v[208:209], off
	s_waitcnt lgkmcnt(8)
	v_readfirstlane_b32 s68, v139
	v_lshl_add_u64 v[246:247], v[226:227], 0, s[28:29]
	s_mov_b32 m0, s68
	v_readfirstlane_b32 s68, v140
	global_load_lds_dwordx4 v[246:247], off
	v_lshl_add_u64 v[246:247], v[226:227], 0, s[30:31]
	s_mov_b32 m0, s68
	s_nop 0
	global_load_lds_dwordx4 v[246:247], off
	ds_read_b128 v[208:211], v158
	ds_read_b128 v[212:215], v158 offset:256
	ds_read_b128 v[216:219], v159
	ds_read_b128 v[220:223], v159 offset:256
	s_barrier
	s_waitcnt lgkmcnt(0)
	s_setprio 1
	s_waitcnt lgkmcnt(0)
	v_mfma_f32_16x16x32_bf16 v[124:127], v[160:163], v[176:179], v[124:127]
	v_mfma_f32_16x16x32_bf16 v[120:123], v[164:167], v[176:179], v[120:123]
	v_mfma_f32_16x16x32_bf16 v[116:119], v[160:163], v[184:187], v[116:119]
	v_mfma_f32_16x16x32_bf16 v[112:115], v[164:167], v[184:187], v[112:115]
	v_mfma_f32_16x16x32_bf16 v[108:111], v[160:163], v[192:195], v[108:111]
	v_mfma_f32_16x16x32_bf16 v[104:107], v[164:167], v[192:195], v[104:107]
	v_mfma_f32_16x16x32_bf16 v[100:103], v[160:163], v[200:203], v[100:103]
	v_mfma_f32_16x16x32_bf16 v[96:99], v[164:167], v[200:203], v[96:99]
	v_mfma_f32_16x16x32_bf16 v[124:127], v[168:171], v[180:183], v[124:127]
	v_mfma_f32_16x16x32_bf16 v[120:123], v[172:175], v[180:183], v[120:123]
	v_mfma_f32_16x16x32_bf16 v[116:119], v[168:171], v[188:191], v[116:119]
	v_mfma_f32_16x16x32_bf16 v[112:115], v[172:175], v[188:191], v[112:115]
	v_mfma_f32_16x16x32_bf16 v[108:111], v[168:171], v[196:199], v[108:111]
	v_mfma_f32_16x16x32_bf16 v[104:107], v[172:175], v[196:199], v[104:107]
	v_mfma_f32_16x16x32_bf16 v[100:103], v[168:171], v[204:207], v[100:103]
	v_mfma_f32_16x16x32_bf16 v[96:99], v[172:175], v[204:207], v[96:99]
	s_setprio 0
	s_waitcnt lgkmcnt(0)
	s_setprio 1
	s_waitcnt lgkmcnt(0)
	v_mfma_f32_16x16x32_bf16 v[92:95], v[208:211], v[176:179], v[92:95]
	v_mfma_f32_16x16x32_bf16 v[88:91], v[212:215], v[176:179], v[88:91]
	v_mfma_f32_16x16x32_bf16 v[84:87], v[208:211], v[184:187], v[84:87]
	v_mfma_f32_16x16x32_bf16 v[80:83], v[212:215], v[184:187], v[80:83]
	v_mfma_f32_16x16x32_bf16 v[76:79], v[208:211], v[192:195], v[76:79]
	v_mfma_f32_16x16x32_bf16 v[72:75], v[212:215], v[192:195], v[72:75]
	v_mfma_f32_16x16x32_bf16 v[68:71], v[208:211], v[200:203], v[68:71]
	v_mfma_f32_16x16x32_bf16 v[64:67], v[212:215], v[200:203], v[64:67]
	v_mfma_f32_16x16x32_bf16 v[92:95], v[216:219], v[180:183], v[92:95]
	v_mfma_f32_16x16x32_bf16 v[88:91], v[220:223], v[180:183], v[88:91]
	v_mfma_f32_16x16x32_bf16 v[84:87], v[216:219], v[188:191], v[84:87]
	v_mfma_f32_16x16x32_bf16 v[80:83], v[220:223], v[188:191], v[80:83]
	v_mfma_f32_16x16x32_bf16 v[76:79], v[216:219], v[196:199], v[76:79]
	v_mfma_f32_16x16x32_bf16 v[72:75], v[220:223], v[196:199], v[72:75]
	v_mfma_f32_16x16x32_bf16 v[68:71], v[216:219], v[204:207], v[68:71]
	v_mfma_f32_16x16x32_bf16 v[64:67], v[220:223], v[204:207], v[64:67]
	s_setprio 0
	s_barrier
; #define STAGE(P, BASE, br, kt) do { const char* _gb = (const char*)(BASE) + ((size_t)(br) * K + (size_t)(kt) * BK) * 2; \
;     __builtin_amdgcn_global_load_lds((const unsigned*)(_gb + loff0), (unsigned*)((char*)(P) + tid * 16), 16, 0, 0); \
;     __builtin_amdgcn_global_load_lds((const unsigned*)(_gb + (size_t)K * 128 + loff0), (unsigned*)((char*)(P) + tid * 16 + 8192), 16, 0, 0); } while (0)
; #define LDA(dst, b, h) for (int m = 0; m < 4; ++m) { \
;     dst[m][0] = *reinterpret_cast<const bf16x8*>((char*)SA(b, h) + aoff0 + m * 2048); \
;     dst[m][1] = *reinterpret_cast<const bf16x8*>((char*)SA(b, h) + aoff1 + m * 2048); }
; #define LDB(dst, b, h) for (int n = 0; n < 2; ++n) { \
;     dst[n][0] = *reinterpret_cast<const bf16x8*>((char*)SB(b, h) + boff0 + n * 256); \
;     dst[n][1] = *reinterpret_cast<const bf16x8*>((char*)SB(b, h) + boff1 + n * 256); }
; #define MMA(ai, bj, At, Btf) do { __builtin_amdgcn_s_setprio(1); \
;     for (int m = 0; m < 4; ++m) for (int n = 0; n < 2; ++n) for (int k = 0; k < 2; ++k) \
;       acc[ai][bj][m][n] = __builtin_amdgcn_mfma_f32_16x16x32_bf16(Btf[n][k], At[m][k], acc[ai][bj][m][n], 0, 0, 0); \
;     __builtin_amdgcn_s_setprio(0); } while (0)
; #define WAIT_V(n) asm volatile("s_waitcnt vmcnt(" #n ")" ::: "memory")
; #define WAIT_L(n) asm volatile("s_waitcnt lgkmcnt(" #n ")" ::: "memory")
; #define BAR __builtin_amdgcn_s_barrier()
; #define SCHED __builtin_amdgcn_sched_barrier(0)
; template <int EPI> ...
;     ...
;     LDA(At, 1, 1); STAGE(SA(1, 0), A, brow, t + 3);
;     BAR; WAIT_L(0); MMA(1, 0, At, B0); BAR; SCHED;
;     STAGE(SB(1, 1), Bt, bcol + HALF, t + 3);
;     WAIT_V(6); BAR; MMA(1, 1, At, B1); BAR;
;   }
;   { LDB(B0, 0, 0); LDA(At, 0, 0); STAGE(SA(1, 1), A, brow + HALF, nt - 1);
;     BAR; WAIT_L(0); MMA(0, 0, At, B0); BAR;
	v_readfirstlane_b32 s68, v143
	v_lshl_add_u64 v[228:229], v[226:227], 0, s[46:47]
	s_mov_b32 m0, s68
	v_readfirstlane_b32 s68, v144
	global_load_lds_dwordx4 v[228:229], off
	v_lshl_add_u64 v[228:229], v[226:227], 0, s[48:49]
	s_mov_b32 m0, s68
	s_nop 0
	global_load_lds_dwordx4 v[228:229], off
	v_readfirstlane_b32 s68, v145
	v_lshl_add_u64 v[228:229], v[224:225], 0, s[50:51]
	s_mov_b32 m0, s68
	v_readfirstlane_b32 s68, v146
	ds_read_b128 v[176:179], v149 offset:49152
	ds_read_b128 v[180:183], v149 offset:50176
	ds_read_b128 v[184:187], v149 offset:51200
	ds_read_b128 v[188:191], v149 offset:52224
	ds_read_b128 v[192:195], v149 offset:53248
	ds_read_b128 v[196:199], v149 offset:54272
	ds_read_b128 v[200:203], v149 offset:55296
	ds_read_b128 v[204:207], v149 offset:56320
	global_load_lds_dwordx4 v[228:229], off
	v_lshl_add_u64 v[224:225], v[224:225], 0, s[52:53]
	s_mov_b32 m0, s68
	s_nop 0
	global_load_lds_dwordx4 v[224:225], off
	s_waitcnt vmcnt(4)
	s_barrier
	s_waitcnt lgkmcnt(0)
	s_setprio 1
	s_waitcnt lgkmcnt(0)
	v_mfma_f32_16x16x32_bf16 v[60:63], v[160:163], v[176:179], v[60:63]
	v_mfma_f32_16x16x32_bf16 v[56:59], v[164:167], v[176:179], v[56:59]
	v_mfma_f32_16x16x32_bf16 v[52:55], v[160:163], v[184:187], v[52:55]
	v_mfma_f32_16x16x32_bf16 v[48:51], v[164:167], v[184:187], v[48:51]
	v_mfma_f32_16x16x32_bf16 v[44:47], v[160:163], v[192:195], v[44:47]
	v_mfma_f32_16x16x32_bf16 v[40:43], v[164:167], v[192:195], v[40:43]
	v_mfma_f32_16x16x32_bf16 v[36:39], v[160:163], v[200:203], v[36:39]
	v_mfma_f32_16x16x32_bf16 v[32:35], v[164:167], v[200:203], v[32:35]
	v_mfma_f32_16x16x32_bf16 v[60:63], v[168:171], v[180:183], v[60:63]
	v_mfma_f32_16x16x32_bf16 v[56:59], v[172:175], v[180:183], v[56:59]
	v_mfma_f32_16x16x32_bf16 v[52:55], v[168:171], v[188:191], v[52:55]
	v_mfma_f32_16x16x32_bf16 v[48:51], v[172:175], v[188:191], v[48:51]
	v_mfma_f32_16x16x32_bf16 v[44:47], v[168:171], v[196:199], v[44:47]
	v_mfma_f32_16x16x32_bf16 v[40:43], v[172:175], v[196:199], v[40:43]
	v_mfma_f32_16x16x32_bf16 v[36:39], v[168:171], v[204:207], v[36:39]
	v_mfma_f32_16x16x32_bf16 v[32:35], v[172:175], v[204:207], v[32:35]
	s_setprio 0
	s_setprio 1
	v_mfma_f32_16x16x32_bf16 v[28:31], v[208:211], v[176:179], v[28:31]
	v_mfma_f32_16x16x32_bf16 v[24:27], v[212:215], v[176:179], v[24:27]
	v_mfma_f32_16x16x32_bf16 v[20:23], v[208:211], v[184:187], v[20:23]
	v_mfma_f32_16x16x32_bf16 v[16:19], v[212:215], v[184:187], v[16:19]
	v_mfma_f32_16x16x32_bf16 v[12:15], v[208:211], v[192:195], v[12:15]
	v_mfma_f32_16x16x32_bf16 v[8:11], v[212:215], v[192:195], v[8:11]
	v_mfma_f32_16x16x32_bf16 v[4:7], v[208:211], v[200:203], v[4:7]
	v_mfma_f32_16x16x32_bf16 v[0:3], v[212:215], v[200:203], v[0:3]
	v_mfma_f32_16x16x32_bf16 v[28:31], v[216:219], v[180:183], v[28:31]
	v_mfma_f32_16x16x32_bf16 v[24:27], v[220:223], v[180:183], v[24:27]
	v_mfma_f32_16x16x32_bf16 v[20:23], v[216:219], v[188:191], v[20:23]
	v_mfma_f32_16x16x32_bf16 v[16:19], v[220:223], v[188:191], v[16:19]
	v_mfma_f32_16x16x32_bf16 v[12:15], v[216:219], v[196:199], v[12:15]
	v_mfma_f32_16x16x32_bf16 v[8:11], v[220:223], v[196:199], v[8:11]
	v_mfma_f32_16x16x32_bf16 v[4:7], v[216:219], v[204:207], v[4:7]
	v_mfma_f32_16x16x32_bf16 v[0:3], v[220:223], v[204:207], v[0:3]
	s_setprio 0
	s_add_i32 s59, s59, 2
	s_add_u32 s64, s64, 0x100
	s_addc_u32 s65, s65, 0
	s_add_u32 s66, s66, 0x100
	s_addc_u32 s67, s67, 0
	s_cmp_lt_u32 s59, 28
	s_barrier
	s_cbranch_scc1 .LBB0_1018
	v_readfirstlane_b32 s68, v147
	v_lshl_add_u64 v[246:247], v[226:227], 0, s[54:55]
	s_mov_b32 m0, s68
	v_readfirstlane_b32 s68, v148
	global_load_lds_dwordx4 v[246:247], off
	v_lshl_add_u64 v[246:247], v[226:227], 0, s[56:57]
	s_mov_b32 m0, s68
	s_nop 0
	global_load_lds_dwordx4 v[246:247], off
	s_add_u32 s62, s72, s62
	s_addc_u32 s63, s73, s63
	v_readfirstlane_b32 s59, v150
	v_lshl_add_u64 v[208:209], s[62:63], 0, v[128:129]
	s_mov_b32 m0, s59
	v_readfirstlane_b32 s59, v151
	ds_read_b128 v[160:163], v152
	ds_read_b128 v[164:167], v152 offset:256
	ds_read_b128 v[168:171], v153
	ds_read_b128 v[172:175], v153 offset:256
	ds_read_b128 v[176:179], v149
	ds_read_b128 v[180:183], v149 offset:1024
	ds_read_b128 v[184:187], v149 offset:2048
	ds_read_b128 v[188:191], v149 offset:3072
	ds_read_b128 v[192:195], v149 offset:4096
	ds_read_b128 v[196:199], v149 offset:5120
	ds_read_b128 v[200:203], v149 offset:6144
	ds_read_b128 v[204:207], v149 offset:7168
	global_load_lds_dwordx4 v[208:209], off
	v_lshl_add_u64 v[208:209], v[208:209], 0, s[8:9]
	s_mov_b32 m0, s59
	s_nop 0
	global_load_lds_dwordx4 v[208:209], off
	s_barrier
	s_waitcnt lgkmcnt(0)
	s_setprio 1
	s_waitcnt lgkmcnt(0)
	v_mfma_f32_16x16x32_bf16 v[124:127], v[160:163], v[176:179], v[124:127]
	v_mfma_f32_16x16x32_bf16 v[116:119], v[160:163], v[184:187], v[116:119]
	v_mfma_f32_16x16x32_bf16 v[108:111], v[160:163], v[192:195], v[108:111]
	v_mfma_f32_16x16x32_bf16 v[100:103], v[160:163], v[200:203], v[100:103]
	v_mfma_f32_16x16x32_bf16 v[96:99], v[164:167], v[200:203], v[96:99]
	v_mfma_f32_16x16x32_bf16 v[124:127], v[168:171], v[180:183], v[124:127]
	v_mfma_f32_16x16x32_bf16 v[120:123], v[164:167], v[176:179], v[120:123]
	v_mfma_f32_16x16x32_bf16 v[116:119], v[168:171], v[188:191], v[116:119]
	v_mfma_f32_16x16x32_bf16 v[112:115], v[164:167], v[184:187], v[112:115]
	v_mfma_f32_16x16x32_bf16 v[108:111], v[168:171], v[196:199], v[108:111]
	v_mfma_f32_16x16x32_bf16 v[104:107], v[164:167], v[192:195], v[104:107]
	v_mfma_f32_16x16x32_bf16 v[100:103], v[168:171], v[204:207], v[100:103]
	v_mfma_f32_16x16x32_bf16 v[96:99], v[172:175], v[204:207], v[96:99]
	v_mfma_f32_16x16x32_bf16 v[208:211], v[172:175], v[180:183], v[120:123]
	v_mfma_f32_16x16x32_bf16 v[212:215], v[172:175], v[188:191], v[112:115]
	v_mfma_f32_16x16x32_bf16 v[216:219], v[172:175], v[196:199], v[104:107]
	s_setprio 0
	s_barrier
; #define LDA(dst, b, h) for (int m = 0; m < 4; ++m) { \
;     dst[m][0] = *reinterpret_cast<const bf16x8*>((char*)SA(b, h) + aoff0 + m * 2048); \
;     dst[m][1] = *reinterpret_cast<const bf16x8*>((char*)SA(b, h) + aoff1 + m * 2048); }
; #define LDB(dst, b, h) for (int n = 0; n < 2; ++n) { \
;     dst[n][0] = *reinterpret_cast<const bf16x8*>((char*)SB(b, h) + boff0 + n * 256); \
;     dst[n][1] = *reinterpret_cast<const bf16x8*>((char*)SB(b, h) + boff1 + n * 256); }
; #define MMA(ai, bj, At, Btf) do { __builtin_amdgcn_s_setprio(1); \
;     for (int m = 0; m < 4; ++m) for (int n = 0; n < 2; ++n) for (int k = 0; k < 2; ++k) \
;       acc[ai][bj][m][n] = __builtin_amdgcn_mfma_f32_16x16x32_bf16(Btf[n][k], At[m][k], acc[ai][bj][m][n], 0, 0, 0); \
;     __builtin_amdgcn_s_setprio(0); } while (0)
; #define WAIT_V(n) asm volatile("s_waitcnt vmcnt(" #n ")" ::: "memory")
; #define WAIT_L(n) asm volatile("s_waitcnt lgkmcnt(" #n ")" ::: "memory")
; #define BAR __builtin_amdgcn_s_barrier()
; template <int EPI> ...
;     ...
;     BAR; WAIT_L(0); MMA(0, 0, At, B0); BAR;
;     LDB(B1, 0, 1); BAR; WAIT_L(0); MMA(0, 1, At, B1); BAR;
;     LDA(At, 0, 1); WAIT_V(4); BAR; WAIT_L(0); MMA(1, 0, At, B0); MMA(1, 1, At, B1); BAR; }
;   { LDB(B0, 1, 0); LDA(At, 1, 0); WAIT_V(2); BAR; WAIT_L(0); MMA(0, 0, At, B0); BAR;
	s_nop 0
	ds_read_b128 v[104:107], v154
	ds_read_b128 v[112:115], v154 offset:256
	ds_read_b128 v[120:123], v155
	ds_read_b128 v[220:223], v155 offset:256
	s_barrier
	s_waitcnt lgkmcnt(0)
	s_setprio 1
	s_waitcnt lgkmcnt(0)
	v_mfma_f32_16x16x32_bf16 v[84:87], v[104:107], v[184:187], v[84:87]
	v_mfma_f32_16x16x32_bf16 v[76:79], v[104:107], v[192:195], v[76:79]
	v_mfma_f32_16x16x32_bf16 v[72:75], v[112:115], v[192:195], v[72:75]
	v_mfma_f32_16x16x32_bf16 v[92:95], v[104:107], v[176:179], v[92:95]
	v_mfma_f32_16x16x32_bf16 v[88:91], v[112:115], v[176:179], v[88:91]
	v_mfma_f32_16x16x32_bf16 v[84:87], v[120:123], v[188:191], v[84:87]
	v_mfma_f32_16x16x32_bf16 v[80:83], v[112:115], v[184:187], v[80:83]
	v_mfma_f32_16x16x32_bf16 v[76:79], v[120:123], v[196:199], v[76:79]
	v_mfma_f32_16x16x32_bf16 v[72:75], v[220:223], v[196:199], v[72:75]
	v_mfma_f32_16x16x32_bf16 v[68:71], v[104:107], v[200:203], v[68:71]
	v_mfma_f32_16x16x32_bf16 v[64:67], v[112:115], v[200:203], v[64:67]
	v_mfma_f32_16x16x32_bf16 v[224:227], v[120:123], v[180:183], v[92:95]
	v_mfma_f32_16x16x32_bf16 v[176:179], v[220:223], v[180:183], v[88:91]
	v_mfma_f32_16x16x32_bf16 v[180:183], v[220:223], v[188:191], v[80:83]
	v_mfma_f32_16x16x32_bf16 v[184:187], v[120:123], v[204:207], v[68:71]
	v_mfma_f32_16x16x32_bf16 v[188:191], v[220:223], v[204:207], v[64:67]
	s_setprio 0
	s_barrier
	s_nop 0
	ds_read_b128 v[64:67], v149 offset:16384
	ds_read_b128 v[68:71], v149 offset:17408
	ds_read_b128 v[80:83], v149 offset:18432
	ds_read_b128 v[88:91], v149 offset:19456
	ds_read_b128 v[92:95], v149 offset:20480
	ds_read_b128 v[192:195], v149 offset:21504
	ds_read_b128 v[196:199], v149 offset:22528
	ds_read_b128 v[200:203], v149 offset:23552
	s_waitcnt vmcnt(4)
	s_barrier
	s_waitcnt lgkmcnt(0)
	s_setprio 1
	s_waitcnt lgkmcnt(0)
	v_mfma_f32_16x16x32_bf16 v[52:55], v[160:163], v[80:83], v[52:55]
	v_mfma_f32_16x16x32_bf16 v[44:47], v[160:163], v[92:95], v[44:47]
	v_mfma_f32_16x16x32_bf16 v[36:39], v[160:163], v[196:199], v[36:39]
	v_mfma_f32_16x16x32_bf16 v[60:63], v[160:163], v[64:67], v[60:63]
	v_mfma_f32_16x16x32_bf16 v[56:59], v[164:167], v[64:67], v[56:59]
	v_mfma_f32_16x16x32_bf16 v[52:55], v[168:171], v[88:91], v[52:55]
	v_mfma_f32_16x16x32_bf16 v[48:51], v[164:167], v[80:83], v[48:51]
	v_mfma_f32_16x16x32_bf16 v[44:47], v[168:171], v[192:195], v[44:47]
	v_mfma_f32_16x16x32_bf16 v[40:43], v[164:167], v[92:95], v[40:43]
	v_mfma_f32_16x16x32_bf16 v[36:39], v[168:171], v[200:203], v[36:39]
	v_mfma_f32_16x16x32_bf16 v[32:35], v[164:167], v[196:199], v[32:35]
	v_mfma_f32_16x16x32_bf16 v[204:207], v[168:171], v[68:71], v[60:63]
	v_mfma_f32_16x16x32_bf16 v[228:231], v[172:175], v[68:71], v[56:59]
	v_mfma_f32_16x16x32_bf16 v[232:235], v[172:175], v[88:91], v[48:51]
	v_mfma_f32_16x16x32_bf16 v[236:239], v[172:175], v[192:195], v[40:43]
	v_mfma_f32_16x16x32_bf16 v[160:163], v[172:175], v[200:203], v[32:35]
	s_setprio 0
	s_setprio 1
	v_mfma_f32_16x16x32_bf16 v[28:31], v[104:107], v[64:67], v[28:31]
	v_mfma_f32_16x16x32_bf16 v[20:23], v[104:107], v[80:83], v[20:23]
	v_mfma_f32_16x16x32_bf16 v[12:15], v[104:107], v[92:95], v[12:15]
	v_mfma_f32_16x16x32_bf16 v[4:7], v[104:107], v[196:199], v[4:7]
	v_mfma_f32_16x16x32_bf16 v[28:31], v[120:123], v[68:71], v[28:31]
	v_mfma_f32_16x16x32_bf16 v[24:27], v[112:115], v[64:67], v[24:27]
	v_mfma_f32_16x16x32_bf16 v[20:23], v[120:123], v[88:91], v[20:23]
	v_mfma_f32_16x16x32_bf16 v[16:19], v[112:115], v[80:83], v[16:19]
	v_mfma_f32_16x16x32_bf16 v[12:15], v[120:123], v[192:195], v[12:15]
	v_mfma_f32_16x16x32_bf16 v[8:11], v[112:115], v[92:95], v[8:11]
	v_mfma_f32_16x16x32_bf16 v[4:7], v[120:123], v[200:203], v[4:7]
	v_mfma_f32_16x16x32_bf16 v[0:3], v[112:115], v[196:199], v[0:3]
	v_mfma_f32_16x16x32_bf16 v[164:167], v[220:223], v[68:71], v[24:27]
	v_mfma_f32_16x16x32_bf16 v[168:171], v[220:223], v[88:91], v[16:19]
	v_mfma_f32_16x16x32_bf16 v[172:175], v[220:223], v[192:195], v[8:11]
	v_mfma_f32_16x16x32_bf16 v[192:195], v[220:223], v[200:203], v[0:3]
	s_setprio 0
	s_barrier
	s_nop 1
	ds_read_b128 v[0:3], v156
	ds_read_b128 v[8:11], v156 offset:256
	ds_read_b128 v[16:19], v157
	ds_read_b128 v[24:27], v157 offset:256
	ds_read_b128 v[32:35], v149 offset:32768
	ds_read_b128 v[40:43], v149 offset:33792
	ds_read_b128 v[48:51], v149 offset:34816
	ds_read_b128 v[56:59], v149 offset:35840
	ds_read_b128 v[60:63], v149 offset:36864
	ds_read_b128 v[68:71], v149 offset:37888
	ds_read_b128 v[196:199], v149 offset:38912
	ds_read_b128 v[200:203], v149 offset:39936
	s_waitcnt vmcnt(2)
	s_barrier
; #define LDA(dst, b, h) for (int m = 0; m < 4; ++m) { \
;     dst[m][0] = *reinterpret_cast<const bf16x8*>((char*)SA(b, h) + aoff0 + m * 2048); \
;     dst[m][1] = *reinterpret_cast<const bf16x8*>((char*)SA(b, h) + aoff1 + m * 2048); }
; #define LDB(dst, b, h) for (int n = 0; n < 2; ++n) { \
;     dst[n][0] = *reinterpret_cast<const bf16x8*>((char*)SB(b, h) + boff0 + n * 256); \
;     dst[n][1] = *reinterpret_cast<const bf16x8*>((char*)SB(b, h) + boff1 + n * 256); }
; #define MMA(ai, bj, At, Btf) do { __builtin_amdgcn_s_setprio(1); \
;     for (int m = 0; m < 4; ++m) for (int n = 0; n < 2; ++n) for (int k = 0; k < 2; ++k) \
;       acc[ai][bj][m][n] = __builtin_amdgcn_mfma_f32_16x16x32_bf16(Btf[n][k], At[m][k], acc[ai][bj][m][n], 0, 0, 0); \
;     __builtin_amdgcn_s_setprio(0); } while (0)
; #define WAIT_V(n) asm volatile("s_waitcnt vmcnt(" #n ")" ::: "memory")
; #define WAIT_L(n) asm volatile("s_waitcnt lgkmcnt(" #n ")" ::: "memory")
; #define BAR __builtin_amdgcn_s_barrier()
; template <int EPI> ...
;     ...
;   { LDB(B0, 1, 0); LDA(At, 1, 0); WAIT_V(2); BAR; WAIT_L(0); MMA(0, 0, At, B0); BAR;
;     LDB(B1, 1, 1); WAIT_V(0); BAR; WAIT_L(0); MMA(0, 1, At, B1); BAR;
;     LDA(At, 1, 1); BAR; WAIT_L(0); MMA(1, 0, At, B0); MMA(1, 1, At, B1); BAR; }
;   if (wr == 0) BAR;
	s_waitcnt lgkmcnt(0)
	s_setprio 1
	s_waitcnt lgkmcnt(0)
	v_mfma_f32_16x16x32_bf16 v[64:67], v[0:3], v[32:35], v[124:127]
	v_mfma_f32_16x16x32_bf16 v[120:123], v[16:19], v[40:43], v[64:67]
	v_mfma_f32_16x16x32_bf16 v[64:67], v[8:11], v[32:35], v[208:211]
	v_mfma_f32_16x16x32_bf16 v[124:127], v[24:27], v[40:43], v[64:67]
	v_mfma_f32_16x16x32_bf16 v[64:67], v[0:3], v[48:51], v[116:119]
	v_mfma_f32_16x16x32_bf16 v[112:115], v[16:19], v[56:59], v[64:67]
	v_mfma_f32_16x16x32_bf16 v[64:67], v[8:11], v[48:51], v[212:215]
	v_mfma_f32_16x16x32_bf16 v[116:119], v[24:27], v[56:59], v[64:67]
	v_mfma_f32_16x16x32_bf16 v[64:67], v[0:3], v[60:63], v[108:111]
	v_mfma_f32_16x16x32_bf16 v[104:107], v[16:19], v[68:71], v[64:67]
	v_mfma_f32_16x16x32_bf16 v[64:67], v[8:11], v[60:63], v[216:219]
	v_mfma_f32_16x16x32_bf16 v[108:111], v[24:27], v[68:71], v[64:67]
	v_mfma_f32_16x16x32_bf16 v[64:67], v[0:3], v[196:199], v[100:103]
	v_mfma_f32_16x16x32_bf16 v[88:91], v[16:19], v[200:203], v[64:67]
	v_mfma_f32_16x16x32_bf16 v[64:67], v[8:11], v[196:199], v[96:99]
	v_mfma_f32_16x16x32_bf16 v[92:95], v[24:27], v[200:203], v[64:67]
	s_setprio 0
	s_barrier
	ds_read_b128 v[208:211], v158
	ds_read_b128 v[212:215], v158 offset:256
	ds_read_b128 v[216:219], v159
	ds_read_b128 v[220:223], v159 offset:256
	s_waitcnt vmcnt(0)
	s_barrier
	s_waitcnt lgkmcnt(0)
	s_setprio 1
	s_waitcnt lgkmcnt(0)
	v_mfma_f32_16x16x32_bf16 v[64:67], v[208:211], v[32:35], v[224:227]
	v_mfma_f32_16x16x32_bf16 v[32:35], v[212:215], v[32:35], v[176:179]
	v_mfma_f32_16x16x32_bf16 v[100:103], v[220:223], v[40:43], v[32:35]
	v_mfma_f32_16x16x32_bf16 v[32:35], v[208:211], v[48:51], v[84:87]
	v_mfma_f32_16x16x32_bf16 v[80:83], v[216:219], v[56:59], v[32:35]
	v_mfma_f32_16x16x32_bf16 v[32:35], v[212:215], v[48:51], v[180:183]
	v_mfma_f32_16x16x32_bf16 v[84:87], v[220:223], v[56:59], v[32:35]
	v_mfma_f32_16x16x32_bf16 v[32:35], v[208:211], v[60:63], v[76:79]
	v_mfma_f32_16x16x32_bf16 v[96:99], v[216:219], v[40:43], v[64:67]
	v_mfma_f32_16x16x32_bf16 v[64:67], v[216:219], v[68:71], v[32:35]
	v_mfma_f32_16x16x32_bf16 v[32:35], v[212:215], v[60:63], v[72:75]
	v_mfma_f32_16x16x32_bf16 v[68:71], v[220:223], v[68:71], v[32:35]
	v_mfma_f32_16x16x32_bf16 v[32:35], v[208:211], v[196:199], v[184:187]
	v_mfma_f32_16x16x32_bf16 v[56:59], v[216:219], v[200:203], v[32:35]
	v_mfma_f32_16x16x32_bf16 v[32:35], v[212:215], v[196:199], v[188:191]
	v_mfma_f32_16x16x32_bf16 v[60:63], v[220:223], v[200:203], v[32:35]
	s_setprio 0
	s_barrier
	ds_read_b128 v[176:179], v149 offset:49152
	ds_read_b128 v[180:183], v149 offset:50176
	ds_read_b128 v[184:187], v149 offset:51200
	ds_read_b128 v[188:191], v149 offset:52224
	ds_read_b128 v[196:199], v149 offset:53248
	ds_read_b128 v[200:203], v149 offset:54272
	ds_read_b128 v[224:227], v149 offset:55296
	ds_read_b128 v[240:243], v149 offset:56320
	s_barrier
	s_waitcnt lgkmcnt(0)
	s_setprio 1
	s_waitcnt lgkmcnt(0)
	v_mfma_f32_16x16x32_bf16 v[32:35], v[0:3], v[176:179], v[204:207]
	v_mfma_f32_16x16x32_bf16 v[72:75], v[16:19], v[180:183], v[32:35]
	v_mfma_f32_16x16x32_bf16 v[32:35], v[8:11], v[176:179], v[228:231]
	v_mfma_f32_16x16x32_bf16 v[76:79], v[24:27], v[180:183], v[32:35]
	v_mfma_f32_16x16x32_bf16 v[32:35], v[0:3], v[184:187], v[52:55]
	v_mfma_f32_16x16x32_bf16 v[48:51], v[16:19], v[188:191], v[32:35]
	v_mfma_f32_16x16x32_bf16 v[32:35], v[8:11], v[184:187], v[232:235]
	v_mfma_f32_16x16x32_bf16 v[52:55], v[24:27], v[188:191], v[32:35]
	v_mfma_f32_16x16x32_bf16 v[32:35], v[0:3], v[196:199], v[44:47]
	v_mfma_f32_16x16x32_bf16 v[40:43], v[16:19], v[200:203], v[32:35]
	v_mfma_f32_16x16x32_bf16 v[32:35], v[8:11], v[196:199], v[236:239]
	v_mfma_f32_16x16x32_bf16 v[0:3], v[0:3], v[224:227], v[36:39]
	v_mfma_f32_16x16x32_bf16 v[44:47], v[24:27], v[200:203], v[32:35]
	v_mfma_f32_16x16x32_bf16 v[32:35], v[16:19], v[240:243], v[0:3]
	v_mfma_f32_16x16x32_bf16 v[0:3], v[8:11], v[224:227], v[160:163]
	v_mfma_f32_16x16x32_bf16 v[36:39], v[24:27], v[240:243], v[0:3]
	s_setprio 0
	s_setprio 1
	v_mfma_f32_16x16x32_bf16 v[0:3], v[208:211], v[176:179], v[28:31]
	v_mfma_f32_16x16x32_bf16 v[24:27], v[216:219], v[180:183], v[0:3]
	v_mfma_f32_16x16x32_bf16 v[0:3], v[212:215], v[176:179], v[164:167]
	v_mfma_f32_16x16x32_bf16 v[28:31], v[220:223], v[180:183], v[0:3]
	v_mfma_f32_16x16x32_bf16 v[0:3], v[208:211], v[184:187], v[20:23]
	v_mfma_f32_16x16x32_bf16 v[16:19], v[216:219], v[188:191], v[0:3]
	v_mfma_f32_16x16x32_bf16 v[0:3], v[212:215], v[184:187], v[168:171]
	v_mfma_f32_16x16x32_bf16 v[20:23], v[220:223], v[188:191], v[0:3]
	v_mfma_f32_16x16x32_bf16 v[0:3], v[208:211], v[196:199], v[12:15]
	v_mfma_f32_16x16x32_bf16 v[8:11], v[216:219], v[200:203], v[0:3]
	v_mfma_f32_16x16x32_bf16 v[0:3], v[212:215], v[196:199], v[172:175]
	v_mfma_f32_16x16x32_bf16 v[12:15], v[220:223], v[200:203], v[0:3]
	v_mfma_f32_16x16x32_bf16 v[0:3], v[208:211], v[224:227], v[4:7]
	v_mfma_f32_16x16x32_bf16 v[4:7], v[212:215], v[224:227], v[192:195]
	v_mfma_f32_16x16x32_bf16 v[0:3], v[216:219], v[240:243], v[0:3]
	v_mfma_f32_16x16x32_bf16 v[4:7], v[220:223], v[240:243], v[4:7]
	s_setprio 0
	s_barrier
	s_and_saveexec_b64 s[62:63], s[2:3]
	s_cbranch_execz .LBB0_1012
	s_barrier
	s_branch .LBB0_1012

; #define STAGE(P, BASE, br, kt) do { const char* _gb = (const char*)(BASE) + ((size_t)(br) * K + (size_t)(kt) * BK) * 2; \
;     __builtin_amdgcn_global_load_lds((const unsigned*)(_gb + loff0), (unsigned*)((char*)(P) + tid * 16), 16, 0, 0); \
;     __builtin_amdgcn_global_load_lds((const unsigned*)(_gb + (size_t)K * 128 + loff0), (unsigned*)((char*)(P) + tid * 16 + 8192), 16, 0, 0); } while (0)
; #define LDA(dst, b, h) for (int m = 0; m < 4; ++m) { \
;     dst[m][0] = *reinterpret_cast<const bf16x8*>((char*)SA(b, h) + aoff0 + m * 2048); \
;     dst[m][1] = *reinterpret_cast<const bf16x8*>((char*)SA(b, h) + aoff1 + m * 2048); }
; #define LDB(dst, b, h) for (int n = 0; n < 2; ++n) { \
;     dst[n][0] = *reinterpret_cast<const bf16x8*>((char*)SB(b, h) + boff0 + n * 256); \
;     dst[n][1] = *reinterpret_cast<const bf16x8*>((char*)SB(b, h) + boff1 + n * 256); }
; #define MMA(ai, bj, At, Btf) do { __builtin_amdgcn_s_setprio(1); \
;     for (int m = 0; m < 4; ++m) for (int n = 0; n < 2; ++n) for (int k = 0; k < 2; ++k) \
;       acc[ai][bj][m][n] = __builtin_amdgcn_mfma_f32_16x16x32_bf16(Btf[n][k], At[m][k], acc[ai][bj][m][n], 0, 0, 0); \
;     __builtin_amdgcn_s_setprio(0); } while (0)
; #define WAIT_V(n) asm volatile("s_waitcnt vmcnt(" #n ")" ::: "memory")
; #define WAIT_L(n) asm volatile("s_waitcnt lgkmcnt(" #n ")" ::: "memory")
; #define BAR __builtin_amdgcn_s_barrier()
; #define SCHED __builtin_amdgcn_sched_barrier(0)
; template <int EPI> ...
;     ...
;   STAGE(SB(0, 0), Bt, bcol, 0); STAGE(SA(0, 0), A, brow, 0);
;   STAGE(SB(0, 1), Bt, bcol + HALF, 0); STAGE(SA(0, 1), A, brow + HALF, 0);
;   if (wr == 1) BAR;
;   WAIT_V(4); BAR;
;   STAGE(SB(1, 0), Bt, bcol, 1); STAGE(SA(1, 0), A, brow, 1); STAGE(SB(1, 1), Bt, bcol + HALF, 1);
;   WAIT_V(6); BAR;
;   for (int t = 0; t < nt - 2; t += 2) {
;     LDB(B0, 0, 0); SCHED; LDA(At, 0, 0); STAGE(SA(1, 1), A, brow + HALF, t + 1);
;     WAIT_L(8); BAR; WAIT_L(0); MMA(0, 0, At, B0); BAR; SCHED;
;     LDB(B1, 0, 1); STAGE(SB(0, 0), Bt, bcol, t + 2);
;     BAR; WAIT_L(0); MMA(0, 1, At, B1); BAR;
;     LDA(At, 0, 1); STAGE(SA(0, 0), A, brow, t + 2);
;     BAR; WAIT_L(0); MMA(1, 0, At, B0); BAR; SCHED;
;     STAGE(SB(0, 1), Bt, bcol + HALF, t + 2);
;     WAIT_V(6); BAR; MMA(1, 1, At, B1); BAR;
.LBB0_1104:
	s_or_b64 exec, exec, s[70:71]
	v_readfirstlane_b32 s65, v144
	v_lshl_add_u64 v[6:7], v[0:1], 0, s[12:13]
	s_mov_b32 m0, s65
	v_readfirstlane_b32 s65, v145
	s_waitcnt vmcnt(2)
	s_barrier
	global_load_lds_dwordx4 v[6:7], off
	v_lshl_add_u64 v[0:1], v[0:1], 0, s[16:17]
	s_mov_b32 m0, s65
	v_readfirstlane_b32 s65, v146
	global_load_lds_dwordx4 v[0:1], off
	v_lshl_add_u64 v[0:1], v[2:3], 0, s[12:13]
	s_mov_b32 m0, s65
	v_readfirstlane_b32 s65, v147
	global_load_lds_dwordx4 v[0:1], off
	v_lshl_add_u64 v[0:1], v[2:3], 0, s[16:17]
	s_mov_b32 m0, s65
	v_readfirstlane_b32 s65, v148
	global_load_lds_dwordx4 v[0:1], off
	v_lshl_add_u64 v[0:1], v[4:5], 0, s[12:13]
	s_mov_b32 m0, s65
	v_readfirstlane_b32 s65, v149
	global_load_lds_dwordx4 v[0:1], off
	v_lshl_add_u64 v[0:1], v[4:5], 0, s[16:17]
	s_mov_b32 m0, s65
	s_add_u32 s66, s6, s66
	global_load_lds_dwordx4 v[0:1], off
	s_addc_u32 s67, s7, s67
	s_add_u32 s68, s6, s68
	v_mov_b32_e32 v0, 0
	s_addc_u32 s69, s7, s69
	s_mov_b32 s65, -2
	v_mov_b32_e32 v1, v0
	v_mov_b32_e32 v2, v0
	v_mov_b32_e32 v3, v0
	v_mov_b32_e32 v4, v0
	v_mov_b32_e32 v5, v0
	v_mov_b32_e32 v6, v0
	v_mov_b32_e32 v7, v0
	s_waitcnt vmcnt(6)
	s_sub_u32 s98, s68, 0x100
	s_subb_u32 s99, s69, 0
	v_lshl_add_u64 v[228:229], s[98:99], 0, v[130:131]
	s_barrier
.LBB0_1105:
	ds_read_b128 v[162:165], v153
	ds_read_b128 v[166:169], v153 offset:256
	ds_read_b128 v[170:173], v154
	ds_read_b128 v[174:177], v154 offset:256
	v_lshl_add_u64 v[226:227], s[66:67], 0, v[130:131]
	v_readfirstlane_b32 s70, v151
	v_lshl_add_u64 v[210:211], v[226:227], 0, s[18:19]
	s_mov_b32 m0, s70
	v_readfirstlane_b32 s70, v152
	ds_read_b128 v[178:181], v150
	ds_read_b128 v[182:185], v150 offset:1024
	ds_read_b128 v[186:189], v150 offset:2048
	ds_read_b128 v[190:193], v150 offset:3072
	ds_read_b128 v[194:197], v150 offset:4096
	ds_read_b128 v[198:201], v150 offset:5120
	ds_read_b128 v[202:205], v150 offset:6144
	ds_read_b128 v[206:209], v150 offset:7168
	global_load_lds_dwordx4 v[210:211], off
	v_lshl_add_u64 v[210:211], v[226:227], 0, s[20:21]
	s_mov_b32 m0, s70
	s_nop 0
	global_load_lds_dwordx4 v[210:211], off
	s_waitcnt lgkmcnt(8)
	v_readfirstlane_b32 s70, v148
	v_lshl_add_u64 v[246:247], v[228:229], 0, s[56:57]
	s_mov_b32 m0, s70
	v_readfirstlane_b32 s70, v149
	global_load_lds_dwordx4 v[246:247], off
	v_lshl_add_u64 v[246:247], v[228:229], 0, s[58:59]
	s_mov_b32 m0, s70
	s_nop 0
	global_load_lds_dwordx4 v[246:247], off
	ds_read_b128 v[210:213], v155
	ds_read_b128 v[214:217], v155 offset:256
	ds_read_b128 v[218:221], v156
	ds_read_b128 v[222:225], v156 offset:256
	s_barrier
	s_waitcnt lgkmcnt(0)
	s_setprio 1
	s_waitcnt lgkmcnt(0)
	v_mfma_f32_16x16x32_bf16 v[124:127], v[162:165], v[178:181], v[124:127]
	v_mfma_f32_16x16x32_bf16 v[120:123], v[166:169], v[178:181], v[120:123]
	v_mfma_f32_16x16x32_bf16 v[116:119], v[162:165], v[186:189], v[116:119]
	v_mfma_f32_16x16x32_bf16 v[112:115], v[166:169], v[186:189], v[112:115]
	v_mfma_f32_16x16x32_bf16 v[108:111], v[162:165], v[194:197], v[108:111]
	v_mfma_f32_16x16x32_bf16 v[104:107], v[166:169], v[194:197], v[104:107]
	v_mfma_f32_16x16x32_bf16 v[100:103], v[162:165], v[202:205], v[100:103]
	v_mfma_f32_16x16x32_bf16 v[96:99], v[166:169], v[202:205], v[96:99]
	v_mfma_f32_16x16x32_bf16 v[124:127], v[170:173], v[182:185], v[124:127]
	v_mfma_f32_16x16x32_bf16 v[120:123], v[174:177], v[182:185], v[120:123]
	v_mfma_f32_16x16x32_bf16 v[116:119], v[170:173], v[190:193], v[116:119]
	v_mfma_f32_16x16x32_bf16 v[112:115], v[174:177], v[190:193], v[112:115]
	v_mfma_f32_16x16x32_bf16 v[108:111], v[170:173], v[198:201], v[108:111]
	v_mfma_f32_16x16x32_bf16 v[104:107], v[174:177], v[198:201], v[104:107]
	v_mfma_f32_16x16x32_bf16 v[100:103], v[170:173], v[206:209], v[100:103]
	v_mfma_f32_16x16x32_bf16 v[96:99], v[174:177], v[206:209], v[96:99]
	s_setprio 0
	s_waitcnt lgkmcnt(0)
	s_setprio 1
	s_waitcnt lgkmcnt(0)
	v_mfma_f32_16x16x32_bf16 v[92:95], v[210:213], v[178:181], v[92:95]
	v_mfma_f32_16x16x32_bf16 v[88:91], v[214:217], v[178:181], v[88:91]
	v_mfma_f32_16x16x32_bf16 v[84:87], v[210:213], v[186:189], v[84:87]
	v_mfma_f32_16x16x32_bf16 v[80:83], v[214:217], v[186:189], v[80:83]
	v_mfma_f32_16x16x32_bf16 v[76:79], v[210:213], v[194:197], v[76:79]
	v_mfma_f32_16x16x32_bf16 v[72:75], v[214:217], v[194:197], v[72:75]
	v_mfma_f32_16x16x32_bf16 v[68:71], v[210:213], v[202:205], v[68:71]
	v_mfma_f32_16x16x32_bf16 v[64:67], v[214:217], v[202:205], v[64:67]
	v_mfma_f32_16x16x32_bf16 v[92:95], v[218:221], v[182:185], v[92:95]
	v_mfma_f32_16x16x32_bf16 v[88:91], v[222:225], v[182:185], v[88:91]
	v_mfma_f32_16x16x32_bf16 v[84:87], v[218:221], v[190:193], v[84:87]
	v_mfma_f32_16x16x32_bf16 v[80:83], v[222:225], v[190:193], v[80:83]
	v_mfma_f32_16x16x32_bf16 v[76:79], v[218:221], v[198:201], v[76:79]
	v_mfma_f32_16x16x32_bf16 v[72:75], v[222:225], v[198:201], v[72:75]
	v_mfma_f32_16x16x32_bf16 v[68:71], v[218:221], v[206:209], v[68:71]
	v_mfma_f32_16x16x32_bf16 v[64:67], v[222:225], v[206:209], v[64:67]
	s_setprio 0
	s_barrier
	v_lshl_add_u64 v[228:229], s[68:69], 0, v[130:131]
	v_readfirstlane_b32 s70, v136
	v_lshl_add_u64 v[230:231], v[228:229], 0, s[22:23]
	s_mov_b32 m0, s70
	v_readfirstlane_b32 s70, v137
	global_load_lds_dwordx4 v[230:231], off
	v_lshl_add_u64 v[230:231], v[228:229], 0, s[24:25]
	s_mov_b32 m0, s70
	s_nop 0
	global_load_lds_dwordx4 v[230:231], off
	v_readfirstlane_b32 s70, v138
	v_lshl_add_u64 v[230:231], v[226:227], 0, s[26:27]
	s_mov_b32 m0, s70
	v_readfirstlane_b32 s70, v139
	ds_read_b128 v[178:181], v150 offset:16384
	ds_read_b128 v[182:185], v150 offset:17408
	ds_read_b128 v[186:189], v150 offset:18432
	ds_read_b128 v[190:193], v150 offset:19456
	ds_read_b128 v[194:197], v150 offset:20480
	ds_read_b128 v[198:201], v150 offset:21504
	ds_read_b128 v[202:205], v150 offset:22528
	ds_read_b128 v[206:209], v150 offset:23552
	global_load_lds_dwordx4 v[230:231], off
	v_lshl_add_u64 v[230:231], v[226:227], 0, s[28:29]
	s_mov_b32 m0, s70
	s_nop 0
	global_load_lds_dwordx4 v[230:231], off
	s_waitcnt vmcnt(4)
	s_barrier
; #define STAGE(P, BASE, br, kt) do { const char* _gb = (const char*)(BASE) + ((size_t)(br) * K + (size_t)(kt) * BK) * 2; \
;     __builtin_amdgcn_global_load_lds((const unsigned*)(_gb + loff0), (unsigned*)((char*)(P) + tid * 16), 16, 0, 0); \
;     __builtin_amdgcn_global_load_lds((const unsigned*)(_gb + (size_t)K * 128 + loff0), (unsigned*)((char*)(P) + tid * 16 + 8192), 16, 0, 0); } while (0)
; #define LDA(dst, b, h) for (int m = 0; m < 4; ++m) { \
;     dst[m][0] = *reinterpret_cast<const bf16x8*>((char*)SA(b, h) + aoff0 + m * 2048); \
;     dst[m][1] = *reinterpret_cast<const bf16x8*>((char*)SA(b, h) + aoff1 + m * 2048); }
; #define LDB(dst, b, h) for (int n = 0; n < 2; ++n) { \
;     dst[n][0] = *reinterpret_cast<const bf16x8*>((char*)SB(b, h) + boff0 + n * 256); \
;     dst[n][1] = *reinterpret_cast<const bf16x8*>((char*)SB(b, h) + boff1 + n * 256); }
; #define MMA(ai, bj, At, Btf) do { __builtin_amdgcn_s_setprio(1); \
;     for (int m = 0; m < 4; ++m) for (int n = 0; n < 2; ++n) for (int k = 0; k < 2; ++k) \
;       acc[ai][bj][m][n] = __builtin_amdgcn_mfma_f32_16x16x32_bf16(Btf[n][k], At[m][k], acc[ai][bj][m][n], 0, 0, 0); \
;     __builtin_amdgcn_s_setprio(0); } while (0)
; #define WAIT_V(n) asm volatile("s_waitcnt vmcnt(" #n ")" ::: "memory")
; #define WAIT_L(n) asm volatile("s_waitcnt lgkmcnt(" #n ")" ::: "memory")
; #define BAR __builtin_amdgcn_s_barrier()
; #define SCHED __builtin_amdgcn_sched_barrier(0)
; template <int EPI> ...
;     ...
;     BAR; WAIT_L(0); MMA(1, 0, At, B0); BAR; SCHED;
;     STAGE(SB(0, 1), Bt, bcol + HALF, t + 2);
;     WAIT_V(6); BAR; MMA(1, 1, At, B1); BAR;
;     LDB(B0, 1, 0); SCHED; LDA(At, 1, 0); STAGE(SA(0, 1), A, brow + HALF, t + 2);
;     WAIT_L(8); BAR; WAIT_L(0); MMA(0, 0, At, B0); BAR; SCHED;
;     LDB(B1, 1, 1); STAGE(SB(1, 0), Bt, bcol, t + 3);
;     BAR; WAIT_L(0); MMA(0, 1, At, B1); BAR;
	s_waitcnt lgkmcnt(0)
	s_setprio 1
	s_waitcnt lgkmcnt(0)
	v_mfma_f32_16x16x32_bf16 v[60:63], v[162:165], v[178:181], v[60:63]
	v_mfma_f32_16x16x32_bf16 v[56:59], v[166:169], v[178:181], v[56:59]
	v_mfma_f32_16x16x32_bf16 v[52:55], v[162:165], v[186:189], v[52:55]
	v_mfma_f32_16x16x32_bf16 v[48:51], v[166:169], v[186:189], v[48:51]
	v_mfma_f32_16x16x32_bf16 v[44:47], v[162:165], v[194:197], v[44:47]
	v_mfma_f32_16x16x32_bf16 v[40:43], v[166:169], v[194:197], v[40:43]
	v_mfma_f32_16x16x32_bf16 v[36:39], v[162:165], v[202:205], v[36:39]
	v_mfma_f32_16x16x32_bf16 v[32:35], v[166:169], v[202:205], v[32:35]
	v_mfma_f32_16x16x32_bf16 v[60:63], v[170:173], v[182:185], v[60:63]
	v_mfma_f32_16x16x32_bf16 v[56:59], v[174:177], v[182:185], v[56:59]
	v_mfma_f32_16x16x32_bf16 v[52:55], v[170:173], v[190:193], v[52:55]
	v_mfma_f32_16x16x32_bf16 v[48:51], v[174:177], v[190:193], v[48:51]
	v_mfma_f32_16x16x32_bf16 v[44:47], v[170:173], v[198:201], v[44:47]
	v_mfma_f32_16x16x32_bf16 v[40:43], v[174:177], v[198:201], v[40:43]
	v_mfma_f32_16x16x32_bf16 v[36:39], v[170:173], v[206:209], v[36:39]
	v_mfma_f32_16x16x32_bf16 v[32:35], v[174:177], v[206:209], v[32:35]
	s_setprio 0
	s_setprio 1
	v_mfma_f32_16x16x32_bf16 v[28:31], v[210:213], v[178:181], v[28:31]
	v_mfma_f32_16x16x32_bf16 v[24:27], v[214:217], v[178:181], v[24:27]
	v_mfma_f32_16x16x32_bf16 v[20:23], v[210:213], v[186:189], v[20:23]
	v_mfma_f32_16x16x32_bf16 v[16:19], v[214:217], v[186:189], v[16:19]
	v_mfma_f32_16x16x32_bf16 v[12:15], v[210:213], v[194:197], v[12:15]
	v_mfma_f32_16x16x32_bf16 v[8:11], v[214:217], v[194:197], v[8:11]
	v_mfma_f32_16x16x32_bf16 v[4:7], v[210:213], v[202:205], v[4:7]
	v_mfma_f32_16x16x32_bf16 v[0:3], v[214:217], v[202:205], v[0:3]
	v_mfma_f32_16x16x32_bf16 v[28:31], v[218:221], v[182:185], v[28:31]
	v_mfma_f32_16x16x32_bf16 v[24:27], v[222:225], v[182:185], v[24:27]
	v_mfma_f32_16x16x32_bf16 v[20:23], v[218:221], v[190:193], v[20:23]
	v_mfma_f32_16x16x32_bf16 v[16:19], v[222:225], v[190:193], v[16:19]
	v_mfma_f32_16x16x32_bf16 v[12:15], v[218:221], v[198:201], v[12:15]
	v_mfma_f32_16x16x32_bf16 v[8:11], v[222:225], v[198:201], v[8:11]
	v_mfma_f32_16x16x32_bf16 v[4:7], v[218:221], v[206:209], v[4:7]
	v_mfma_f32_16x16x32_bf16 v[0:3], v[222:225], v[206:209], v[0:3]
	s_setprio 0
	s_barrier
	ds_read_b128 v[162:165], v157
	ds_read_b128 v[166:169], v157 offset:256
	ds_read_b128 v[170:173], v158
	ds_read_b128 v[174:177], v158 offset:256
	v_readfirstlane_b32 s70, v142
	v_lshl_add_u64 v[210:211], v[226:227], 0, s[38:39]
	s_mov_b32 m0, s70
	v_readfirstlane_b32 s70, v143
	ds_read_b128 v[178:181], v150 offset:32768
	ds_read_b128 v[182:185], v150 offset:33792
	ds_read_b128 v[186:189], v150 offset:34816
	ds_read_b128 v[190:193], v150 offset:35840
	ds_read_b128 v[194:197], v150 offset:36864
	ds_read_b128 v[198:201], v150 offset:37888
	ds_read_b128 v[202:205], v150 offset:38912
	ds_read_b128 v[206:209], v150 offset:39936
	global_load_lds_dwordx4 v[210:211], off
	v_lshl_add_u64 v[210:211], v[226:227], 0, s[46:47]
	s_mov_b32 m0, s70
	s_nop 0
	global_load_lds_dwordx4 v[210:211], off
	s_waitcnt lgkmcnt(8)
	v_readfirstlane_b32 s70, v140
	v_lshl_add_u64 v[246:247], v[228:229], 0, s[30:31]
	s_mov_b32 m0, s70
	v_readfirstlane_b32 s70, v141
	global_load_lds_dwordx4 v[246:247], off
	v_lshl_add_u64 v[246:247], v[228:229], 0, s[36:37]
	s_mov_b32 m0, s70
	s_nop 0
	global_load_lds_dwordx4 v[246:247], off
	ds_read_b128 v[210:213], v159
	ds_read_b128 v[214:217], v159 offset:256
	ds_read_b128 v[218:221], v160
	ds_read_b128 v[222:225], v160 offset:256
	s_barrier
	s_waitcnt lgkmcnt(0)
	s_setprio 1
	s_waitcnt lgkmcnt(0)
	v_mfma_f32_16x16x32_bf16 v[124:127], v[162:165], v[178:181], v[124:127]
	v_mfma_f32_16x16x32_bf16 v[120:123], v[166:169], v[178:181], v[120:123]
	v_mfma_f32_16x16x32_bf16 v[116:119], v[162:165], v[186:189], v[116:119]
	v_mfma_f32_16x16x32_bf16 v[112:115], v[166:169], v[186:189], v[112:115]
	v_mfma_f32_16x16x32_bf16 v[108:111], v[162:165], v[194:197], v[108:111]
	v_mfma_f32_16x16x32_bf16 v[104:107], v[166:169], v[194:197], v[104:107]
	v_mfma_f32_16x16x32_bf16 v[100:103], v[162:165], v[202:205], v[100:103]
	v_mfma_f32_16x16x32_bf16 v[96:99], v[166:169], v[202:205], v[96:99]
	v_mfma_f32_16x16x32_bf16 v[124:127], v[170:173], v[182:185], v[124:127]
	v_mfma_f32_16x16x32_bf16 v[120:123], v[174:177], v[182:185], v[120:123]
	v_mfma_f32_16x16x32_bf16 v[116:119], v[170:173], v[190:193], v[116:119]
	v_mfma_f32_16x16x32_bf16 v[112:115], v[174:177], v[190:193], v[112:115]
	v_mfma_f32_16x16x32_bf16 v[108:111], v[170:173], v[198:201], v[108:111]
	v_mfma_f32_16x16x32_bf16 v[104:107], v[174:177], v[198:201], v[104:107]
	v_mfma_f32_16x16x32_bf16 v[100:103], v[170:173], v[206:209], v[100:103]
	v_mfma_f32_16x16x32_bf16 v[96:99], v[174:177], v[206:209], v[96:99]
	s_setprio 0
	s_waitcnt lgkmcnt(0)
	s_setprio 1
	s_waitcnt lgkmcnt(0)
	v_mfma_f32_16x16x32_bf16 v[92:95], v[210:213], v[178:181], v[92:95]
	v_mfma_f32_16x16x32_bf16 v[88:91], v[214:217], v[178:181], v[88:91]
	v_mfma_f32_16x16x32_bf16 v[84:87], v[210:213], v[186:189], v[84:87]
	v_mfma_f32_16x16x32_bf16 v[80:83], v[214:217], v[186:189], v[80:83]
	v_mfma_f32_16x16x32_bf16 v[76:79], v[210:213], v[194:197], v[76:79]
	v_mfma_f32_16x16x32_bf16 v[72:75], v[214:217], v[194:197], v[72:75]
	v_mfma_f32_16x16x32_bf16 v[68:71], v[210:213], v[202:205], v[68:71]
	v_mfma_f32_16x16x32_bf16 v[64:67], v[214:217], v[202:205], v[64:67]
	v_mfma_f32_16x16x32_bf16 v[92:95], v[218:221], v[182:185], v[92:95]
	v_mfma_f32_16x16x32_bf16 v[88:91], v[222:225], v[182:185], v[88:91]
	v_mfma_f32_16x16x32_bf16 v[84:87], v[218:221], v[190:193], v[84:87]
	v_mfma_f32_16x16x32_bf16 v[80:83], v[222:225], v[190:193], v[80:83]
	v_mfma_f32_16x16x32_bf16 v[76:79], v[218:221], v[198:201], v[76:79]
	v_mfma_f32_16x16x32_bf16 v[72:75], v[222:225], v[198:201], v[72:75]
	v_mfma_f32_16x16x32_bf16 v[68:71], v[218:221], v[206:209], v[68:71]
	v_mfma_f32_16x16x32_bf16 v[64:67], v[222:225], v[206:209], v[64:67]
	s_setprio 0
	s_barrier
; #define STAGE(P, BASE, br, kt) do { const char* _gb = (const char*)(BASE) + ((size_t)(br) * K + (size_t)(kt) * BK) * 2; \
;     __builtin_amdgcn_global_load_lds((const unsigned*)(_gb + loff0), (unsigned*)((char*)(P) + tid * 16), 16, 0, 0); \
;     __builtin_amdgcn_global_load_lds((const unsigned*)(_gb + (size_t)K * 128 + loff0), (unsigned*)((char*)(P) + tid * 16 + 8192), 16, 0, 0); } while (0)
; #define LDA(dst, b, h) for (int m = 0; m < 4; ++m) { \
;     dst[m][0] = *reinterpret_cast<const bf16x8*>((char*)SA(b, h) + aoff0 + m * 2048); \
;     dst[m][1] = *reinterpret_cast<const bf16x8*>((char*)SA(b, h) + aoff1 + m * 2048); }
; #define LDB(dst, b, h) for (int n = 0; n < 2; ++n) { \
;     dst[n][0] = *reinterpret_cast<const bf16x8*>((char*)SB(b, h) + boff0 + n * 256); \
;     dst[n][1] = *reinterpret_cast<const bf16x8*>((char*)SB(b, h) + boff1 + n * 256); }
; #define MMA(ai, bj, At, Btf) do { __builtin_amdgcn_s_setprio(1); \
;     for (int m = 0; m < 4; ++m) for (int n = 0; n < 2; ++n) for (int k = 0; k < 2; ++k) \
;       acc[ai][bj][m][n] = __builtin_amdgcn_mfma_f32_16x16x32_bf16(Btf[n][k], At[m][k], acc[ai][bj][m][n], 0, 0, 0); \
;     __builtin_amdgcn_s_setprio(0); } while (0)
; #define WAIT_V(n) asm volatile("s_waitcnt vmcnt(" #n ")" ::: "memory")
; #define WAIT_L(n) asm volatile("s_waitcnt lgkmcnt(" #n ")" ::: "memory")
; #define BAR __builtin_amdgcn_s_barrier()
; #define SCHED __builtin_amdgcn_sched_barrier(0)
; template <int EPI> ...
;     ...
;     LDA(At, 1, 1); STAGE(SA(1, 0), A, brow, t + 3);
;     BAR; WAIT_L(0); MMA(1, 0, At, B0); BAR; SCHED;
;     STAGE(SB(1, 1), Bt, bcol + HALF, t + 3);
;     WAIT_V(6); BAR; MMA(1, 1, At, B1); BAR;
;   }
;   { LDB(B0, 0, 0); LDA(At, 0, 0); STAGE(SA(1, 1), A, brow + HALF, nt - 1);
;     BAR; WAIT_L(0); MMA(0, 0, At, B0); BAR;
	v_readfirstlane_b32 s70, v144
	v_lshl_add_u64 v[230:231], v[228:229], 0, s[48:49]
	s_mov_b32 m0, s70
	v_readfirstlane_b32 s70, v145
	global_load_lds_dwordx4 v[230:231], off
	v_lshl_add_u64 v[230:231], v[228:229], 0, s[50:51]
	s_mov_b32 m0, s70
	s_nop 0
	global_load_lds_dwordx4 v[230:231], off
	v_readfirstlane_b32 s70, v146
	v_lshl_add_u64 v[230:231], v[226:227], 0, s[52:53]
	s_mov_b32 m0, s70
	v_readfirstlane_b32 s70, v147
	ds_read_b128 v[178:181], v150 offset:49152
	ds_read_b128 v[182:185], v150 offset:50176
	ds_read_b128 v[186:189], v150 offset:51200
	ds_read_b128 v[190:193], v150 offset:52224
	ds_read_b128 v[194:197], v150 offset:53248
	ds_read_b128 v[198:201], v150 offset:54272
	ds_read_b128 v[202:205], v150 offset:55296
	ds_read_b128 v[206:209], v150 offset:56320
	global_load_lds_dwordx4 v[230:231], off
	v_lshl_add_u64 v[226:227], v[226:227], 0, s[54:55]
	s_mov_b32 m0, s70
	s_nop 0
	global_load_lds_dwordx4 v[226:227], off
	s_waitcnt vmcnt(4)
	s_barrier
	s_waitcnt lgkmcnt(0)
	s_setprio 1
	s_waitcnt lgkmcnt(0)
	v_mfma_f32_16x16x32_bf16 v[60:63], v[162:165], v[178:181], v[60:63]
	v_mfma_f32_16x16x32_bf16 v[56:59], v[166:169], v[178:181], v[56:59]
	v_mfma_f32_16x16x32_bf16 v[52:55], v[162:165], v[186:189], v[52:55]
	v_mfma_f32_16x16x32_bf16 v[48:51], v[166:169], v[186:189], v[48:51]
	v_mfma_f32_16x16x32_bf16 v[44:47], v[162:165], v[194:197], v[44:47]
	v_mfma_f32_16x16x32_bf16 v[40:43], v[166:169], v[194:197], v[40:43]
	v_mfma_f32_16x16x32_bf16 v[36:39], v[162:165], v[202:205], v[36:39]
	v_mfma_f32_16x16x32_bf16 v[32:35], v[166:169], v[202:205], v[32:35]
	v_mfma_f32_16x16x32_bf16 v[60:63], v[170:173], v[182:185], v[60:63]
	v_mfma_f32_16x16x32_bf16 v[56:59], v[174:177], v[182:185], v[56:59]
	v_mfma_f32_16x16x32_bf16 v[52:55], v[170:173], v[190:193], v[52:55]
	v_mfma_f32_16x16x32_bf16 v[48:51], v[174:177], v[190:193], v[48:51]
	v_mfma_f32_16x16x32_bf16 v[44:47], v[170:173], v[198:201], v[44:47]
	v_mfma_f32_16x16x32_bf16 v[40:43], v[174:177], v[198:201], v[40:43]
	v_mfma_f32_16x16x32_bf16 v[36:39], v[170:173], v[206:209], v[36:39]
	v_mfma_f32_16x16x32_bf16 v[32:35], v[174:177], v[206:209], v[32:35]
	s_setprio 0
	s_setprio 1
	v_mfma_f32_16x16x32_bf16 v[28:31], v[210:213], v[178:181], v[28:31]
	v_mfma_f32_16x16x32_bf16 v[24:27], v[214:217], v[178:181], v[24:27]
	v_mfma_f32_16x16x32_bf16 v[20:23], v[210:213], v[186:189], v[20:23]
	v_mfma_f32_16x16x32_bf16 v[16:19], v[214:217], v[186:189], v[16:19]
	v_mfma_f32_16x16x32_bf16 v[12:15], v[210:213], v[194:197], v[12:15]
	v_mfma_f32_16x16x32_bf16 v[8:11], v[214:217], v[194:197], v[8:11]
	v_mfma_f32_16x16x32_bf16 v[4:7], v[210:213], v[202:205], v[4:7]
	v_mfma_f32_16x16x32_bf16 v[0:3], v[214:217], v[202:205], v[0:3]
	v_mfma_f32_16x16x32_bf16 v[28:31], v[218:221], v[182:185], v[28:31]
	v_mfma_f32_16x16x32_bf16 v[24:27], v[222:225], v[182:185], v[24:27]
	v_mfma_f32_16x16x32_bf16 v[20:23], v[218:221], v[190:193], v[20:23]
	v_mfma_f32_16x16x32_bf16 v[16:19], v[222:225], v[190:193], v[16:19]
	v_mfma_f32_16x16x32_bf16 v[12:15], v[218:221], v[198:201], v[12:15]
	v_mfma_f32_16x16x32_bf16 v[8:11], v[222:225], v[198:201], v[8:11]
	v_mfma_f32_16x16x32_bf16 v[4:7], v[218:221], v[206:209], v[4:7]
	v_mfma_f32_16x16x32_bf16 v[0:3], v[222:225], v[206:209], v[0:3]
	s_setprio 0
	s_add_i32 s65, s65, 2
	s_add_u32 s66, s66, 0x100
	s_addc_u32 s67, s67, 0
	s_add_u32 s68, s68, 0x100
	s_addc_u32 s69, s69, 0
	s_cmp_lt_u32 s65, 28
	s_barrier
	s_cbranch_scc1 .LBB0_1105
	v_readfirstlane_b32 s70, v148
	v_lshl_add_u64 v[246:247], v[228:229], 0, s[56:57]
	s_mov_b32 m0, s70
	v_readfirstlane_b32 s70, v149
	global_load_lds_dwordx4 v[246:247], off
	v_lshl_add_u64 v[246:247], v[228:229], 0, s[58:59]
	s_mov_b32 m0, s70
	s_nop 0
	global_load_lds_dwordx4 v[246:247], off
	v_readfirstlane_b32 s65, v151
	v_lshl_add_u64 v[210:211], v[132:133], 0, s[60:61]
	s_mov_b32 m0, s65
	v_readfirstlane_b32 s65, v152
	ds_read_b128 v[162:165], v153
	ds_read_b128 v[166:169], v153 offset:256
	ds_read_b128 v[170:173], v154
	ds_read_b128 v[174:177], v154 offset:256
	ds_read_b128 v[178:181], v150
	ds_read_b128 v[182:185], v150 offset:1024
	ds_read_b128 v[186:189], v150 offset:2048
	ds_read_b128 v[190:193], v150 offset:3072
	ds_read_b128 v[194:197], v150 offset:4096
	ds_read_b128 v[198:201], v150 offset:5120
	ds_read_b128 v[202:205], v150 offset:6144
	ds_read_b128 v[206:209], v150 offset:7168
	global_load_lds_dwordx4 v[210:211], off
	v_lshl_add_u64 v[132:133], v[132:133], 0, s[62:63]
	s_mov_b32 m0, s65
	s_nop 0
	global_load_lds_dwordx4 v[132:133], off
	s_barrier
	s_waitcnt lgkmcnt(0)
	s_setprio 1
	s_waitcnt lgkmcnt(0)
	v_mfma_f32_16x16x32_bf16 v[124:127], v[162:165], v[178:181], v[124:127]
	v_mfma_f32_16x16x32_bf16 v[116:119], v[162:165], v[186:189], v[116:119]
	v_mfma_f32_16x16x32_bf16 v[108:111], v[162:165], v[194:197], v[108:111]
	v_mfma_f32_16x16x32_bf16 v[100:103], v[162:165], v[202:205], v[100:103]
	v_mfma_f32_16x16x32_bf16 v[124:127], v[170:173], v[182:185], v[124:127]
	v_mfma_f32_16x16x32_bf16 v[120:123], v[166:169], v[178:181], v[120:123]
	v_mfma_f32_16x16x32_bf16 v[116:119], v[170:173], v[190:193], v[116:119]
	v_mfma_f32_16x16x32_bf16 v[112:115], v[166:169], v[186:189], v[112:115]
	v_mfma_f32_16x16x32_bf16 v[108:111], v[170:173], v[198:201], v[108:111]
	v_mfma_f32_16x16x32_bf16 v[104:107], v[166:169], v[194:197], v[104:107]
	v_mfma_f32_16x16x32_bf16 v[100:103], v[170:173], v[206:209], v[100:103]
	v_mfma_f32_16x16x32_bf16 v[96:99], v[166:169], v[202:205], v[96:99]
	v_mfma_f32_16x16x32_bf16 v[210:213], v[174:177], v[182:185], v[120:123]
	v_mfma_f32_16x16x32_bf16 v[214:217], v[174:177], v[190:193], v[112:115]
	v_mfma_f32_16x16x32_bf16 v[218:221], v[174:177], v[198:201], v[104:107]
	v_mfma_f32_16x16x32_bf16 v[222:225], v[174:177], v[206:209], v[96:99]
	s_setprio 0
	s_barrier
; #define LDA(dst, b, h) for (int m = 0; m < 4; ++m) { \
;     dst[m][0] = *reinterpret_cast<const bf16x8*>((char*)SA(b, h) + aoff0 + m * 2048); \
;     dst[m][1] = *reinterpret_cast<const bf16x8*>((char*)SA(b, h) + aoff1 + m * 2048); }
; #define LDB(dst, b, h) for (int n = 0; n < 2; ++n) { \
;     dst[n][0] = *reinterpret_cast<const bf16x8*>((char*)SB(b, h) + boff0 + n * 256); \
;     dst[n][1] = *reinterpret_cast<const bf16x8*>((char*)SB(b, h) + boff1 + n * 256); }
; #define MMA(ai, bj, At, Btf) do { __builtin_amdgcn_s_setprio(1); \
;     for (int m = 0; m < 4; ++m) for (int n = 0; n < 2; ++n) for (int k = 0; k < 2; ++k) \
;       acc[ai][bj][m][n] = __builtin_amdgcn_mfma_f32_16x16x32_bf16(Btf[n][k], At[m][k], acc[ai][bj][m][n], 0, 0, 0); \
;     __builtin_amdgcn_s_setprio(0); } while (0)
; #define WAIT_V(n) asm volatile("s_waitcnt vmcnt(" #n ")" ::: "memory")
; #define WAIT_L(n) asm volatile("s_waitcnt lgkmcnt(" #n ")" ::: "memory")
; #define BAR __builtin_amdgcn_s_barrier()
; template <int EPI> ...
;     ...
;     BAR; WAIT_L(0); MMA(0, 0, At, B0); BAR;
;     LDB(B1, 0, 1); BAR; WAIT_L(0); MMA(0, 1, At, B1); BAR;
;     LDA(At, 0, 1); WAIT_V(4); BAR; WAIT_L(0); MMA(1, 0, At, B0); MMA(1, 1, At, B1); BAR; }
;   { LDB(B0, 1, 0); LDA(At, 1, 0); WAIT_V(2); BAR; WAIT_L(0); MMA(0, 0, At, B0); BAR;
	s_nop 1
	ds_read_b128 v[96:99], v155
	ds_read_b128 v[104:107], v155 offset:256
	ds_read_b128 v[112:115], v156
	ds_read_b128 v[120:123], v156 offset:256
	s_barrier
	s_waitcnt lgkmcnt(0)
	s_setprio 1
	s_waitcnt lgkmcnt(0)
	v_mfma_f32_16x16x32_bf16 v[92:95], v[96:99], v[178:181], v[92:95]
	v_mfma_f32_16x16x32_bf16 v[84:87], v[96:99], v[186:189], v[84:87]
	v_mfma_f32_16x16x32_bf16 v[76:79], v[96:99], v[194:197], v[76:79]
	v_mfma_f32_16x16x32_bf16 v[68:71], v[96:99], v[202:205], v[68:71]
	v_mfma_f32_16x16x32_bf16 v[92:95], v[112:115], v[182:185], v[92:95]
	v_mfma_f32_16x16x32_bf16 v[88:91], v[104:107], v[178:181], v[88:91]
	v_mfma_f32_16x16x32_bf16 v[84:87], v[112:115], v[190:193], v[84:87]
	v_mfma_f32_16x16x32_bf16 v[80:83], v[104:107], v[186:189], v[80:83]
	v_mfma_f32_16x16x32_bf16 v[76:79], v[112:115], v[198:201], v[76:79]
	v_mfma_f32_16x16x32_bf16 v[72:75], v[104:107], v[194:197], v[72:75]
	v_mfma_f32_16x16x32_bf16 v[68:71], v[112:115], v[206:209], v[68:71]
	v_mfma_f32_16x16x32_bf16 v[64:67], v[104:107], v[202:205], v[64:67]
	v_mfma_f32_16x16x32_bf16 v[178:181], v[120:123], v[182:185], v[88:91]
	v_mfma_f32_16x16x32_bf16 v[182:185], v[120:123], v[190:193], v[80:83]
	v_mfma_f32_16x16x32_bf16 v[186:189], v[120:123], v[198:201], v[72:75]
	v_mfma_f32_16x16x32_bf16 v[190:193], v[120:123], v[206:209], v[64:67]
	s_setprio 0
	s_barrier
	s_nop 1
	ds_read_b128 v[64:67], v150 offset:16384
	ds_read_b128 v[72:75], v150 offset:17408
	ds_read_b128 v[80:83], v150 offset:18432
	ds_read_b128 v[88:91], v150 offset:19456
	ds_read_b128 v[194:197], v150 offset:20480
	ds_read_b128 v[198:201], v150 offset:21504
	ds_read_b128 v[202:205], v150 offset:22528
	ds_read_b128 v[206:209], v150 offset:23552
	s_waitcnt vmcnt(4)
	s_barrier
	s_waitcnt lgkmcnt(0)
	s_setprio 1
	s_waitcnt lgkmcnt(0)
	v_mfma_f32_16x16x32_bf16 v[60:63], v[162:165], v[64:67], v[60:63]
	v_mfma_f32_16x16x32_bf16 v[56:59], v[166:169], v[64:67], v[56:59]
	v_mfma_f32_16x16x32_bf16 v[52:55], v[162:165], v[80:83], v[52:55]
	v_mfma_f32_16x16x32_bf16 v[40:43], v[166:169], v[194:197], v[40:43]
	v_mfma_f32_16x16x32_bf16 v[36:39], v[162:165], v[202:205], v[36:39]
	v_mfma_f32_16x16x32_bf16 v[60:63], v[170:173], v[72:75], v[60:63]
	v_mfma_f32_16x16x32_bf16 v[56:59], v[174:177], v[72:75], v[56:59]
	v_mfma_f32_16x16x32_bf16 v[52:55], v[170:173], v[88:91], v[52:55]
	v_mfma_f32_16x16x32_bf16 v[48:51], v[166:169], v[80:83], v[48:51]
	v_mfma_f32_16x16x32_bf16 v[44:47], v[162:165], v[194:197], v[44:47]
	v_mfma_f32_16x16x32_bf16 v[40:43], v[174:177], v[198:201], v[40:43]
	v_mfma_f32_16x16x32_bf16 v[36:39], v[170:173], v[206:209], v[36:39]
	v_mfma_f32_16x16x32_bf16 v[32:35], v[166:169], v[202:205], v[32:35]
	v_mfma_f32_16x16x32_bf16 v[226:229], v[174:177], v[88:91], v[48:51]
	v_mfma_f32_16x16x32_bf16 v[230:233], v[170:173], v[198:201], v[44:47]
	v_mfma_f32_16x16x32_bf16 v[162:165], v[174:177], v[206:209], v[32:35]
	s_setprio 0
	s_setprio 1
	v_mfma_f32_16x16x32_bf16 v[24:27], v[104:107], v[64:67], v[24:27]
	v_mfma_f32_16x16x32_bf16 v[20:23], v[96:99], v[80:83], v[20:23]
	v_mfma_f32_16x16x32_bf16 v[8:11], v[104:107], v[194:197], v[8:11]
	v_mfma_f32_16x16x32_bf16 v[4:7], v[96:99], v[202:205], v[4:7]
	v_mfma_f32_16x16x32_bf16 v[28:31], v[96:99], v[64:67], v[28:31]
	v_mfma_f32_16x16x32_bf16 v[24:27], v[120:123], v[72:75], v[24:27]
	v_mfma_f32_16x16x32_bf16 v[20:23], v[112:115], v[88:91], v[20:23]
	v_mfma_f32_16x16x32_bf16 v[16:19], v[104:107], v[80:83], v[16:19]
	v_mfma_f32_16x16x32_bf16 v[12:15], v[96:99], v[194:197], v[12:15]
	v_mfma_f32_16x16x32_bf16 v[8:11], v[120:123], v[198:201], v[8:11]
	v_mfma_f32_16x16x32_bf16 v[4:7], v[112:115], v[206:209], v[4:7]
	v_mfma_f32_16x16x32_bf16 v[0:3], v[104:107], v[202:205], v[0:3]
	v_mfma_f32_16x16x32_bf16 v[166:169], v[112:115], v[72:75], v[28:31]
	v_mfma_f32_16x16x32_bf16 v[170:173], v[120:123], v[88:91], v[16:19]
	v_mfma_f32_16x16x32_bf16 v[174:177], v[112:115], v[198:201], v[12:15]
	v_mfma_f32_16x16x32_bf16 v[194:197], v[120:123], v[206:209], v[0:3]
	s_setprio 0
	s_barrier
	s_nop 1
	ds_read_b128 v[0:3], v157
	ds_read_b128 v[198:201], v157 offset:256
	ds_read_b128 v[12:15], v158
	ds_read_b128 v[202:205], v158 offset:256
	ds_read_b128 v[16:19], v150 offset:32768
	ds_read_b128 v[28:31], v150 offset:33792
	ds_read_b128 v[32:35], v150 offset:34816
	ds_read_b128 v[44:47], v150 offset:35840
	ds_read_b128 v[48:51], v150 offset:36864
	ds_read_b128 v[206:209], v150 offset:37888
	ds_read_b128 v[234:237], v150 offset:38912
	ds_read_b128 v[238:241], v150 offset:39936
	s_waitcnt vmcnt(2)
	s_barrier
; #define LDA(dst, b, h) for (int m = 0; m < 4; ++m) { \
;     dst[m][0] = *reinterpret_cast<const bf16x8*>((char*)SA(b, h) + aoff0 + m * 2048); \
;     dst[m][1] = *reinterpret_cast<const bf16x8*>((char*)SA(b, h) + aoff1 + m * 2048); }
; #define LDB(dst, b, h) for (int n = 0; n < 2; ++n) { \
;     dst[n][0] = *reinterpret_cast<const bf16x8*>((char*)SB(b, h) + boff0 + n * 256); \
;     dst[n][1] = *reinterpret_cast<const bf16x8*>((char*)SB(b, h) + boff1 + n * 256); }
; #define MMA(ai, bj, At, Btf) do { __builtin_amdgcn_s_setprio(1); \
;     for (int m = 0; m < 4; ++m) for (int n = 0; n < 2; ++n) for (int k = 0; k < 2; ++k) \
;       acc[ai][bj][m][n] = __builtin_amdgcn_mfma_f32_16x16x32_bf16(Btf[n][k], At[m][k], acc[ai][bj][m][n], 0, 0, 0); \
;     __builtin_amdgcn_s_setprio(0); } while (0)
; #define WAIT_V(n) asm volatile("s_waitcnt vmcnt(" #n ")" ::: "memory")
; #define WAIT_L(n) asm volatile("s_waitcnt lgkmcnt(" #n ")" ::: "memory")
; #define BAR __builtin_amdgcn_s_barrier()
; template <int EPI> ...
;     ...
;   { LDB(B0, 1, 0); LDA(At, 1, 0); WAIT_V(2); BAR; WAIT_L(0); MMA(0, 0, At, B0); BAR;
;     LDB(B1, 1, 1); WAIT_V(0); BAR; WAIT_L(0); MMA(0, 1, At, B1); BAR;
;     LDA(At, 1, 1); BAR; WAIT_L(0); MMA(1, 0, At, B0); MMA(1, 1, At, B1); BAR; }
;   if (wr == 0) BAR;
	s_waitcnt lgkmcnt(0)
	s_setprio 1
	s_waitcnt lgkmcnt(0)
	v_mfma_f32_16x16x32_bf16 v[64:67], v[0:3], v[16:19], v[124:127]
	v_mfma_f32_16x16x32_bf16 v[120:123], v[12:15], v[28:31], v[64:67]
	v_mfma_f32_16x16x32_bf16 v[64:67], v[198:201], v[16:19], v[210:213]
	v_mfma_f32_16x16x32_bf16 v[112:115], v[202:205], v[28:31], v[64:67]
	v_mfma_f32_16x16x32_bf16 v[64:67], v[0:3], v[32:35], v[116:119]
	v_mfma_f32_16x16x32_bf16 v[104:107], v[12:15], v[44:47], v[64:67]
	v_mfma_f32_16x16x32_bf16 v[64:67], v[198:201], v[32:35], v[214:217]
	v_mfma_f32_16x16x32_bf16 v[96:99], v[202:205], v[44:47], v[64:67]
	v_mfma_f32_16x16x32_bf16 v[64:67], v[0:3], v[48:51], v[108:111]
	v_mfma_f32_16x16x32_bf16 v[88:91], v[12:15], v[206:209], v[64:67]
	v_mfma_f32_16x16x32_bf16 v[64:67], v[198:201], v[48:51], v[218:221]
	v_mfma_f32_16x16x32_bf16 v[80:83], v[202:205], v[206:209], v[64:67]
	v_mfma_f32_16x16x32_bf16 v[64:67], v[0:3], v[234:237], v[100:103]
	v_mfma_f32_16x16x32_bf16 v[72:75], v[12:15], v[238:241], v[64:67]
	v_mfma_f32_16x16x32_bf16 v[64:67], v[198:201], v[234:237], v[222:225]
	v_mfma_f32_16x16x32_bf16 v[64:67], v[202:205], v[238:241], v[64:67]
	s_setprio 0
	s_barrier
	ds_read_b128 v[210:213], v159
	ds_read_b128 v[214:217], v159 offset:256
	ds_read_b128 v[218:221], v160
	ds_read_b128 v[222:225], v160 offset:256
	s_waitcnt vmcnt(0)
	s_barrier
	s_waitcnt lgkmcnt(0)
	s_setprio 1
	s_waitcnt lgkmcnt(0)
	v_mfma_f32_16x16x32_bf16 v[92:95], v[210:213], v[16:19], v[92:95]
	v_mfma_f32_16x16x32_bf16 v[16:19], v[214:217], v[16:19], v[178:181]
	v_mfma_f32_16x16x32_bf16 v[116:119], v[222:225], v[28:31], v[16:19]
	v_mfma_f32_16x16x32_bf16 v[16:19], v[210:213], v[32:35], v[84:87]
	v_mfma_f32_16x16x32_bf16 v[108:111], v[218:221], v[44:47], v[16:19]
	v_mfma_f32_16x16x32_bf16 v[16:19], v[214:217], v[32:35], v[182:185]
	v_mfma_f32_16x16x32_bf16 v[100:103], v[222:225], v[44:47], v[16:19]
	v_mfma_f32_16x16x32_bf16 v[16:19], v[210:213], v[48:51], v[76:79]
	v_mfma_f32_16x16x32_bf16 v[124:127], v[218:221], v[28:31], v[92:95]
	v_mfma_f32_16x16x32_bf16 v[92:95], v[218:221], v[206:209], v[16:19]
	v_mfma_f32_16x16x32_bf16 v[16:19], v[214:217], v[48:51], v[186:189]
	v_mfma_f32_16x16x32_bf16 v[84:87], v[222:225], v[206:209], v[16:19]
	v_mfma_f32_16x16x32_bf16 v[16:19], v[210:213], v[234:237], v[68:71]
	v_mfma_f32_16x16x32_bf16 v[76:79], v[218:221], v[238:241], v[16:19]
	v_mfma_f32_16x16x32_bf16 v[16:19], v[214:217], v[234:237], v[190:193]
	v_mfma_f32_16x16x32_bf16 v[68:71], v[222:225], v[238:241], v[16:19]
	s_setprio 0
	s_barrier
	ds_read_b128 v[178:181], v150 offset:49152
	ds_read_b128 v[182:185], v150 offset:50176
	ds_read_b128 v[186:189], v150 offset:51200
	ds_read_b128 v[190:193], v150 offset:52224
	ds_read_b128 v[206:209], v150 offset:53248
	ds_read_b128 v[234:237], v150 offset:54272
	ds_read_b128 v[238:241], v150 offset:55296
	ds_read_b128 v[242:245], v150 offset:56320
	s_barrier
	s_waitcnt lgkmcnt(0)
	s_setprio 1
	s_waitcnt lgkmcnt(0)
	v_mfma_f32_16x16x32_bf16 v[16:19], v[0:3], v[178:181], v[60:63]
	v_mfma_f32_16x16x32_bf16 v[60:63], v[12:15], v[182:185], v[16:19]
	v_mfma_f32_16x16x32_bf16 v[16:19], v[198:201], v[178:181], v[56:59]
	v_mfma_f32_16x16x32_bf16 v[48:51], v[202:205], v[182:185], v[16:19]
	v_mfma_f32_16x16x32_bf16 v[16:19], v[0:3], v[186:189], v[52:55]
	v_mfma_f32_16x16x32_bf16 v[44:47], v[12:15], v[190:193], v[16:19]
	v_mfma_f32_16x16x32_bf16 v[16:19], v[198:201], v[186:189], v[226:229]
	v_mfma_f32_16x16x32_bf16 v[32:35], v[202:205], v[190:193], v[16:19]
	v_mfma_f32_16x16x32_bf16 v[16:19], v[0:3], v[206:209], v[230:233]
	v_mfma_f32_16x16x32_bf16 v[0:3], v[0:3], v[238:241], v[36:39]
	v_mfma_f32_16x16x32_bf16 v[28:31], v[12:15], v[234:237], v[16:19]
	v_mfma_f32_16x16x32_bf16 v[16:19], v[198:201], v[206:209], v[40:43]
	v_mfma_f32_16x16x32_bf16 v[12:15], v[12:15], v[242:245], v[0:3]
	v_mfma_f32_16x16x32_bf16 v[0:3], v[198:201], v[238:241], v[162:165]
	v_mfma_f32_16x16x32_bf16 v[16:19], v[202:205], v[234:237], v[16:19]
	v_mfma_f32_16x16x32_bf16 v[0:3], v[202:205], v[242:245], v[0:3]
	s_setprio 0
	s_setprio 1
	v_mfma_f32_16x16x32_bf16 v[20:23], v[210:213], v[186:189], v[20:23]
	v_mfma_f32_16x16x32_bf16 v[36:39], v[210:213], v[178:181], v[166:169]
	v_mfma_f32_16x16x32_bf16 v[40:43], v[218:221], v[190:193], v[20:23]
	v_mfma_f32_16x16x32_bf16 v[20:23], v[214:217], v[186:189], v[170:173]
	v_mfma_f32_16x16x32_bf16 v[56:59], v[218:221], v[182:185], v[36:39]
	v_mfma_f32_16x16x32_bf16 v[24:27], v[214:217], v[178:181], v[24:27]
	v_mfma_f32_16x16x32_bf16 v[36:39], v[222:225], v[190:193], v[20:23]
	v_mfma_f32_16x16x32_bf16 v[20:23], v[210:213], v[206:209], v[174:177]
	v_mfma_f32_16x16x32_bf16 v[8:11], v[214:217], v[206:209], v[8:11]
	v_mfma_f32_16x16x32_bf16 v[4:7], v[210:213], v[238:241], v[4:7]
	v_mfma_f32_16x16x32_bf16 v[52:55], v[222:225], v[182:185], v[24:27]
	v_mfma_f32_16x16x32_bf16 v[24:27], v[218:221], v[234:237], v[20:23]
	v_mfma_f32_16x16x32_bf16 v[20:23], v[222:225], v[234:237], v[8:11]
	v_mfma_f32_16x16x32_bf16 v[8:11], v[218:221], v[242:245], v[4:7]
	v_mfma_f32_16x16x32_bf16 v[4:7], v[214:217], v[238:241], v[194:197]
	v_mfma_f32_16x16x32_bf16 v[4:7], v[222:225], v[242:245], v[4:7]
	s_setprio 0
	s_barrier
	s_and_saveexec_b64 s[66:67], s[2:3]
	s_cbranch_execz .LBB0_1099
	s_barrier
	s_branch .LBB0_1099

; #define STAGE(P, BASE, br, kt) do { const char* _gb = (const char*)(BASE) + ((size_t)(br) * K + (size_t)(kt) * BK) * 2; \
;     __builtin_amdgcn_global_load_lds((const unsigned*)(_gb + loff0), (unsigned*)((char*)(P) + tid * 16), 16, 0, 0); \
;     __builtin_amdgcn_global_load_lds((const unsigned*)(_gb + (size_t)K * 128 + loff0), (unsigned*)((char*)(P) + tid * 16 + 8192), 16, 0, 0); } while (0)
; #define LDA(dst, b, h) for (int m = 0; m < 4; ++m) { \
;     dst[m][0] = *reinterpret_cast<const bf16x8*>((char*)SA(b, h) + aoff0 + m * 2048); \
;     dst[m][1] = *reinterpret_cast<const bf16x8*>((char*)SA(b, h) + aoff1 + m * 2048); }
; #define LDB(dst, b, h) for (int n = 0; n < 2; ++n) { \
;     dst[n][0] = *reinterpret_cast<const bf16x8*>((char*)SB(b, h) + boff0 + n * 256); \
;     dst[n][1] = *reinterpret_cast<const bf16x8*>((char*)SB(b, h) + boff1 + n * 256); }
; #define MMA(ai, bj, At, Btf) do { __builtin_amdgcn_s_setprio(1); \
;     for (int m = 0; m < 4; ++m) for (int n = 0; n < 2; ++n) for (int k = 0; k < 2; ++k) \
;       acc[ai][bj][m][n] = __builtin_amdgcn_mfma_f32_16x16x32_bf16(Btf[n][k], At[m][k], acc[ai][bj][m][n], 0, 0, 0); \
;     __builtin_amdgcn_s_setprio(0); } while (0)
; #define WAIT_V(n) asm volatile("s_waitcnt vmcnt(" #n ")" ::: "memory")
; #define WAIT_L(n) asm volatile("s_waitcnt lgkmcnt(" #n ")" ::: "memory")
; #define BAR __builtin_amdgcn_s_barrier()
; #define SCHED __builtin_amdgcn_sched_barrier(0)
; template <int EPI> ...
;     ...
;   STAGE(SB(0, 0), Bt, bcol, 0); STAGE(SA(0, 0), A, brow, 0);
;   STAGE(SB(0, 1), Bt, bcol + HALF, 0); STAGE(SA(0, 1), A, brow + HALF, 0);
;   if (wr == 1) BAR;
;   WAIT_V(4); BAR;
;   STAGE(SB(1, 0), Bt, bcol, 1); STAGE(SA(1, 0), A, brow, 1); STAGE(SB(1, 1), Bt, bcol + HALF, 1);
;   WAIT_V(6); BAR;
;   for (int t = 0; t < nt - 2; t += 2) {
;     LDB(B0, 0, 0); SCHED; LDA(At, 0, 0); STAGE(SA(1, 1), A, brow + HALF, t + 1);
;     WAIT_L(8); BAR; WAIT_L(0); MMA(0, 0, At, B0); BAR; SCHED;
;     LDB(B1, 0, 1); STAGE(SB(0, 0), Bt, bcol, t + 2);
;     BAR; WAIT_L(0); MMA(0, 1, At, B1); BAR;
;     LDA(At, 0, 1); STAGE(SA(0, 0), A, brow, t + 2);
;     BAR; WAIT_L(0); MMA(1, 0, At, B0); BAR; SCHED;
;     STAGE(SB(0, 1), Bt, bcol + HALF, t + 2);
;     WAIT_V(6); BAR; MMA(1, 1, At, B1); BAR;
.LBB0_1151:
	s_or_b64 exec, exec, s[62:63]
	v_readfirstlane_b32 s62, v143
	v_lshl_add_u64 v[6:7], v[0:1], 0, s[10:11]
	s_mov_b32 m0, s62
	v_readfirstlane_b32 s62, v144
	s_waitcnt vmcnt(2)
	s_barrier
	global_load_lds_dwordx4 v[6:7], off
	v_lshl_add_u64 v[0:1], v[0:1], 0, s[12:13]
	s_mov_b32 m0, s62
	v_readfirstlane_b32 s62, v145
	global_load_lds_dwordx4 v[0:1], off
	v_lshl_add_u64 v[0:1], v[2:3], 0, s[10:11]
	s_mov_b32 m0, s62
	v_readfirstlane_b32 s62, v146
	global_load_lds_dwordx4 v[0:1], off
	v_lshl_add_u64 v[0:1], v[2:3], 0, s[12:13]
	s_mov_b32 m0, s62
	v_readfirstlane_b32 s62, v147
	global_load_lds_dwordx4 v[0:1], off
	v_lshl_add_u64 v[0:1], v[4:5], 0, s[10:11]
	s_mov_b32 m0, s62
	v_readfirstlane_b32 s62, v148
	global_load_lds_dwordx4 v[0:1], off
	v_lshl_add_u64 v[0:1], v[4:5], 0, s[12:13]
	s_mov_b32 m0, s62
	s_ashr_i32 s59, s58, 31
	global_load_lds_dwordx4 v[0:1], off
	s_add_u32 s60, s6, s60
	s_addc_u32 s61, s7, s61
	s_add_u32 s62, s6, s75
	s_addc_u32 s63, s7, s74
	s_add_u32 s64, s6, s64
	v_mov_b32_e32 v0, 0
	s_addc_u32 s65, s7, s65
	s_mov_b32 s74, -2
	v_mov_b32_e32 v1, v0
	v_mov_b32_e32 v2, v0
	v_mov_b32_e32 v3, v0
	v_mov_b32_e32 v4, v0
	v_mov_b32_e32 v5, v0
	v_mov_b32_e32 v6, v0
	v_mov_b32_e32 v7, v0
	s_waitcnt vmcnt(6)
	s_sub_u32 s98, s60, 0x100
	s_subb_u32 s99, s61, 0
	v_lshl_add_u64 v[228:229], s[98:99], 0, v[132:133]
	s_barrier
.LBB0_1152:
	ds_read_b128 v[160:163], v152
	ds_read_b128 v[164:167], v152 offset:256
	ds_read_b128 v[168:171], v153
	ds_read_b128 v[172:175], v153 offset:256
	v_lshl_add_u64 v[224:225], s[62:63], 0, v[132:133]
	v_readfirstlane_b32 s75, v150
	v_lshl_add_u64 v[208:209], v[224:225], 0, s[16:17]
	s_mov_b32 m0, s75
	v_readfirstlane_b32 s75, v151
	ds_read_b128 v[176:179], v149
	ds_read_b128 v[180:183], v149 offset:1024
	ds_read_b128 v[184:187], v149 offset:2048
	ds_read_b128 v[188:191], v149 offset:3072
	ds_read_b128 v[192:195], v149 offset:4096
	ds_read_b128 v[196:199], v149 offset:5120
	ds_read_b128 v[200:203], v149 offset:6144
	ds_read_b128 v[204:207], v149 offset:7168
	global_load_lds_dwordx4 v[208:209], off
	v_lshl_add_u64 v[208:209], v[224:225], 0, s[18:19]
	s_mov_b32 m0, s75
	s_nop 0
	global_load_lds_dwordx4 v[208:209], off
	s_waitcnt lgkmcnt(8)
	v_readfirstlane_b32 s75, v147
	v_lshl_add_u64 v[246:247], v[228:229], 0, s[54:55]
	s_mov_b32 m0, s75
	v_readfirstlane_b32 s75, v148
	global_load_lds_dwordx4 v[246:247], off
	v_lshl_add_u64 v[246:247], v[228:229], 0, s[56:57]
	s_mov_b32 m0, s75
	s_nop 0
	global_load_lds_dwordx4 v[246:247], off
	ds_read_b128 v[208:211], v154
	ds_read_b128 v[212:215], v154 offset:256
	ds_read_b128 v[216:219], v155
	ds_read_b128 v[220:223], v155 offset:256
	s_barrier
	s_waitcnt lgkmcnt(0)
	s_setprio 1
	s_waitcnt lgkmcnt(0)
	v_mfma_f32_16x16x32_bf16 v[124:127], v[160:163], v[176:179], v[124:127]
	v_mfma_f32_16x16x32_bf16 v[120:123], v[164:167], v[176:179], v[120:123]
	v_mfma_f32_16x16x32_bf16 v[116:119], v[160:163], v[184:187], v[116:119]
	v_mfma_f32_16x16x32_bf16 v[112:115], v[164:167], v[184:187], v[112:115]
	v_mfma_f32_16x16x32_bf16 v[108:111], v[160:163], v[192:195], v[108:111]
	v_mfma_f32_16x16x32_bf16 v[104:107], v[164:167], v[192:195], v[104:107]
	v_mfma_f32_16x16x32_bf16 v[100:103], v[160:163], v[200:203], v[100:103]
	v_mfma_f32_16x16x32_bf16 v[96:99], v[164:167], v[200:203], v[96:99]
	v_mfma_f32_16x16x32_bf16 v[124:127], v[168:171], v[180:183], v[124:127]
	v_mfma_f32_16x16x32_bf16 v[120:123], v[172:175], v[180:183], v[120:123]
	v_mfma_f32_16x16x32_bf16 v[116:119], v[168:171], v[188:191], v[116:119]
	v_mfma_f32_16x16x32_bf16 v[112:115], v[172:175], v[188:191], v[112:115]
	v_mfma_f32_16x16x32_bf16 v[108:111], v[168:171], v[196:199], v[108:111]
	v_mfma_f32_16x16x32_bf16 v[104:107], v[172:175], v[196:199], v[104:107]
	v_mfma_f32_16x16x32_bf16 v[100:103], v[168:171], v[204:207], v[100:103]
	v_mfma_f32_16x16x32_bf16 v[96:99], v[172:175], v[204:207], v[96:99]
	s_setprio 0
	s_waitcnt lgkmcnt(0)
	s_setprio 1
	s_waitcnt lgkmcnt(0)
	v_mfma_f32_16x16x32_bf16 v[92:95], v[208:211], v[176:179], v[92:95]
	v_mfma_f32_16x16x32_bf16 v[88:91], v[212:215], v[176:179], v[88:91]
	v_mfma_f32_16x16x32_bf16 v[84:87], v[208:211], v[184:187], v[84:87]
	v_mfma_f32_16x16x32_bf16 v[80:83], v[212:215], v[184:187], v[80:83]
	v_mfma_f32_16x16x32_bf16 v[76:79], v[208:211], v[192:195], v[76:79]
	v_mfma_f32_16x16x32_bf16 v[72:75], v[212:215], v[192:195], v[72:75]
	v_mfma_f32_16x16x32_bf16 v[68:71], v[208:211], v[200:203], v[68:71]
	v_mfma_f32_16x16x32_bf16 v[64:67], v[212:215], v[200:203], v[64:67]
	v_mfma_f32_16x16x32_bf16 v[92:95], v[216:219], v[180:183], v[92:95]
	v_mfma_f32_16x16x32_bf16 v[88:91], v[220:223], v[180:183], v[88:91]
	v_mfma_f32_16x16x32_bf16 v[84:87], v[216:219], v[188:191], v[84:87]
	v_mfma_f32_16x16x32_bf16 v[80:83], v[220:223], v[188:191], v[80:83]
	v_mfma_f32_16x16x32_bf16 v[76:79], v[216:219], v[196:199], v[76:79]
	v_mfma_f32_16x16x32_bf16 v[72:75], v[220:223], v[196:199], v[72:75]
	v_mfma_f32_16x16x32_bf16 v[68:71], v[216:219], v[204:207], v[68:71]
	v_mfma_f32_16x16x32_bf16 v[64:67], v[220:223], v[204:207], v[64:67]
	s_setprio 0
	s_barrier
	v_lshl_add_u64 v[226:227], s[64:65], 0, v[132:133]
	v_readfirstlane_b32 s75, v135
	v_lshl_add_u64 v[228:229], v[226:227], 0, s[20:21]
	s_mov_b32 m0, s75
	v_readfirstlane_b32 s75, v136
	global_load_lds_dwordx4 v[228:229], off
	v_lshl_add_u64 v[228:229], v[226:227], 0, s[22:23]
	s_mov_b32 m0, s75
	s_nop 0
	global_load_lds_dwordx4 v[228:229], off
	v_readfirstlane_b32 s75, v137
	v_lshl_add_u64 v[228:229], v[224:225], 0, s[24:25]
	s_mov_b32 m0, s75
	v_readfirstlane_b32 s75, v138
	ds_read_b128 v[176:179], v149 offset:16384
	ds_read_b128 v[180:183], v149 offset:17408
	ds_read_b128 v[184:187], v149 offset:18432
	ds_read_b128 v[188:191], v149 offset:19456
	ds_read_b128 v[192:195], v149 offset:20480
	ds_read_b128 v[196:199], v149 offset:21504
	ds_read_b128 v[200:203], v149 offset:22528
	ds_read_b128 v[204:207], v149 offset:23552
	global_load_lds_dwordx4 v[228:229], off
	v_lshl_add_u64 v[228:229], v[224:225], 0, s[26:27]
	s_mov_b32 m0, s75
	s_nop 0
	global_load_lds_dwordx4 v[228:229], off
	s_waitcnt vmcnt(4)
	s_barrier
; #define STAGE(P, BASE, br, kt) do { const char* _gb = (const char*)(BASE) + ((size_t)(br) * K + (size_t)(kt) * BK) * 2; \
;     __builtin_amdgcn_global_load_lds((const unsigned*)(_gb + loff0), (unsigned*)((char*)(P) + tid * 16), 16, 0, 0); \
;     __builtin_amdgcn_global_load_lds((const unsigned*)(_gb + (size_t)K * 128 + loff0), (unsigned*)((char*)(P) + tid * 16 + 8192), 16, 0, 0); } while (0)
; #define LDA(dst, b, h) for (int m = 0; m < 4; ++m) { \
;     dst[m][0] = *reinterpret_cast<const bf16x8*>((char*)SA(b, h) + aoff0 + m * 2048); \
;     dst[m][1] = *reinterpret_cast<const bf16x8*>((char*)SA(b, h) + aoff1 + m * 2048); }
; #define LDB(dst, b, h) for (int n = 0; n < 2; ++n) { \
;     dst[n][0] = *reinterpret_cast<const bf16x8*>((char*)SB(b, h) + boff0 + n * 256); \
;     dst[n][1] = *reinterpret_cast<const bf16x8*>((char*)SB(b, h) + boff1 + n * 256); }
; #define MMA(ai, bj, At, Btf) do { __builtin_amdgcn_s_setprio(1); \
;     for (int m = 0; m < 4; ++m) for (int n = 0; n < 2; ++n) for (int k = 0; k < 2; ++k) \
;       acc[ai][bj][m][n] = __builtin_amdgcn_mfma_f32_16x16x32_bf16(Btf[n][k], At[m][k], acc[ai][bj][m][n], 0, 0, 0); \
;     __builtin_amdgcn_s_setprio(0); } while (0)
; #define WAIT_V(n) asm volatile("s_waitcnt vmcnt(" #n ")" ::: "memory")
; #define WAIT_L(n) asm volatile("s_waitcnt lgkmcnt(" #n ")" ::: "memory")
; #define BAR __builtin_amdgcn_s_barrier()
; #define SCHED __builtin_amdgcn_sched_barrier(0)
; template <int EPI> ...
;     ...
;     BAR; WAIT_L(0); MMA(1, 0, At, B0); BAR; SCHED;
;     STAGE(SB(0, 1), Bt, bcol + HALF, t + 2);
;     WAIT_V(6); BAR; MMA(1, 1, At, B1); BAR;
;     LDB(B0, 1, 0); SCHED; LDA(At, 1, 0); STAGE(SA(0, 1), A, brow + HALF, t + 2);
;     WAIT_L(8); BAR; WAIT_L(0); MMA(0, 0, At, B0); BAR; SCHED;
;     LDB(B1, 1, 1); STAGE(SB(1, 0), Bt, bcol, t + 3);
;     BAR; WAIT_L(0); MMA(0, 1, At, B1); BAR;
	s_waitcnt lgkmcnt(0)
	s_setprio 1
	s_waitcnt lgkmcnt(0)
	v_mfma_f32_16x16x32_bf16 v[60:63], v[160:163], v[176:179], v[60:63]
	v_mfma_f32_16x16x32_bf16 v[56:59], v[164:167], v[176:179], v[56:59]
	v_mfma_f32_16x16x32_bf16 v[52:55], v[160:163], v[184:187], v[52:55]
	v_mfma_f32_16x16x32_bf16 v[48:51], v[164:167], v[184:187], v[48:51]
	v_mfma_f32_16x16x32_bf16 v[44:47], v[160:163], v[192:195], v[44:47]
	v_mfma_f32_16x16x32_bf16 v[40:43], v[164:167], v[192:195], v[40:43]
	v_mfma_f32_16x16x32_bf16 v[36:39], v[160:163], v[200:203], v[36:39]
	v_mfma_f32_16x16x32_bf16 v[32:35], v[164:167], v[200:203], v[32:35]
	v_mfma_f32_16x16x32_bf16 v[60:63], v[168:171], v[180:183], v[60:63]
	v_mfma_f32_16x16x32_bf16 v[56:59], v[172:175], v[180:183], v[56:59]
	v_mfma_f32_16x16x32_bf16 v[52:55], v[168:171], v[188:191], v[52:55]
	v_mfma_f32_16x16x32_bf16 v[48:51], v[172:175], v[188:191], v[48:51]
	v_mfma_f32_16x16x32_bf16 v[44:47], v[168:171], v[196:199], v[44:47]
	v_mfma_f32_16x16x32_bf16 v[40:43], v[172:175], v[196:199], v[40:43]
	v_mfma_f32_16x16x32_bf16 v[36:39], v[168:171], v[204:207], v[36:39]
	v_mfma_f32_16x16x32_bf16 v[32:35], v[172:175], v[204:207], v[32:35]
	s_setprio 0
	s_setprio 1
	v_mfma_f32_16x16x32_bf16 v[28:31], v[208:211], v[176:179], v[28:31]
	v_mfma_f32_16x16x32_bf16 v[24:27], v[212:215], v[176:179], v[24:27]
	v_mfma_f32_16x16x32_bf16 v[20:23], v[208:211], v[184:187], v[20:23]
	v_mfma_f32_16x16x32_bf16 v[16:19], v[212:215], v[184:187], v[16:19]
	v_mfma_f32_16x16x32_bf16 v[12:15], v[208:211], v[192:195], v[12:15]
	v_mfma_f32_16x16x32_bf16 v[8:11], v[212:215], v[192:195], v[8:11]
	v_mfma_f32_16x16x32_bf16 v[4:7], v[208:211], v[200:203], v[4:7]
	v_mfma_f32_16x16x32_bf16 v[0:3], v[212:215], v[200:203], v[0:3]
	v_mfma_f32_16x16x32_bf16 v[28:31], v[216:219], v[180:183], v[28:31]
	v_mfma_f32_16x16x32_bf16 v[24:27], v[220:223], v[180:183], v[24:27]
	v_mfma_f32_16x16x32_bf16 v[20:23], v[216:219], v[188:191], v[20:23]
	v_mfma_f32_16x16x32_bf16 v[16:19], v[220:223], v[188:191], v[16:19]
	v_mfma_f32_16x16x32_bf16 v[12:15], v[216:219], v[196:199], v[12:15]
	v_mfma_f32_16x16x32_bf16 v[8:11], v[220:223], v[196:199], v[8:11]
	v_mfma_f32_16x16x32_bf16 v[4:7], v[216:219], v[204:207], v[4:7]
	v_mfma_f32_16x16x32_bf16 v[0:3], v[220:223], v[204:207], v[0:3]
	s_setprio 0
	s_barrier
	ds_read_b128 v[160:163], v156
	ds_read_b128 v[164:167], v156 offset:256
	ds_read_b128 v[168:171], v157
	ds_read_b128 v[172:175], v157 offset:256
	v_readfirstlane_b32 s75, v141
	v_lshl_add_u64 v[208:209], v[224:225], 0, s[36:37]
	s_mov_b32 m0, s75
	v_readfirstlane_b32 s75, v142
	ds_read_b128 v[176:179], v149 offset:32768
	ds_read_b128 v[180:183], v149 offset:33792
	ds_read_b128 v[184:187], v149 offset:34816
	ds_read_b128 v[188:191], v149 offset:35840
	ds_read_b128 v[192:195], v149 offset:36864
	ds_read_b128 v[196:199], v149 offset:37888
	ds_read_b128 v[200:203], v149 offset:38912
	ds_read_b128 v[204:207], v149 offset:39936
	global_load_lds_dwordx4 v[208:209], off
	v_lshl_add_u64 v[208:209], v[224:225], 0, s[38:39]
	s_mov_b32 m0, s75
	s_nop 0
	global_load_lds_dwordx4 v[208:209], off
	s_waitcnt lgkmcnt(8)
	v_lshl_add_u64 v[228:229], s[60:61], 0, v[132:133]
	v_readfirstlane_b32 s75, v139
	v_lshl_add_u64 v[246:247], v[228:229], 0, s[28:29]
	s_mov_b32 m0, s75
	v_readfirstlane_b32 s75, v140
	global_load_lds_dwordx4 v[246:247], off
	v_lshl_add_u64 v[246:247], v[228:229], 0, s[30:31]
	s_mov_b32 m0, s75
	s_nop 0
	global_load_lds_dwordx4 v[246:247], off
	ds_read_b128 v[208:211], v158
	ds_read_b128 v[212:215], v158 offset:256
	ds_read_b128 v[216:219], v159
	ds_read_b128 v[220:223], v159 offset:256
	s_barrier
	s_waitcnt lgkmcnt(0)
	s_setprio 1
	s_waitcnt lgkmcnt(0)
	v_mfma_f32_16x16x32_bf16 v[124:127], v[160:163], v[176:179], v[124:127]
	v_mfma_f32_16x16x32_bf16 v[120:123], v[164:167], v[176:179], v[120:123]
	v_mfma_f32_16x16x32_bf16 v[116:119], v[160:163], v[184:187], v[116:119]
	v_mfma_f32_16x16x32_bf16 v[112:115], v[164:167], v[184:187], v[112:115]
	v_mfma_f32_16x16x32_bf16 v[108:111], v[160:163], v[192:195], v[108:111]
	v_mfma_f32_16x16x32_bf16 v[104:107], v[164:167], v[192:195], v[104:107]
	v_mfma_f32_16x16x32_bf16 v[100:103], v[160:163], v[200:203], v[100:103]
	v_mfma_f32_16x16x32_bf16 v[96:99], v[164:167], v[200:203], v[96:99]
	v_mfma_f32_16x16x32_bf16 v[124:127], v[168:171], v[180:183], v[124:127]
	v_mfma_f32_16x16x32_bf16 v[120:123], v[172:175], v[180:183], v[120:123]
	v_mfma_f32_16x16x32_bf16 v[116:119], v[168:171], v[188:191], v[116:119]
	v_mfma_f32_16x16x32_bf16 v[112:115], v[172:175], v[188:191], v[112:115]
	v_mfma_f32_16x16x32_bf16 v[108:111], v[168:171], v[196:199], v[108:111]
	v_mfma_f32_16x16x32_bf16 v[104:107], v[172:175], v[196:199], v[104:107]
	v_mfma_f32_16x16x32_bf16 v[100:103], v[168:171], v[204:207], v[100:103]
	v_mfma_f32_16x16x32_bf16 v[96:99], v[172:175], v[204:207], v[96:99]
	s_setprio 0
	s_waitcnt lgkmcnt(0)
	s_setprio 1
	s_waitcnt lgkmcnt(0)
	v_mfma_f32_16x16x32_bf16 v[92:95], v[208:211], v[176:179], v[92:95]
	v_mfma_f32_16x16x32_bf16 v[88:91], v[212:215], v[176:179], v[88:91]
	v_mfma_f32_16x16x32_bf16 v[84:87], v[208:211], v[184:187], v[84:87]
	v_mfma_f32_16x16x32_bf16 v[80:83], v[212:215], v[184:187], v[80:83]
	v_mfma_f32_16x16x32_bf16 v[76:79], v[208:211], v[192:195], v[76:79]
	v_mfma_f32_16x16x32_bf16 v[72:75], v[212:215], v[192:195], v[72:75]
	v_mfma_f32_16x16x32_bf16 v[68:71], v[208:211], v[200:203], v[68:71]
	v_mfma_f32_16x16x32_bf16 v[64:67], v[212:215], v[200:203], v[64:67]
	v_mfma_f32_16x16x32_bf16 v[92:95], v[216:219], v[180:183], v[92:95]
	v_mfma_f32_16x16x32_bf16 v[88:91], v[220:223], v[180:183], v[88:91]
	v_mfma_f32_16x16x32_bf16 v[84:87], v[216:219], v[188:191], v[84:87]
	v_mfma_f32_16x16x32_bf16 v[80:83], v[220:223], v[188:191], v[80:83]
	v_mfma_f32_16x16x32_bf16 v[76:79], v[216:219], v[196:199], v[76:79]
	v_mfma_f32_16x16x32_bf16 v[72:75], v[220:223], v[196:199], v[72:75]
	v_mfma_f32_16x16x32_bf16 v[68:71], v[216:219], v[204:207], v[68:71]
	v_mfma_f32_16x16x32_bf16 v[64:67], v[220:223], v[204:207], v[64:67]
	s_setprio 0
	s_barrier
; #define STAGE(P, BASE, br, kt) do { const char* _gb = (const char*)(BASE) + ((size_t)(br) * K + (size_t)(kt) * BK) * 2; \
;     __builtin_amdgcn_global_load_lds((const unsigned*)(_gb + loff0), (unsigned*)((char*)(P) + tid * 16), 16, 0, 0); \
;     __builtin_amdgcn_global_load_lds((const unsigned*)(_gb + (size_t)K * 128 + loff0), (unsigned*)((char*)(P) + tid * 16 + 8192), 16, 0, 0); } while (0)
; #define LDA(dst, b, h) for (int m = 0; m < 4; ++m) { \
;     dst[m][0] = *reinterpret_cast<const bf16x8*>((char*)SA(b, h) + aoff0 + m * 2048); \
;     dst[m][1] = *reinterpret_cast<const bf16x8*>((char*)SA(b, h) + aoff1 + m * 2048); }
; #define LDB(dst, b, h) for (int n = 0; n < 2; ++n) { \
;     dst[n][0] = *reinterpret_cast<const bf16x8*>((char*)SB(b, h) + boff0 + n * 256); \
;     dst[n][1] = *reinterpret_cast<const bf16x8*>((char*)SB(b, h) + boff1 + n * 256); }
; #define MMA(ai, bj, At, Btf) do { __builtin_amdgcn_s_setprio(1); \
;     for (int m = 0; m < 4; ++m) for (int n = 0; n < 2; ++n) for (int k = 0; k < 2; ++k) \
;       acc[ai][bj][m][n] = __builtin_amdgcn_mfma_f32_16x16x32_bf16(Btf[n][k], At[m][k], acc[ai][bj][m][n], 0, 0, 0); \
;     __builtin_amdgcn_s_setprio(0); } while (0)
; #define WAIT_V(n) asm volatile("s_waitcnt vmcnt(" #n ")" ::: "memory")
; #define WAIT_L(n) asm volatile("s_waitcnt lgkmcnt(" #n ")" ::: "memory")
; #define BAR __builtin_amdgcn_s_barrier()
; #define SCHED __builtin_amdgcn_sched_barrier(0)
; template <int EPI> ...
;     ...
;     LDA(At, 1, 1); STAGE(SA(1, 0), A, brow, t + 3);
;     BAR; WAIT_L(0); MMA(1, 0, At, B0); BAR; SCHED;
;     STAGE(SB(1, 1), Bt, bcol + HALF, t + 3);
;     WAIT_V(6); BAR; MMA(1, 1, At, B1); BAR;
;   }
;   { LDB(B0, 0, 0); LDA(At, 0, 0); STAGE(SA(1, 1), A, brow + HALF, nt - 1);
;     BAR; WAIT_L(0); MMA(0, 0, At, B0); BAR;
	v_readfirstlane_b32 s75, v143
	v_lshl_add_u64 v[230:231], v[226:227], 0, s[46:47]
	s_mov_b32 m0, s75
	v_readfirstlane_b32 s75, v144
	global_load_lds_dwordx4 v[230:231], off
	v_lshl_add_u64 v[226:227], v[226:227], 0, s[48:49]
	s_mov_b32 m0, s75
	s_nop 0
	global_load_lds_dwordx4 v[226:227], off
	v_readfirstlane_b32 s75, v145
	v_lshl_add_u64 v[226:227], v[224:225], 0, s[50:51]
	s_mov_b32 m0, s75
	v_readfirstlane_b32 s75, v146
	ds_read_b128 v[176:179], v149 offset:49152
	ds_read_b128 v[180:183], v149 offset:50176
	ds_read_b128 v[184:187], v149 offset:51200
	ds_read_b128 v[188:191], v149 offset:52224
	ds_read_b128 v[192:195], v149 offset:53248
	ds_read_b128 v[196:199], v149 offset:54272
	ds_read_b128 v[200:203], v149 offset:55296
	ds_read_b128 v[204:207], v149 offset:56320
	global_load_lds_dwordx4 v[226:227], off
	v_lshl_add_u64 v[224:225], v[224:225], 0, s[52:53]
	s_mov_b32 m0, s75
	s_nop 0
	global_load_lds_dwordx4 v[224:225], off
	s_waitcnt vmcnt(4)
	s_barrier
	s_waitcnt lgkmcnt(0)
	s_setprio 1
	s_waitcnt lgkmcnt(0)
	v_mfma_f32_16x16x32_bf16 v[60:63], v[160:163], v[176:179], v[60:63]
	v_mfma_f32_16x16x32_bf16 v[56:59], v[164:167], v[176:179], v[56:59]
	v_mfma_f32_16x16x32_bf16 v[52:55], v[160:163], v[184:187], v[52:55]
	v_mfma_f32_16x16x32_bf16 v[48:51], v[164:167], v[184:187], v[48:51]
	v_mfma_f32_16x16x32_bf16 v[44:47], v[160:163], v[192:195], v[44:47]
	v_mfma_f32_16x16x32_bf16 v[40:43], v[164:167], v[192:195], v[40:43]
	v_mfma_f32_16x16x32_bf16 v[36:39], v[160:163], v[200:203], v[36:39]
	v_mfma_f32_16x16x32_bf16 v[32:35], v[164:167], v[200:203], v[32:35]
	v_mfma_f32_16x16x32_bf16 v[60:63], v[168:171], v[180:183], v[60:63]
	v_mfma_f32_16x16x32_bf16 v[56:59], v[172:175], v[180:183], v[56:59]
	v_mfma_f32_16x16x32_bf16 v[52:55], v[168:171], v[188:191], v[52:55]
	v_mfma_f32_16x16x32_bf16 v[48:51], v[172:175], v[188:191], v[48:51]
	v_mfma_f32_16x16x32_bf16 v[44:47], v[168:171], v[196:199], v[44:47]
	v_mfma_f32_16x16x32_bf16 v[40:43], v[172:175], v[196:199], v[40:43]
	v_mfma_f32_16x16x32_bf16 v[36:39], v[168:171], v[204:207], v[36:39]
	v_mfma_f32_16x16x32_bf16 v[32:35], v[172:175], v[204:207], v[32:35]
	s_setprio 0
	s_setprio 1
	v_mfma_f32_16x16x32_bf16 v[28:31], v[208:211], v[176:179], v[28:31]
	v_mfma_f32_16x16x32_bf16 v[24:27], v[212:215], v[176:179], v[24:27]
	v_mfma_f32_16x16x32_bf16 v[20:23], v[208:211], v[184:187], v[20:23]
	v_mfma_f32_16x16x32_bf16 v[16:19], v[212:215], v[184:187], v[16:19]
	v_mfma_f32_16x16x32_bf16 v[12:15], v[208:211], v[192:195], v[12:15]
	v_mfma_f32_16x16x32_bf16 v[8:11], v[212:215], v[192:195], v[8:11]
	v_mfma_f32_16x16x32_bf16 v[4:7], v[208:211], v[200:203], v[4:7]
	v_mfma_f32_16x16x32_bf16 v[0:3], v[212:215], v[200:203], v[0:3]
	v_mfma_f32_16x16x32_bf16 v[28:31], v[216:219], v[180:183], v[28:31]
	v_mfma_f32_16x16x32_bf16 v[24:27], v[220:223], v[180:183], v[24:27]
	v_mfma_f32_16x16x32_bf16 v[20:23], v[216:219], v[188:191], v[20:23]
	v_mfma_f32_16x16x32_bf16 v[16:19], v[220:223], v[188:191], v[16:19]
	v_mfma_f32_16x16x32_bf16 v[12:15], v[216:219], v[196:199], v[12:15]
	v_mfma_f32_16x16x32_bf16 v[8:11], v[220:223], v[196:199], v[8:11]
	v_mfma_f32_16x16x32_bf16 v[4:7], v[216:219], v[204:207], v[4:7]
	v_mfma_f32_16x16x32_bf16 v[0:3], v[220:223], v[204:207], v[0:3]
	s_setprio 0
	s_add_i32 s74, s74, 2
	s_add_u32 s60, s60, 0x100
	s_addc_u32 s61, s61, 0
	s_add_u32 s62, s62, 0x100
	s_addc_u32 s63, s63, 0
	s_add_u32 s64, s64, 0x100
	s_addc_u32 s65, s65, 0
	s_cmpk_lt_u32 s74, 0x54
	s_barrier
	s_cbranch_scc1 .LBB0_1152
	v_readfirstlane_b32 s75, v147
	v_lshl_add_u64 v[246:247], v[228:229], 0, s[54:55]
	s_mov_b32 m0, s75
	v_readfirstlane_b32 s75, v148
	global_load_lds_dwordx4 v[246:247], off
	v_lshl_add_u64 v[246:247], v[228:229], 0, s[56:57]
	s_mov_b32 m0, s75
	s_nop 0
	global_load_lds_dwordx4 v[246:247], off
	s_add_u32 s60, s68, s73
	s_addc_u32 s61, s69, s72
	v_lshl_add_u64 v[208:209], s[60:61], 0, v[128:129]
	v_readfirstlane_b32 s60, v150
	s_mov_b32 m0, s60
	v_readfirstlane_b32 s60, v151
	ds_read_b128 v[160:163], v152
	ds_read_b128 v[164:167], v152 offset:256
	ds_read_b128 v[168:171], v153
	ds_read_b128 v[172:175], v153 offset:256
	ds_read_b128 v[176:179], v149
	ds_read_b128 v[180:183], v149 offset:1024
	ds_read_b128 v[184:187], v149 offset:2048
	ds_read_b128 v[188:191], v149 offset:3072
	ds_read_b128 v[192:195], v149 offset:4096
	ds_read_b128 v[196:199], v149 offset:5120
	ds_read_b128 v[200:203], v149 offset:6144
	ds_read_b128 v[204:207], v149 offset:7168
	global_load_lds_dwordx4 v[208:209], off
	v_lshl_add_u64 v[208:209], v[208:209], 0, s[8:9]
	s_mov_b32 m0, s60
	s_nop 0
	global_load_lds_dwordx4 v[208:209], off
	s_barrier
	s_waitcnt lgkmcnt(0)
	s_setprio 1
	s_waitcnt lgkmcnt(0)
	v_mfma_f32_16x16x32_bf16 v[124:127], v[160:163], v[176:179], v[124:127]
	v_mfma_f32_16x16x32_bf16 v[116:119], v[160:163], v[184:187], v[116:119]
	v_mfma_f32_16x16x32_bf16 v[108:111], v[160:163], v[192:195], v[108:111]
	v_mfma_f32_16x16x32_bf16 v[100:103], v[160:163], v[200:203], v[100:103]
	v_mfma_f32_16x16x32_bf16 v[96:99], v[164:167], v[200:203], v[96:99]
	v_mfma_f32_16x16x32_bf16 v[124:127], v[168:171], v[180:183], v[124:127]
	v_mfma_f32_16x16x32_bf16 v[120:123], v[164:167], v[176:179], v[120:123]
	v_mfma_f32_16x16x32_bf16 v[116:119], v[168:171], v[188:191], v[116:119]
	v_mfma_f32_16x16x32_bf16 v[112:115], v[164:167], v[184:187], v[112:115]
	v_mfma_f32_16x16x32_bf16 v[108:111], v[168:171], v[196:199], v[108:111]
	v_mfma_f32_16x16x32_bf16 v[104:107], v[164:167], v[192:195], v[104:107]
	v_mfma_f32_16x16x32_bf16 v[100:103], v[168:171], v[204:207], v[100:103]
	v_mfma_f32_16x16x32_bf16 v[96:99], v[172:175], v[204:207], v[96:99]
	v_mfma_f32_16x16x32_bf16 v[208:211], v[172:175], v[180:183], v[120:123]
	v_mfma_f32_16x16x32_bf16 v[212:215], v[172:175], v[188:191], v[112:115]
	v_mfma_f32_16x16x32_bf16 v[216:219], v[172:175], v[196:199], v[104:107]
	s_setprio 0
	s_barrier
; #define LDA(dst, b, h) for (int m = 0; m < 4; ++m) { \
;     dst[m][0] = *reinterpret_cast<const bf16x8*>((char*)SA(b, h) + aoff0 + m * 2048); \
;     dst[m][1] = *reinterpret_cast<const bf16x8*>((char*)SA(b, h) + aoff1 + m * 2048); }
; #define LDB(dst, b, h) for (int n = 0; n < 2; ++n) { \
;     dst[n][0] = *reinterpret_cast<const bf16x8*>((char*)SB(b, h) + boff0 + n * 256); \
;     dst[n][1] = *reinterpret_cast<const bf16x8*>((char*)SB(b, h) + boff1 + n * 256); }
; #define MMA(ai, bj, At, Btf) do { __builtin_amdgcn_s_setprio(1); \
;     for (int m = 0; m < 4; ++m) for (int n = 0; n < 2; ++n) for (int k = 0; k < 2; ++k) \
;       acc[ai][bj][m][n] = __builtin_amdgcn_mfma_f32_16x16x32_bf16(Btf[n][k], At[m][k], acc[ai][bj][m][n], 0, 0, 0); \
;     __builtin_amdgcn_s_setprio(0); } while (0)
; #define WAIT_V(n) asm volatile("s_waitcnt vmcnt(" #n ")" ::: "memory")
; #define WAIT_L(n) asm volatile("s_waitcnt lgkmcnt(" #n ")" ::: "memory")
; #define BAR __builtin_amdgcn_s_barrier()
; template <int EPI> ...
;     ...
;     BAR; WAIT_L(0); MMA(0, 0, At, B0); BAR;
;     LDB(B1, 0, 1); BAR; WAIT_L(0); MMA(0, 1, At, B1); BAR;
;     LDA(At, 0, 1); WAIT_V(4); BAR; WAIT_L(0); MMA(1, 0, At, B0); MMA(1, 1, At, B1); BAR; }
;   { LDB(B0, 1, 0); LDA(At, 1, 0); WAIT_V(2); BAR; WAIT_L(0); MMA(0, 0, At, B0); BAR;
	s_nop 0
	ds_read_b128 v[104:107], v154
	ds_read_b128 v[112:115], v154 offset:256
	ds_read_b128 v[120:123], v155
	ds_read_b128 v[220:223], v155 offset:256
	s_barrier
	s_waitcnt lgkmcnt(0)
	s_setprio 1
	s_waitcnt lgkmcnt(0)
	v_mfma_f32_16x16x32_bf16 v[84:87], v[104:107], v[184:187], v[84:87]
	v_mfma_f32_16x16x32_bf16 v[76:79], v[104:107], v[192:195], v[76:79]
	v_mfma_f32_16x16x32_bf16 v[72:75], v[112:115], v[192:195], v[72:75]
	v_mfma_f32_16x16x32_bf16 v[92:95], v[104:107], v[176:179], v[92:95]
	v_mfma_f32_16x16x32_bf16 v[88:91], v[112:115], v[176:179], v[88:91]
	v_mfma_f32_16x16x32_bf16 v[84:87], v[120:123], v[188:191], v[84:87]
	v_mfma_f32_16x16x32_bf16 v[80:83], v[112:115], v[184:187], v[80:83]
	v_mfma_f32_16x16x32_bf16 v[76:79], v[120:123], v[196:199], v[76:79]
	v_mfma_f32_16x16x32_bf16 v[72:75], v[220:223], v[196:199], v[72:75]
	v_mfma_f32_16x16x32_bf16 v[68:71], v[104:107], v[200:203], v[68:71]
	v_mfma_f32_16x16x32_bf16 v[64:67], v[112:115], v[200:203], v[64:67]
	v_mfma_f32_16x16x32_bf16 v[224:227], v[120:123], v[180:183], v[92:95]
	v_mfma_f32_16x16x32_bf16 v[176:179], v[220:223], v[180:183], v[88:91]
	v_mfma_f32_16x16x32_bf16 v[180:183], v[220:223], v[188:191], v[80:83]
	v_mfma_f32_16x16x32_bf16 v[184:187], v[120:123], v[204:207], v[68:71]
	v_mfma_f32_16x16x32_bf16 v[188:191], v[220:223], v[204:207], v[64:67]
	s_setprio 0
	s_barrier
	s_nop 0
	ds_read_b128 v[64:67], v149 offset:16384
	ds_read_b128 v[68:71], v149 offset:17408
	ds_read_b128 v[80:83], v149 offset:18432
	ds_read_b128 v[88:91], v149 offset:19456
	ds_read_b128 v[92:95], v149 offset:20480
	ds_read_b128 v[192:195], v149 offset:21504
	ds_read_b128 v[196:199], v149 offset:22528
	ds_read_b128 v[200:203], v149 offset:23552
	s_waitcnt vmcnt(4)
	s_barrier
	s_waitcnt lgkmcnt(0)
	s_setprio 1
	s_waitcnt lgkmcnt(0)
	v_mfma_f32_16x16x32_bf16 v[52:55], v[160:163], v[80:83], v[52:55]
	v_mfma_f32_16x16x32_bf16 v[44:47], v[160:163], v[92:95], v[44:47]
	v_mfma_f32_16x16x32_bf16 v[36:39], v[160:163], v[196:199], v[36:39]
	v_mfma_f32_16x16x32_bf16 v[60:63], v[160:163], v[64:67], v[60:63]
	v_mfma_f32_16x16x32_bf16 v[56:59], v[164:167], v[64:67], v[56:59]
	v_mfma_f32_16x16x32_bf16 v[52:55], v[168:171], v[88:91], v[52:55]
	v_mfma_f32_16x16x32_bf16 v[48:51], v[164:167], v[80:83], v[48:51]
	v_mfma_f32_16x16x32_bf16 v[44:47], v[168:171], v[192:195], v[44:47]
	v_mfma_f32_16x16x32_bf16 v[40:43], v[164:167], v[92:95], v[40:43]
	v_mfma_f32_16x16x32_bf16 v[36:39], v[168:171], v[200:203], v[36:39]
	v_mfma_f32_16x16x32_bf16 v[32:35], v[164:167], v[196:199], v[32:35]
	v_mfma_f32_16x16x32_bf16 v[204:207], v[168:171], v[68:71], v[60:63]
	v_mfma_f32_16x16x32_bf16 v[228:231], v[172:175], v[68:71], v[56:59]
	v_mfma_f32_16x16x32_bf16 v[232:235], v[172:175], v[88:91], v[48:51]
	v_mfma_f32_16x16x32_bf16 v[236:239], v[172:175], v[192:195], v[40:43]
	v_mfma_f32_16x16x32_bf16 v[160:163], v[172:175], v[200:203], v[32:35]
	s_setprio 0
	s_setprio 1
	v_mfma_f32_16x16x32_bf16 v[28:31], v[104:107], v[64:67], v[28:31]
	v_mfma_f32_16x16x32_bf16 v[20:23], v[104:107], v[80:83], v[20:23]
	v_mfma_f32_16x16x32_bf16 v[12:15], v[104:107], v[92:95], v[12:15]
	v_mfma_f32_16x16x32_bf16 v[4:7], v[104:107], v[196:199], v[4:7]
	v_mfma_f32_16x16x32_bf16 v[28:31], v[120:123], v[68:71], v[28:31]
	v_mfma_f32_16x16x32_bf16 v[24:27], v[112:115], v[64:67], v[24:27]
	v_mfma_f32_16x16x32_bf16 v[20:23], v[120:123], v[88:91], v[20:23]
	v_mfma_f32_16x16x32_bf16 v[16:19], v[112:115], v[80:83], v[16:19]
	v_mfma_f32_16x16x32_bf16 v[12:15], v[120:123], v[192:195], v[12:15]
	v_mfma_f32_16x16x32_bf16 v[8:11], v[112:115], v[92:95], v[8:11]
	v_mfma_f32_16x16x32_bf16 v[4:7], v[120:123], v[200:203], v[4:7]
	v_mfma_f32_16x16x32_bf16 v[0:3], v[112:115], v[196:199], v[0:3]
	v_mfma_f32_16x16x32_bf16 v[164:167], v[220:223], v[68:71], v[24:27]
	v_mfma_f32_16x16x32_bf16 v[168:171], v[220:223], v[88:91], v[16:19]
	v_mfma_f32_16x16x32_bf16 v[172:175], v[220:223], v[192:195], v[8:11]
	v_mfma_f32_16x16x32_bf16 v[192:195], v[220:223], v[200:203], v[0:3]
	s_setprio 0
	s_barrier
	s_nop 1
	ds_read_b128 v[0:3], v156
	ds_read_b128 v[8:11], v156 offset:256
	ds_read_b128 v[16:19], v157
	ds_read_b128 v[24:27], v157 offset:256
	ds_read_b128 v[32:35], v149 offset:32768
	ds_read_b128 v[40:43], v149 offset:33792
	ds_read_b128 v[48:51], v149 offset:34816
	ds_read_b128 v[56:59], v149 offset:35840
	ds_read_b128 v[60:63], v149 offset:36864
	ds_read_b128 v[68:71], v149 offset:37888
	ds_read_b128 v[196:199], v149 offset:38912
	ds_read_b128 v[200:203], v149 offset:39936
	s_waitcnt vmcnt(2)
	s_barrier
; #define LDA(dst, b, h) for (int m = 0; m < 4; ++m) { \
;     dst[m][0] = *reinterpret_cast<const bf16x8*>((char*)SA(b, h) + aoff0 + m * 2048); \
;     dst[m][1] = *reinterpret_cast<const bf16x8*>((char*)SA(b, h) + aoff1 + m * 2048); }
; #define LDB(dst, b, h) for (int n = 0; n < 2; ++n) { \
;     dst[n][0] = *reinterpret_cast<const bf16x8*>((char*)SB(b, h) + boff0 + n * 256); \
;     dst[n][1] = *reinterpret_cast<const bf16x8*>((char*)SB(b, h) + boff1 + n * 256); }
; #define MMA(ai, bj, At, Btf) do { __builtin_amdgcn_s_setprio(1); \
;     for (int m = 0; m < 4; ++m) for (int n = 0; n < 2; ++n) for (int k = 0; k < 2; ++k) \
;       acc[ai][bj][m][n] = __builtin_amdgcn_mfma_f32_16x16x32_bf16(Btf[n][k], At[m][k], acc[ai][bj][m][n], 0, 0, 0); \
;     __builtin_amdgcn_s_setprio(0); } while (0)
; #define WAIT_V(n) asm volatile("s_waitcnt vmcnt(" #n ")" ::: "memory")
; #define WAIT_L(n) asm volatile("s_waitcnt lgkmcnt(" #n ")" ::: "memory")
; #define BAR __builtin_amdgcn_s_barrier()
; template <int EPI> ...
;     ...
;   { LDB(B0, 1, 0); LDA(At, 1, 0); WAIT_V(2); BAR; WAIT_L(0); MMA(0, 0, At, B0); BAR;
;     LDB(B1, 1, 1); WAIT_V(0); BAR; WAIT_L(0); MMA(0, 1, At, B1); BAR;
;     LDA(At, 1, 1); BAR; WAIT_L(0); MMA(1, 0, At, B0); MMA(1, 1, At, B1); BAR; }
;   if (wr == 0) BAR;
	s_waitcnt lgkmcnt(0)
	s_setprio 1
	s_waitcnt lgkmcnt(0)
	v_mfma_f32_16x16x32_bf16 v[64:67], v[0:3], v[32:35], v[124:127]
	v_mfma_f32_16x16x32_bf16 v[120:123], v[16:19], v[40:43], v[64:67]
	v_mfma_f32_16x16x32_bf16 v[64:67], v[8:11], v[32:35], v[208:211]
	v_mfma_f32_16x16x32_bf16 v[124:127], v[24:27], v[40:43], v[64:67]
	v_mfma_f32_16x16x32_bf16 v[64:67], v[0:3], v[48:51], v[116:119]
	v_mfma_f32_16x16x32_bf16 v[112:115], v[16:19], v[56:59], v[64:67]
	v_mfma_f32_16x16x32_bf16 v[64:67], v[8:11], v[48:51], v[212:215]
	v_mfma_f32_16x16x32_bf16 v[116:119], v[24:27], v[56:59], v[64:67]
	v_mfma_f32_16x16x32_bf16 v[64:67], v[0:3], v[60:63], v[108:111]
	v_mfma_f32_16x16x32_bf16 v[104:107], v[16:19], v[68:71], v[64:67]
	v_mfma_f32_16x16x32_bf16 v[64:67], v[8:11], v[60:63], v[216:219]
	v_mfma_f32_16x16x32_bf16 v[108:111], v[24:27], v[68:71], v[64:67]
	v_mfma_f32_16x16x32_bf16 v[64:67], v[0:3], v[196:199], v[100:103]
	v_mfma_f32_16x16x32_bf16 v[88:91], v[16:19], v[200:203], v[64:67]
	v_mfma_f32_16x16x32_bf16 v[64:67], v[8:11], v[196:199], v[96:99]
	v_mfma_f32_16x16x32_bf16 v[92:95], v[24:27], v[200:203], v[64:67]
	s_setprio 0
	s_barrier
	ds_read_b128 v[208:211], v158
	ds_read_b128 v[212:215], v158 offset:256
	ds_read_b128 v[216:219], v159
	ds_read_b128 v[220:223], v159 offset:256
	s_waitcnt vmcnt(0)
	s_barrier
	s_waitcnt lgkmcnt(0)
	s_setprio 1
	s_waitcnt lgkmcnt(0)
	v_mfma_f32_16x16x32_bf16 v[64:67], v[208:211], v[32:35], v[224:227]
	v_mfma_f32_16x16x32_bf16 v[32:35], v[212:215], v[32:35], v[176:179]
	v_mfma_f32_16x16x32_bf16 v[100:103], v[220:223], v[40:43], v[32:35]
	v_mfma_f32_16x16x32_bf16 v[32:35], v[208:211], v[48:51], v[84:87]
	v_mfma_f32_16x16x32_bf16 v[80:83], v[216:219], v[56:59], v[32:35]
	v_mfma_f32_16x16x32_bf16 v[32:35], v[212:215], v[48:51], v[180:183]
	v_mfma_f32_16x16x32_bf16 v[84:87], v[220:223], v[56:59], v[32:35]
	v_mfma_f32_16x16x32_bf16 v[32:35], v[208:211], v[60:63], v[76:79]
	v_mfma_f32_16x16x32_bf16 v[96:99], v[216:219], v[40:43], v[64:67]
	v_mfma_f32_16x16x32_bf16 v[64:67], v[216:219], v[68:71], v[32:35]
	v_mfma_f32_16x16x32_bf16 v[32:35], v[212:215], v[60:63], v[72:75]
	v_mfma_f32_16x16x32_bf16 v[68:71], v[220:223], v[68:71], v[32:35]
	v_mfma_f32_16x16x32_bf16 v[32:35], v[208:211], v[196:199], v[184:187]
	v_mfma_f32_16x16x32_bf16 v[56:59], v[216:219], v[200:203], v[32:35]
	v_mfma_f32_16x16x32_bf16 v[32:35], v[212:215], v[196:199], v[188:191]
	v_mfma_f32_16x16x32_bf16 v[60:63], v[220:223], v[200:203], v[32:35]
	s_setprio 0
	s_barrier
	ds_read_b128 v[176:179], v149 offset:49152
	ds_read_b128 v[180:183], v149 offset:50176
	ds_read_b128 v[184:187], v149 offset:51200
	ds_read_b128 v[188:191], v149 offset:52224
	ds_read_b128 v[196:199], v149 offset:53248
	ds_read_b128 v[200:203], v149 offset:54272
	ds_read_b128 v[224:227], v149 offset:55296
	ds_read_b128 v[240:243], v149 offset:56320
	s_barrier
	s_waitcnt lgkmcnt(0)
	s_setprio 1
	s_waitcnt lgkmcnt(0)
	v_mfma_f32_16x16x32_bf16 v[32:35], v[0:3], v[176:179], v[204:207]
	v_mfma_f32_16x16x32_bf16 v[72:75], v[16:19], v[180:183], v[32:35]
	v_mfma_f32_16x16x32_bf16 v[32:35], v[8:11], v[176:179], v[228:231]
	v_mfma_f32_16x16x32_bf16 v[76:79], v[24:27], v[180:183], v[32:35]
	v_mfma_f32_16x16x32_bf16 v[32:35], v[0:3], v[184:187], v[52:55]
	v_mfma_f32_16x16x32_bf16 v[48:51], v[16:19], v[188:191], v[32:35]
	v_mfma_f32_16x16x32_bf16 v[32:35], v[8:11], v[184:187], v[232:235]
	v_mfma_f32_16x16x32_bf16 v[52:55], v[24:27], v[188:191], v[32:35]
	v_mfma_f32_16x16x32_bf16 v[32:35], v[0:3], v[196:199], v[44:47]
	v_mfma_f32_16x16x32_bf16 v[40:43], v[16:19], v[200:203], v[32:35]
	v_mfma_f32_16x16x32_bf16 v[32:35], v[8:11], v[196:199], v[236:239]
	v_mfma_f32_16x16x32_bf16 v[0:3], v[0:3], v[224:227], v[36:39]
	v_mfma_f32_16x16x32_bf16 v[44:47], v[24:27], v[200:203], v[32:35]
	v_mfma_f32_16x16x32_bf16 v[32:35], v[16:19], v[240:243], v[0:3]
	v_mfma_f32_16x16x32_bf16 v[0:3], v[8:11], v[224:227], v[160:163]
	v_mfma_f32_16x16x32_bf16 v[36:39], v[24:27], v[240:243], v[0:3]
	s_setprio 0
	s_setprio 1
	v_mfma_f32_16x16x32_bf16 v[0:3], v[208:211], v[176:179], v[28:31]
	v_mfma_f32_16x16x32_bf16 v[24:27], v[216:219], v[180:183], v[0:3]
	v_mfma_f32_16x16x32_bf16 v[0:3], v[212:215], v[176:179], v[164:167]
	v_mfma_f32_16x16x32_bf16 v[28:31], v[220:223], v[180:183], v[0:3]
	v_mfma_f32_16x16x32_bf16 v[0:3], v[208:211], v[184:187], v[20:23]
	v_mfma_f32_16x16x32_bf16 v[16:19], v[216:219], v[188:191], v[0:3]
	v_mfma_f32_16x16x32_bf16 v[0:3], v[212:215], v[184:187], v[168:171]
	v_mfma_f32_16x16x32_bf16 v[20:23], v[220:223], v[188:191], v[0:3]
	v_mfma_f32_16x16x32_bf16 v[0:3], v[208:211], v[196:199], v[12:15]
	v_mfma_f32_16x16x32_bf16 v[8:11], v[216:219], v[200:203], v[0:3]
	v_mfma_f32_16x16x32_bf16 v[0:3], v[212:215], v[196:199], v[172:175]
	v_mfma_f32_16x16x32_bf16 v[12:15], v[220:223], v[200:203], v[0:3]
	v_mfma_f32_16x16x32_bf16 v[0:3], v[208:211], v[224:227], v[4:7]
	v_mfma_f32_16x16x32_bf16 v[4:7], v[212:215], v[224:227], v[192:195]
	v_mfma_f32_16x16x32_bf16 v[0:3], v[216:219], v[240:243], v[0:3]
	v_mfma_f32_16x16x32_bf16 v[4:7], v[220:223], v[240:243], v[4:7]
	s_setprio 0
	s_barrier
	s_and_saveexec_b64 s[60:61], s[2:3]
	s_cbranch_execz .LBB0_1146
	s_barrier
	s_branch .LBB0_1146
